# removed 62 duplicated back-to-back s_waitcnt instructions (second of two identical waits, mostly lgkmcnt(0) pairs in front of the GEMM MFMA blocks)
# baseline (speedup 1.0000x reference)
; #define PG8_STAGE(bufoff, gbase, voff) do { _Pragma("unroll") for (int _i = 0; _i < 2; ++_i) \
;         __builtin_amdgcn_global_load_lds((const unsigned*)((const char*)(gbase) + (voff)[_i]), (PG8_LAS unsigned*)(lds + (bufoff) + ldsw + _i * 8192), 16, 0, 0); } while (0)
; #define PG8_LDA(dst, b, h) do { _Pragma("unroll") for (int m = 0; m < 4; ++m) _Pragma("unroll") for (int k = 0; k < 2; ++k) dst[m][k] = *(const PG8_LAS bf16x8*)(lds + PG8_SA(b, h) + aoff + m * 2048 + k * 1024); } while (0)
; #define PG8_LDB(dst, b, h) do { _Pragma("unroll") for (int n = 0; n < 2; ++n) _Pragma("unroll") for (int k = 0; k < 2; ++k) dst[n][k] = *(const PG8_LAS bf16x8*)(lds + PG8_SB(b, h) + boff + n * 2048 + k * 1024); } while (0)
; #define PG8_WAIT_L(n) asm volatile("s_waitcnt lgkmcnt(" #n ")" ::: "memory")
; #define PG8_BAR __builtin_amdgcn_s_barrier()
; #define PG8_SCHED __builtin_amdgcn_sched_barrier(0)
; template <bool FP8, class Epi, class Sched>
; __device__ __forceinline__ void gemm_phase(PG8_LAS unsigned char* lds, const Gemm g, const Sched& S, const Epi& E) {
;     ...
;             PG8_LDB(B0, 0, 0); PG8_SCHED; PG8_LDA(At, 0, 0); PG8_STAGE(PG8_SA(1, 1), a1 + hstepA, voffA);
;             PG8_WAIT_L(8); PG8_BAR; PG8_WAIT_L(0); PG8_MMA(0, 0, At, B0); PG8_BAR; PG8_SCHED;
;             PG8_LDB(B1, 0, 1); PG8_STAGE(PG8_SB(0, 0), b2, voffB);
;             PG8_BAR; PG8_WAIT_L(0); PG8_MMA(0, 1, At, B1); PG8_BAR;
;             PG8_LDA(At, 0, 1); PG8_STAGE(PG8_SA(0, 0), a2, voffA);
;             PG8_BAR; PG8_WAIT_L(0); PG8_MMA(1, 0, At, B0); PG8_BAR; PG8_SCHED;
.LBB0_139:
	s_add_u32 s12, s0, 0xfff80080
	s_addc_u32 s13, s1, -1
	s_add_i32 s30, 0, 0x10000
	v_add_u32_e32 v140, s30, v143
	ds_read_b128 v[146:149], v140
	ds_read_b128 v[150:153], v140 offset:1024
	ds_read_b128 v[154:157], v140 offset:2048
	ds_read_b128 v[158:161], v140 offset:3072
	s_cmp_eq_u32 vcc_hi, 28
	s_cselect_b32 s69, s17, s13
	s_cselect_b32 s68, s87, s12
	s_cselect_b32 s13, s15, vcc_lo
	s_cselect_b32 s12, s94, s95
	v_lshl_add_u64 v[140:141], s[0:1], 0, v[136:137]
	s_add_i32 m0, s26, 0xc000
	ds_read_b128 v[162:165], v145
	ds_read_b128 v[166:169], v145 offset:1024
	ds_read_b128 v[170:173], v145 offset:2048
	ds_read_b128 v[182:185], v145 offset:3072
	ds_read_b128 v[186:189], v145 offset:4096
	ds_read_b128 v[190:193], v145 offset:5120
	ds_read_b128 v[194:197], v145 offset:6144
	ds_read_b128 v[198:201], v145 offset:7168
	global_load_lds_dwordx4 v[140:141], off
	v_lshl_add_u64 v[140:141], s[0:1], 0, v[138:139]
	s_add_i32 m0, s26, 0xe000
	s_nop 0
	global_load_lds_dwordx4 v[140:141], off
	s_waitcnt lgkmcnt(8)
	s_barrier
	s_waitcnt lgkmcnt(0)
	v_mfma_f32_16x16x32_bf16 v[126:129], v[146:149], v[162:165], v[126:129]
	v_mfma_f32_16x16x32_bf16 v[122:125], v[154:157], v[162:165], v[122:125]
	v_mfma_f32_16x16x32_bf16 v[110:113], v[146:149], v[170:173], v[110:113]
	v_mfma_f32_16x16x32_bf16 v[106:109], v[154:157], v[170:173], v[106:109]
	v_mfma_f32_16x16x32_bf16 v[94:97], v[146:149], v[186:189], v[94:97]
	v_mfma_f32_16x16x32_bf16 v[90:93], v[154:157], v[186:189], v[90:93]
	v_mfma_f32_16x16x32_bf16 v[78:81], v[146:149], v[194:197], v[78:81]
	v_mfma_f32_16x16x32_bf16 v[74:77], v[154:157], v[194:197], v[74:77]
	v_mfma_f32_16x16x32_bf16 v[126:129], v[150:153], v[166:169], v[126:129]
	v_mfma_f32_16x16x32_bf16 v[122:125], v[158:161], v[166:169], v[122:125]
	v_mfma_f32_16x16x32_bf16 v[110:113], v[150:153], v[182:185], v[110:113]
	v_mfma_f32_16x16x32_bf16 v[106:109], v[158:161], v[182:185], v[106:109]
	v_mfma_f32_16x16x32_bf16 v[94:97], v[150:153], v[190:193], v[94:97]
	v_mfma_f32_16x16x32_bf16 v[90:93], v[158:161], v[190:193], v[90:93]
	v_mfma_f32_16x16x32_bf16 v[78:81], v[150:153], v[198:201], v[78:81]
	v_mfma_f32_16x16x32_bf16 v[74:77], v[158:161], v[198:201], v[74:77]
	s_barrier
	s_add_i32 s86, 0, 0x14000
	v_add_u32_e32 v140, s86, v143
	s_add_i32 s30, s30, s25
	ds_read_b128 v[202:205], v140
	ds_read_b128 v[206:209], v140 offset:1024
	ds_read_b128 v[210:213], v140 offset:2048
	ds_read_b128 v[214:217], v140 offset:3072
	v_lshl_add_u64 v[140:141], s[12:13], 0, v[0:1]
	s_mov_b32 m0, s30
	v_lshl_add_u64 v[174:175], s[12:13], 0, v[130:131]
	global_load_lds_dwordx4 v[140:141], off
	s_add_i32 m0, s30, 0x2000
	s_nop 0
	global_load_lds_dwordx4 v[174:175], off
	s_barrier
	s_waitcnt lgkmcnt(0)
	v_mfma_f32_16x16x32_bf16 v[118:121], v[202:205], v[162:165], v[118:121]
	v_mfma_f32_16x16x32_bf16 v[114:117], v[210:213], v[162:165], v[114:117]
	v_mfma_f32_16x16x32_bf16 v[102:105], v[202:205], v[170:173], v[102:105]
	v_mfma_f32_16x16x32_bf16 v[98:101], v[210:213], v[170:173], v[98:101]
	v_mfma_f32_16x16x32_bf16 v[86:89], v[202:205], v[186:189], v[86:89]
	v_mfma_f32_16x16x32_bf16 v[82:85], v[210:213], v[186:189], v[82:85]
	v_mfma_f32_16x16x32_bf16 v[70:73], v[202:205], v[194:197], v[70:73]
	v_mfma_f32_16x16x32_bf16 v[66:69], v[210:213], v[194:197], v[66:69]
	v_mfma_f32_16x16x32_bf16 v[118:121], v[206:209], v[166:169], v[118:121]
	v_mfma_f32_16x16x32_bf16 v[114:117], v[214:217], v[166:169], v[114:117]
	v_mfma_f32_16x16x32_bf16 v[102:105], v[206:209], v[182:185], v[102:105]
	v_mfma_f32_16x16x32_bf16 v[98:101], v[214:217], v[182:185], v[98:101]
	v_mfma_f32_16x16x32_bf16 v[86:89], v[206:209], v[190:193], v[86:89]
	v_mfma_f32_16x16x32_bf16 v[82:85], v[214:217], v[190:193], v[82:85]
	v_mfma_f32_16x16x32_bf16 v[70:73], v[206:209], v[198:201], v[70:73]
	v_mfma_f32_16x16x32_bf16 v[66:69], v[214:217], v[198:201], v[66:69]
	s_mov_b32 m0, s26
	v_lshl_add_u64 v[236:237], s[68:69], 0, v[134:135]
	s_barrier
	ds_read_b128 v[162:165], v145 offset:16384
	ds_read_b128 v[166:169], v145 offset:17408
	ds_read_b128 v[170:173], v145 offset:18432
	ds_read_b128 v[182:185], v145 offset:19456
	ds_read_b128 v[186:189], v145 offset:20480
	ds_read_b128 v[190:193], v145 offset:21504
	ds_read_b128 v[194:197], v145 offset:22528
	ds_read_b128 v[198:201], v145 offset:23552
	global_load_lds_dwordx4 v[236:237], off
	v_lshl_add_u64 v[238:239], s[68:69], 0, v[132:133]
	s_mov_b32 m0, s27
	s_nop 0
	global_load_lds_dwordx4 v[238:239], off
	s_barrier
	s_waitcnt lgkmcnt(0)
	v_mfma_f32_16x16x32_bf16 v[62:65], v[146:149], v[162:165], v[62:65]
	v_mfma_f32_16x16x32_bf16 v[58:61], v[154:157], v[162:165], v[58:61]
	v_mfma_f32_16x16x32_bf16 v[46:49], v[146:149], v[170:173], v[46:49]
	v_mfma_f32_16x16x32_bf16 v[42:45], v[154:157], v[170:173], v[42:45]
	v_mfma_f32_16x16x32_bf16 v[30:33], v[146:149], v[186:189], v[30:33]
	v_mfma_f32_16x16x32_bf16 v[26:29], v[154:157], v[186:189], v[26:29]
	v_mfma_f32_16x16x32_bf16 v[14:17], v[146:149], v[194:197], v[14:17]
	v_mfma_f32_16x16x32_bf16 v[10:13], v[154:157], v[194:197], v[10:13]
	v_mfma_f32_16x16x32_bf16 v[62:65], v[150:153], v[166:169], v[62:65]
	v_mfma_f32_16x16x32_bf16 v[58:61], v[158:161], v[166:169], v[58:61]
	v_mfma_f32_16x16x32_bf16 v[46:49], v[150:153], v[182:185], v[46:49]
	v_mfma_f32_16x16x32_bf16 v[42:45], v[158:161], v[182:185], v[42:45]
	v_mfma_f32_16x16x32_bf16 v[30:33], v[150:153], v[190:193], v[30:33]
	v_mfma_f32_16x16x32_bf16 v[26:29], v[158:161], v[190:193], v[26:29]
	v_mfma_f32_16x16x32_bf16 v[14:17], v[150:153], v[198:201], v[14:17]
	v_mfma_f32_16x16x32_bf16 v[10:13], v[158:161], v[198:201], v[10:13]
	s_barrier
; #define PG8_STAGE(bufoff, gbase, voff) do { _Pragma("unroll") for (int _i = 0; _i < 2; ++_i) \
;         __builtin_amdgcn_global_load_lds((const unsigned*)((const char*)(gbase) + (voff)[_i]), (PG8_LAS unsigned*)(lds + (bufoff) + ldsw + _i * 8192), 16, 0, 0); } while (0)
; #define PG8_LDA(dst, b, h) do { _Pragma("unroll") for (int m = 0; m < 4; ++m) _Pragma("unroll") for (int k = 0; k < 2; ++k) dst[m][k] = *(const PG8_LAS bf16x8*)(lds + PG8_SA(b, h) + aoff + m * 2048 + k * 1024); } while (0)
; #define PG8_LDB(dst, b, h) do { _Pragma("unroll") for (int n = 0; n < 2; ++n) _Pragma("unroll") for (int k = 0; k < 2; ++k) dst[n][k] = *(const PG8_LAS bf16x8*)(lds + PG8_SB(b, h) + boff + n * 2048 + k * 1024); } while (0)
; #define PG8_WAIT_V(n) asm volatile("s_waitcnt vmcnt(" #n ")" ::: "memory")
; #define PG8_WAIT_L(n) asm volatile("s_waitcnt lgkmcnt(" #n ")" ::: "memory")
; #define PG8_BAR __builtin_amdgcn_s_barrier()
; #define PG8_SCHED __builtin_amdgcn_sched_barrier(0)
; template <bool FP8, class Epi, class Sched>
; __device__ __forceinline__ void gemm_phase(PG8_LAS unsigned char* lds, const Gemm g, const Sched& S, const Epi& E) {
;     ...
;             PG8_STAGE(PG8_SB(0, 1), b2 + hstep, voffB);
;             PG8_WAIT_V(6); PG8_BAR; PG8_MMA(1, 1, At, B1); PG8_BAR;
;             PG8_LDB(B0, 1, 0); PG8_SCHED; PG8_LDA(At, 1, 0); PG8_STAGE(PG8_SA(0, 1), a2 + hstepA, voffA);
;             PG8_WAIT_L(8); PG8_BAR; PG8_WAIT_L(0); PG8_MMA(0, 0, At, B0); PG8_BAR; PG8_SCHED;
;             PG8_LDB(B1, 1, 1); PG8_STAGE(PG8_SB(1, 0), b3, voffB);
;             PG8_BAR; PG8_WAIT_L(0); PG8_MMA(0, 1, At, B1); PG8_BAR;
	s_add_u32 s30, s12, 0x80000
	s_addc_u32 s31, s13, 0
	s_add_i32 s86, s86, s25
	v_lshl_add_u64 v[146:147], s[30:31], 0, v[0:1]
	s_mov_b32 m0, s86
	s_nop 0
	global_load_lds_dwordx4 v[146:147], off
	v_lshl_add_u64 v[146:147], s[30:31], 0, v[130:131]
	s_add_i32 m0, s86, 0x2000
	s_nop 0
	global_load_lds_dwordx4 v[146:147], off
	s_waitcnt vmcnt(6)
	s_barrier
	v_mfma_f32_16x16x32_bf16 v[54:57], v[202:205], v[162:165], v[54:57]
	v_mfma_f32_16x16x32_bf16 v[50:53], v[210:213], v[162:165], v[50:53]
	v_mfma_f32_16x16x32_bf16 v[38:41], v[202:205], v[170:173], v[38:41]
	v_mfma_f32_16x16x32_bf16 v[34:37], v[210:213], v[170:173], v[34:37]
	v_mfma_f32_16x16x32_bf16 v[22:25], v[202:205], v[186:189], v[22:25]
	v_mfma_f32_16x16x32_bf16 v[18:21], v[210:213], v[186:189], v[18:21]
	v_mfma_f32_16x16x32_bf16 v[6:9], v[202:205], v[194:197], v[6:9]
	v_mfma_f32_16x16x32_bf16 v[2:5], v[210:213], v[194:197], v[2:5]
	v_mfma_f32_16x16x32_bf16 v[54:57], v[206:209], v[166:169], v[54:57]
	v_mfma_f32_16x16x32_bf16 v[50:53], v[214:217], v[166:169], v[50:53]
	v_mfma_f32_16x16x32_bf16 v[38:41], v[206:209], v[182:185], v[38:41]
	v_mfma_f32_16x16x32_bf16 v[34:37], v[214:217], v[182:185], v[34:37]
	v_mfma_f32_16x16x32_bf16 v[22:25], v[206:209], v[190:193], v[22:25]
	v_mfma_f32_16x16x32_bf16 v[18:21], v[214:217], v[190:193], v[18:21]
	v_mfma_f32_16x16x32_bf16 v[6:9], v[206:209], v[198:201], v[6:9]
	v_mfma_f32_16x16x32_bf16 v[2:5], v[214:217], v[198:201], v[2:5]
	s_add_i32 s86, 0, 0x18000
	v_add_u32_e32 v158, s86, v143
	s_barrier
	ds_read_b128 v[146:149], v158
	ds_read_b128 v[150:153], v158 offset:1024
	ds_read_b128 v[154:157], v158 offset:2048
	ds_read_b128 v[158:161], v158 offset:3072
	s_add_u32 s30, s68, 0x80000
	s_addc_u32 s31, s69, 0
	s_mov_b32 m0, s54
	v_lshl_add_u64 v[202:203], s[30:31], 0, v[134:135]
	ds_read_b128 v[162:165], v145 offset:32768
	ds_read_b128 v[166:169], v145 offset:33792
	ds_read_b128 v[170:173], v145 offset:34816
	ds_read_b128 v[182:185], v145 offset:35840
	ds_read_b128 v[186:189], v145 offset:36864
	ds_read_b128 v[190:193], v145 offset:37888
	ds_read_b128 v[194:197], v145 offset:38912
	ds_read_b128 v[198:201], v145 offset:39936
	global_load_lds_dwordx4 v[202:203], off
	v_lshl_add_u64 v[202:203], s[30:31], 0, v[132:133]
	s_mov_b32 m0, s70
	s_nop 0
	global_load_lds_dwordx4 v[202:203], off
	s_waitcnt lgkmcnt(8)
	s_barrier
	s_waitcnt lgkmcnt(0)
	v_mfma_f32_16x16x32_bf16 v[126:129], v[146:149], v[162:165], v[126:129]
	v_mfma_f32_16x16x32_bf16 v[122:125], v[154:157], v[162:165], v[122:125]
	v_mfma_f32_16x16x32_bf16 v[110:113], v[146:149], v[170:173], v[110:113]
	v_mfma_f32_16x16x32_bf16 v[106:109], v[154:157], v[170:173], v[106:109]
	v_mfma_f32_16x16x32_bf16 v[94:97], v[146:149], v[186:189], v[94:97]
	v_mfma_f32_16x16x32_bf16 v[90:93], v[154:157], v[186:189], v[90:93]
	v_mfma_f32_16x16x32_bf16 v[78:81], v[146:149], v[194:197], v[78:81]
	v_mfma_f32_16x16x32_bf16 v[74:77], v[154:157], v[194:197], v[74:77]
	v_mfma_f32_16x16x32_bf16 v[126:129], v[150:153], v[166:169], v[126:129]
	v_mfma_f32_16x16x32_bf16 v[122:125], v[158:161], v[166:169], v[122:125]
	v_mfma_f32_16x16x32_bf16 v[110:113], v[150:153], v[182:185], v[110:113]
	v_mfma_f32_16x16x32_bf16 v[106:109], v[158:161], v[182:185], v[106:109]
	v_mfma_f32_16x16x32_bf16 v[94:97], v[150:153], v[190:193], v[94:97]
	v_mfma_f32_16x16x32_bf16 v[90:93], v[158:161], v[190:193], v[90:93]
	v_mfma_f32_16x16x32_bf16 v[78:81], v[150:153], v[198:201], v[78:81]
	v_mfma_f32_16x16x32_bf16 v[74:77], v[158:161], v[198:201], v[74:77]
	s_barrier
	s_add_i32 s30, 0, 0x1c000
	s_add_i32 s31, s86, s25
	v_add_u32_e32 v214, s30, v143
	v_lshl_add_u64 v[140:141], v[140:141], 0, s[56:57]
	s_mov_b32 m0, s31
	ds_read_b128 v[202:205], v214
	ds_read_b128 v[206:209], v214 offset:1024
	ds_read_b128 v[210:213], v214 offset:2048
	ds_read_b128 v[214:217], v214 offset:3072
	global_load_lds_dwordx4 v[140:141], off
	v_lshl_add_u64 v[140:141], v[174:175], 0, s[56:57]
	s_add_i32 m0, s31, 0x2000
	s_nop 0
	global_load_lds_dwordx4 v[140:141], off
	s_barrier
	s_waitcnt lgkmcnt(0)
	v_mfma_f32_16x16x32_bf16 v[118:121], v[202:205], v[162:165], v[118:121]
	v_mfma_f32_16x16x32_bf16 v[114:117], v[210:213], v[162:165], v[114:117]
	v_mfma_f32_16x16x32_bf16 v[102:105], v[202:205], v[170:173], v[102:105]
	v_mfma_f32_16x16x32_bf16 v[98:101], v[210:213], v[170:173], v[98:101]
	v_mfma_f32_16x16x32_bf16 v[86:89], v[202:205], v[186:189], v[86:89]
	v_mfma_f32_16x16x32_bf16 v[82:85], v[210:213], v[186:189], v[82:85]
	v_mfma_f32_16x16x32_bf16 v[70:73], v[202:205], v[194:197], v[70:73]
	v_mfma_f32_16x16x32_bf16 v[66:69], v[210:213], v[194:197], v[66:69]
	v_mfma_f32_16x16x32_bf16 v[118:121], v[206:209], v[166:169], v[118:121]
	v_mfma_f32_16x16x32_bf16 v[114:117], v[214:217], v[166:169], v[114:117]
	v_mfma_f32_16x16x32_bf16 v[102:105], v[206:209], v[182:185], v[102:105]
	v_mfma_f32_16x16x32_bf16 v[98:101], v[214:217], v[182:185], v[98:101]
	v_mfma_f32_16x16x32_bf16 v[86:89], v[206:209], v[190:193], v[86:89]
	v_mfma_f32_16x16x32_bf16 v[82:85], v[214:217], v[190:193], v[82:85]
	v_mfma_f32_16x16x32_bf16 v[70:73], v[206:209], v[198:201], v[70:73]
	v_mfma_f32_16x16x32_bf16 v[66:69], v[214:217], v[198:201], v[66:69]
	s_mov_b32 m0, s71
	v_lshl_add_u64 v[140:141], v[236:237], 0, s[56:57]
	s_barrier
; #define PG8_STAGE(bufoff, gbase, voff) do { _Pragma("unroll") for (int _i = 0; _i < 2; ++_i) \
;         __builtin_amdgcn_global_load_lds((const unsigned*)((const char*)(gbase) + (voff)[_i]), (PG8_LAS unsigned*)(lds + (bufoff) + ldsw + _i * 8192), 16, 0, 0); } while (0)
; template <bool FP8, class Epi, class Sched>
; __device__ __forceinline__ void gemm_phase(PG8_LAS unsigned char* lds, const Gemm g, const Sched& S, const Epi& E) {
;     ...
;             PG8_LDA(At, 1, 1); PG8_STAGE(PG8_SA(1, 0), a3, voffA);
;             PG8_BAR; PG8_WAIT_L(0); PG8_MMA(1, 0, At, B0); PG8_BAR; PG8_SCHED;
;             PG8_STAGE(PG8_SB(1, 1), b3 + hstep, voffB);
;             PG8_WAIT_V(6); PG8_BAR; PG8_MMA(1, 1, At, B1); PG8_BAR;
;         }
;   DI void operator()(const f32x4 (&acc)[2][2][4][2], const pg8::Unit& u, int wr, int wc, int fr, int fq) const {
;     const int row0 = u.pm * 256 + wr * 64 + fr, colb = u.pn * 256 + wc * 32 + 8 * fq;
; #pragma unroll
;     for (int ai = 0; ai < 2; ++ai)
; #pragma unroll
;       for (int m = 0; m < 4; ++m) {
;         const int row = row0 + ai * 128 + m * 16;
; #pragma unroll
;         for (int bj = 0; bj < 2; ++bj) {
;           const int col = colb + bj * 128;
;           f32x4 v0 = acc[ai][bj][m][0] * sc, v1 = acc[ai][bj][m][1] * sc;
;           u16* dst = nullptr;
;           if (MODE == 0) { if (col < N) dst = d0 + (size_t)row * ld0 + (col + coff2 + ((col < csplit) ? (coff1 - coff2) : 0)); }
;           else if (MODE == 1) {
;             const int oc = col + coff2 + ((col < csplit) ? (coff1 - coff2) : 0);
;             if (col < N) {
;               if (oc < 2048) dst = d0 + (size_t)row * 2048 + oc;
;               else if (oc < 2112) { rot(v0, v1, row, oc); dst = d2 + (size_t)row * 64 + (oc - 2048); }
;               else dst = d1 + (size_t)row * 4096 + (oc - 2112);
;             }
;           } else if (MODE == 3) {
;             if (col < N) { const bool lo = col < csplit; u16* bp = lo ? d0 : d1; const int ldd = lo ? 2048 : 4096, oc = lo ? col : col + (coff2 - 2112); dst = bp + (size_t)row * ldd + oc + (lo ? coff1 : 0); }
;           } else {
;             if (((col >> 6) % 3) == 2) rot(v0, v1, row, col);
;             dst = d0 + (size_t)row * 3072 + col;
;           }
;           if (dst) { u32x4 w = {pk2(v0[0], v0[1]), pk2(v0[2], v0[3]), pk2(v1[0], v1[1]), pk2(v1[2], v1[3])}; *(u32x4*)dst = w; }
	ds_read_b128 v[162:165], v145 offset:49152
	ds_read_b128 v[166:169], v145 offset:50176
	ds_read_b128 v[170:173], v145 offset:51200
	ds_read_b128 v[182:185], v145 offset:52224
	ds_read_b128 v[186:189], v145 offset:53248
	ds_read_b128 v[190:193], v145 offset:54272
	ds_read_b128 v[194:197], v145 offset:55296
	ds_read_b128 v[198:201], v145 offset:56320
	global_load_lds_dwordx4 v[140:141], off
	v_lshl_add_u64 v[140:141], v[238:239], 0, s[56:57]
	s_mov_b32 m0, s72
	s_nop 0
	global_load_lds_dwordx4 v[140:141], off
	s_barrier
	s_waitcnt lgkmcnt(0)
	v_mfma_f32_16x16x32_bf16 v[62:65], v[146:149], v[162:165], v[62:65]
	v_mfma_f32_16x16x32_bf16 v[58:61], v[154:157], v[162:165], v[58:61]
	v_mfma_f32_16x16x32_bf16 v[46:49], v[146:149], v[170:173], v[46:49]
	v_mfma_f32_16x16x32_bf16 v[42:45], v[154:157], v[170:173], v[42:45]
	v_mfma_f32_16x16x32_bf16 v[30:33], v[146:149], v[186:189], v[30:33]
	v_mfma_f32_16x16x32_bf16 v[26:29], v[154:157], v[186:189], v[26:29]
	v_mfma_f32_16x16x32_bf16 v[14:17], v[146:149], v[194:197], v[14:17]
	v_mfma_f32_16x16x32_bf16 v[10:13], v[154:157], v[194:197], v[10:13]
	v_mfma_f32_16x16x32_bf16 v[62:65], v[150:153], v[166:169], v[62:65]
	v_mfma_f32_16x16x32_bf16 v[58:61], v[158:161], v[166:169], v[58:61]
	v_mfma_f32_16x16x32_bf16 v[46:49], v[150:153], v[182:185], v[46:49]
	v_mfma_f32_16x16x32_bf16 v[42:45], v[158:161], v[182:185], v[42:45]
	v_mfma_f32_16x16x32_bf16 v[30:33], v[150:153], v[190:193], v[30:33]
	v_mfma_f32_16x16x32_bf16 v[26:29], v[158:161], v[190:193], v[26:29]
	v_mfma_f32_16x16x32_bf16 v[14:17], v[150:153], v[198:201], v[14:17]
	v_mfma_f32_16x16x32_bf16 v[10:13], v[158:161], v[198:201], v[10:13]
	s_barrier
	s_add_u32 s12, s12, 0x80080
	s_addc_u32 s13, s13, 0
	s_add_i32 s30, s30, s25
	v_lshl_add_u64 v[140:141], s[12:13], 0, v[0:1]
	s_mov_b32 m0, s30
	s_nop 0
	global_load_lds_dwordx4 v[140:141], off
	v_lshl_add_u64 v[140:141], s[12:13], 0, v[130:131]
	s_add_i32 m0, s30, 0x2000
	s_nop 0
	global_load_lds_dwordx4 v[140:141], off
	s_waitcnt vmcnt(6)
	s_barrier
	v_mfma_f32_16x16x32_bf16 v[54:57], v[202:205], v[162:165], v[54:57]
	v_mfma_f32_16x16x32_bf16 v[50:53], v[210:213], v[162:165], v[50:53]
	v_mfma_f32_16x16x32_bf16 v[38:41], v[202:205], v[170:173], v[38:41]
	v_mfma_f32_16x16x32_bf16 v[34:37], v[210:213], v[170:173], v[34:37]
	v_mfma_f32_16x16x32_bf16 v[22:25], v[202:205], v[186:189], v[22:25]
	v_mfma_f32_16x16x32_bf16 v[18:21], v[210:213], v[186:189], v[18:21]
	v_mfma_f32_16x16x32_bf16 v[6:9], v[202:205], v[194:197], v[6:9]
	v_mfma_f32_16x16x32_bf16 v[2:5], v[210:213], v[194:197], v[2:5]
	v_mfma_f32_16x16x32_bf16 v[54:57], v[206:209], v[166:169], v[54:57]
	v_mfma_f32_16x16x32_bf16 v[50:53], v[214:217], v[166:169], v[50:53]
	v_mfma_f32_16x16x32_bf16 v[38:41], v[206:209], v[182:185], v[38:41]
	v_mfma_f32_16x16x32_bf16 v[34:37], v[214:217], v[182:185], v[34:37]
	v_mfma_f32_16x16x32_bf16 v[22:25], v[206:209], v[190:193], v[22:25]
	v_mfma_f32_16x16x32_bf16 v[18:21], v[214:217], v[190:193], v[18:21]
	v_mfma_f32_16x16x32_bf16 v[6:9], v[206:209], v[198:201], v[6:9]
	v_mfma_f32_16x16x32_bf16 v[2:5], v[214:217], v[198:201], v[2:5]
	s_add_i32 vcc_hi, vcc_hi, 2
	s_add_u32 s0, s0, 0x100
	s_addc_u32 s1, s1, 0
	s_add_u32 s95, s95, 0x100
	s_addc_u32 vcc_lo, vcc_lo, 0
	s_cmp_gt_u32 vcc_hi, 29
	s_barrier
	s_cbranch_scc0 .LBB0_139
	v_lshl_or_b32 v146, s28, 8, v144
	s_movk_i32 s0, 0xe00
	v_lshl_add_u32 v147, s29, 8, v142
	v_cmp_gt_i32_e32 vcc, s0, v146
	v_mov_b64_e32 v[140:141], 0
	s_and_saveexec_b64 s[12:13], vcc
	v_mov_b64_e32 v[140:141], s[96:97]
	s_movk_i32 s0, 0x3400
	v_mad_i64_i32 v[140:141], s[0:1], v147, s0, v[140:141]
	s_movk_i32 s0, 0x200
	s_nop 0
	v_cmp_gt_i32_e64 s[0:1], s0, v146
	s_nop 1
	v_cndmask_b32_e64 v148, 0, v227, s[0:1]
	v_add3_u32 v148, v146, v148, s34
	v_ashrrev_i32_e32 v149, 31, v148
	v_lshl_add_u64 v[140:141], v[148:149], 1, v[140:141]
	s_or_b64 exec, exec, s[12:13]
	v_cmp_ne_u64_e64 s[0:1], 0, v[140:141]
	s_and_saveexec_b64 s[12:13], s[0:1]
	s_movk_i32 s20, 0x600
	s_mov_b32 s86, 0x800000
	s_movk_i32 s87, 0x3fff
	v_readlane_b32 s3, v254, 29
	s_cbranch_execz .LBB0_144
	v_cvt_pk_bf16_f32 v126, v126, v127
	v_cvt_pk_bf16_f32 v127, v128, v129
	v_cvt_pk_bf16_f32 v128, v122, v123
	v_cvt_pk_bf16_f32 v129, v124, v125
	global_store_dwordx4 v[140:141], v[126:129], off

; #define PG8_STAGE(bufoff, gbase, voff) do { _Pragma("unroll") for (int _i = 0; _i < 2; ++_i) \
;         __builtin_amdgcn_global_load_lds((const unsigned*)((const char*)(gbase) + (voff)[_i]), (PG8_LAS unsigned*)(lds + (bufoff) + ldsw + _i * 8192), 16, 0, 0); } while (0)
; #define PG8_LDA(dst, b, h) do { _Pragma("unroll") for (int m = 0; m < 4; ++m) _Pragma("unroll") for (int k = 0; k < 2; ++k) dst[m][k] = *(const PG8_LAS bf16x8*)(lds + PG8_SA(b, h) + aoff + m * 2048 + k * 1024); } while (0)
; #define PG8_LDB(dst, b, h) do { _Pragma("unroll") for (int n = 0; n < 2; ++n) _Pragma("unroll") for (int k = 0; k < 2; ++k) dst[n][k] = *(const PG8_LAS bf16x8*)(lds + PG8_SB(b, h) + boff + n * 2048 + k * 1024); } while (0)
; #define PG8_WAIT_L(n) asm volatile("s_waitcnt lgkmcnt(" #n ")" ::: "memory")
; #define PG8_BAR __builtin_amdgcn_s_barrier()
; #define PG8_SCHED __builtin_amdgcn_sched_barrier(0)
; template <bool FP8, class Epi, class Sched>
; __device__ __forceinline__ void gemm_phase(PG8_LAS unsigned char* lds, const Gemm g, const Sched& S, const Epi& E) {
;     ...
;             PG8_LDB(B0, 0, 0); PG8_SCHED; PG8_LDA(At, 0, 0); PG8_STAGE(PG8_SA(1, 1), a1 + hstepA, voffA);
;             PG8_WAIT_L(8); PG8_BAR; PG8_WAIT_L(0); PG8_MMA(0, 0, At, B0); PG8_BAR; PG8_SCHED;
;             PG8_LDB(B1, 0, 1); PG8_STAGE(PG8_SB(0, 0), b2, voffB);
;             PG8_BAR; PG8_WAIT_L(0); PG8_MMA(0, 1, At, B1); PG8_BAR;
;             PG8_LDA(At, 0, 1); PG8_STAGE(PG8_SA(0, 0), a2, voffA);
;             PG8_BAR; PG8_WAIT_L(0); PG8_MMA(1, 0, At, B0); PG8_BAR; PG8_SCHED;
.LBB0_226:
	s_add_u32 s10, s0, 0xfffc0080
	s_addc_u32 s11, s1, -1
	s_add_i32 s30, 0, 0x10000
	v_add_u32_e32 v6, s30, v174
	ds_read_b128 v[10:13], v6
	ds_read_b128 v[14:17], v6 offset:1024
	ds_read_b128 v[2:5], v6 offset:2048
	ds_read_b128 v[6:9], v6 offset:3072
	s_cmp_eq_u32 vcc_hi, 12
	s_cselect_b32 s69, s15, s11
	s_cselect_b32 s68, s87, s10
	s_cselect_b32 s11, s13, vcc_lo
	s_cselect_b32 s10, s94, s95
	v_lshl_add_u64 v[18:19], s[0:1], 0, v[160:161]
	s_add_i32 m0, s26, 0xc000
	ds_read_b128 v[184:187], v182
	ds_read_b128 v[188:191], v182 offset:1024
	ds_read_b128 v[192:195], v182 offset:2048
	ds_read_b128 v[196:199], v182 offset:3072
	ds_read_b128 v[200:203], v182 offset:4096
	ds_read_b128 v[204:207], v182 offset:5120
	ds_read_b128 v[208:211], v182 offset:6144
	ds_read_b128 v[212:215], v182 offset:7168
	global_load_lds_dwordx4 v[18:19], off
	v_lshl_add_u64 v[18:19], s[0:1], 0, v[162:163]
	s_add_i32 m0, s26, 0xe000
	s_nop 0
	global_load_lds_dwordx4 v[18:19], off
	s_waitcnt lgkmcnt(8)
	s_barrier
	s_waitcnt lgkmcnt(0)
	s_nop 1
	v_mfma_scale_f32_16x16x128_f8f6f4 v[150:153], v[10:17], v[184:191], v[150:153], v172, v172 op_sel_hi:[0,0,0]
	s_nop 1
	v_mfma_scale_f32_16x16x128_f8f6f4 v[146:149], v[2:9], v[184:191], v[146:149], v172, v172 op_sel_hi:[0,0,0]
	s_nop 1
	v_mfma_scale_f32_16x16x128_f8f6f4 v[134:137], v[10:17], v[192:199], v[134:137], v172, v172 op_sel_hi:[0,0,0]
	s_nop 1
	v_mfma_scale_f32_16x16x128_f8f6f4 v[130:133], v[2:9], v[192:199], v[130:133], v172, v172 op_sel_hi:[0,0,0]
	s_nop 1
	v_mfma_scale_f32_16x16x128_f8f6f4 v[118:121], v[10:17], v[200:207], v[118:121], v172, v172 op_sel_hi:[0,0,0]
	s_nop 1
	v_mfma_scale_f32_16x16x128_f8f6f4 v[114:117], v[2:9], v[200:207], v[114:117], v172, v172 op_sel_hi:[0,0,0]
	s_nop 1
	v_mfma_scale_f32_16x16x128_f8f6f4 v[102:105], v[10:17], v[208:215], v[102:105], v172, v172 op_sel_hi:[0,0,0]
	s_nop 1
	v_mfma_scale_f32_16x16x128_f8f6f4 v[98:101], v[2:9], v[208:215], v[98:101], v172, v172 op_sel_hi:[0,0,0]
	s_barrier
	s_add_i32 s86, 0, 0x14000
	s_add_i32 s30, s30, s25
	v_add_u32_e32 v22, s86, v174
	v_lshl_add_u64 v[164:165], s[10:11], 0, v[0:1]
	s_mov_b32 m0, s30
	ds_read_b128 v[236:239], v22
	ds_read_b128 v[240:243], v22 offset:1024
	ds_read_b128 v[18:21], v22 offset:2048
	ds_read_b128 v[22:25], v22 offset:3072
	global_load_lds_dwordx4 v[164:165], off
	v_lshl_add_u64 v[166:167], s[10:11], 0, v[158:159]
	s_add_i32 m0, s30, 0x2000
	s_nop 0
	global_load_lds_dwordx4 v[166:167], off
	s_barrier
	s_waitcnt lgkmcnt(0)
	s_nop 1
	v_mfma_scale_f32_16x16x128_f8f6f4 v[142:145], v[236:243], v[184:191], v[142:145], v172, v172 op_sel_hi:[0,0,0]
	s_nop 1
	v_mfma_scale_f32_16x16x128_f8f6f4 v[138:141], v[18:25], v[184:191], v[138:141], v172, v172 op_sel_hi:[0,0,0]
	s_nop 1
	v_mfma_scale_f32_16x16x128_f8f6f4 v[126:129], v[236:243], v[192:199], v[126:129], v172, v172 op_sel_hi:[0,0,0]
	s_nop 1
	v_mfma_scale_f32_16x16x128_f8f6f4 v[122:125], v[18:25], v[192:199], v[122:125], v172, v172 op_sel_hi:[0,0,0]
	s_nop 1
	v_mfma_scale_f32_16x16x128_f8f6f4 v[110:113], v[236:243], v[200:207], v[110:113], v172, v172 op_sel_hi:[0,0,0]
	s_nop 1
	v_mfma_scale_f32_16x16x128_f8f6f4 v[106:109], v[18:25], v[200:207], v[106:109], v172, v172 op_sel_hi:[0,0,0]
	s_nop 1
	v_mfma_scale_f32_16x16x128_f8f6f4 v[94:97], v[236:243], v[208:215], v[94:97], v172, v172 op_sel_hi:[0,0,0]
	s_nop 1
	v_mfma_scale_f32_16x16x128_f8f6f4 v[90:93], v[18:25], v[208:215], v[90:93], v172, v172 op_sel_hi:[0,0,0]
	s_mov_b32 m0, s26
	v_lshl_add_u64 v[168:169], s[68:69], 0, v[154:155]
	s_barrier
	ds_read_b128 v[184:187], v182 offset:16384
	ds_read_b128 v[188:191], v182 offset:17408
	ds_read_b128 v[192:195], v182 offset:18432
	ds_read_b128 v[196:199], v182 offset:19456
	ds_read_b128 v[200:203], v182 offset:20480
	ds_read_b128 v[204:207], v182 offset:21504
	ds_read_b128 v[208:211], v182 offset:22528
	ds_read_b128 v[212:215], v182 offset:23552
	global_load_lds_dwordx4 v[168:169], off
	v_lshl_add_u64 v[170:171], s[68:69], 0, v[156:157]
	s_mov_b32 m0, s27
	s_nop 0
	global_load_lds_dwordx4 v[170:171], off
	s_barrier
	s_waitcnt lgkmcnt(0)
	s_nop 1
	v_mfma_scale_f32_16x16x128_f8f6f4 v[86:89], v[10:17], v[184:191], v[86:89], v172, v172 op_sel_hi:[0,0,0]
	s_nop 1
	v_mfma_scale_f32_16x16x128_f8f6f4 v[82:85], v[2:9], v[184:191], v[82:85], v172, v172 op_sel_hi:[0,0,0]
	s_nop 1
	v_mfma_scale_f32_16x16x128_f8f6f4 v[70:73], v[10:17], v[192:199], v[70:73], v172, v172 op_sel_hi:[0,0,0]
	s_nop 1
	v_mfma_scale_f32_16x16x128_f8f6f4 v[66:69], v[2:9], v[192:199], v[66:69], v172, v172 op_sel_hi:[0,0,0]
	s_nop 1
	v_mfma_scale_f32_16x16x128_f8f6f4 v[54:57], v[10:17], v[200:207], v[54:57], v172, v172 op_sel_hi:[0,0,0]
	s_nop 1
	v_mfma_scale_f32_16x16x128_f8f6f4 v[50:53], v[2:9], v[200:207], v[50:53], v172, v172 op_sel_hi:[0,0,0]
	s_nop 1
	v_mfma_scale_f32_16x16x128_f8f6f4 v[38:41], v[10:17], v[208:215], v[38:41], v172, v172 op_sel_hi:[0,0,0]
	s_nop 1
	v_mfma_scale_f32_16x16x128_f8f6f4 v[34:37], v[2:9], v[208:215], v[34:37], v172, v172 op_sel_hi:[0,0,0]
	s_barrier
	s_add_u32 s30, s10, 0x40000
	s_addc_u32 s31, s11, 0
	s_add_i32 s86, s86, s25
	v_lshl_add_u64 v[2:3], s[30:31], 0, v[0:1]
	s_mov_b32 m0, s86
	s_nop 0
	global_load_lds_dwordx4 v[2:3], off
	v_lshl_add_u64 v[2:3], s[30:31], 0, v[158:159]
	s_add_i32 m0, s86, 0x2000
	s_nop 0
	global_load_lds_dwordx4 v[2:3], off
	s_waitcnt vmcnt(6)
	s_barrier
; #define PG8_STAGE(bufoff, gbase, voff) do { _Pragma("unroll") for (int _i = 0; _i < 2; ++_i) \
;         __builtin_amdgcn_global_load_lds((const unsigned*)((const char*)(gbase) + (voff)[_i]), (PG8_LAS unsigned*)(lds + (bufoff) + ldsw + _i * 8192), 16, 0, 0); } while (0)
; #define PG8_LDA(dst, b, h) do { _Pragma("unroll") for (int m = 0; m < 4; ++m) _Pragma("unroll") for (int k = 0; k < 2; ++k) dst[m][k] = *(const PG8_LAS bf16x8*)(lds + PG8_SA(b, h) + aoff + m * 2048 + k * 1024); } while (0)
; #define PG8_LDB(dst, b, h) do { _Pragma("unroll") for (int n = 0; n < 2; ++n) _Pragma("unroll") for (int k = 0; k < 2; ++k) dst[n][k] = *(const PG8_LAS bf16x8*)(lds + PG8_SB(b, h) + boff + n * 2048 + k * 1024); } while (0)
; #define PG8_WAIT_V(n) asm volatile("s_waitcnt vmcnt(" #n ")" ::: "memory")
; #define PG8_WAIT_L(n) asm volatile("s_waitcnt lgkmcnt(" #n ")" ::: "memory")
; #define PG8_BAR __builtin_amdgcn_s_barrier()
; #define PG8_SCHED __builtin_amdgcn_sched_barrier(0)
; template <bool FP8, class Epi, class Sched>
; __device__ __forceinline__ void gemm_phase(PG8_LAS unsigned char* lds, const Gemm g, const Sched& S, const Epi& E) {
;     ...
;             PG8_STAGE(PG8_SB(0, 1), b2 + hstep, voffB);
;             PG8_WAIT_V(6); PG8_BAR; PG8_MMA(1, 1, At, B1); PG8_BAR;
;             PG8_LDB(B0, 1, 0); PG8_SCHED; PG8_LDA(At, 1, 0); PG8_STAGE(PG8_SA(0, 1), a2 + hstepA, voffA);
;             PG8_WAIT_L(8); PG8_BAR; PG8_WAIT_L(0); PG8_MMA(0, 0, At, B0); PG8_BAR; PG8_SCHED;
;             PG8_LDB(B1, 1, 1); PG8_STAGE(PG8_SB(1, 0), b3, voffB);
;             PG8_BAR; PG8_WAIT_L(0); PG8_MMA(0, 1, At, B1); PG8_BAR;
	s_nop 1
	v_mfma_scale_f32_16x16x128_f8f6f4 v[78:81], v[236:243], v[184:191], v[78:81], v172, v172 op_sel_hi:[0,0,0]
	s_nop 1
	v_mfma_scale_f32_16x16x128_f8f6f4 v[74:77], v[18:25], v[184:191], v[74:77], v172, v172 op_sel_hi:[0,0,0]
	s_nop 1
	v_mfma_scale_f32_16x16x128_f8f6f4 v[62:65], v[236:243], v[192:199], v[62:65], v172, v172 op_sel_hi:[0,0,0]
	s_nop 1
	v_mfma_scale_f32_16x16x128_f8f6f4 v[58:61], v[18:25], v[192:199], v[58:61], v172, v172 op_sel_hi:[0,0,0]
	s_nop 1
	v_mfma_scale_f32_16x16x128_f8f6f4 v[46:49], v[236:243], v[200:207], v[46:49], v172, v172 op_sel_hi:[0,0,0]
	s_nop 1
	v_mfma_scale_f32_16x16x128_f8f6f4 v[42:45], v[18:25], v[200:207], v[42:45], v172, v172 op_sel_hi:[0,0,0]
	s_nop 1
	v_mfma_scale_f32_16x16x128_f8f6f4 v[30:33], v[236:243], v[208:215], v[30:33], v172, v172 op_sel_hi:[0,0,0]
	s_nop 1
	v_mfma_scale_f32_16x16x128_f8f6f4 v[26:29], v[18:25], v[208:215], v[26:29], v172, v172 op_sel_hi:[0,0,0]
	s_add_i32 s86, 0, 0x18000
	v_add_u32_e32 v14, s86, v174
	s_barrier
	ds_read_b128 v[2:5], v14
	ds_read_b128 v[6:9], v14 offset:1024
	ds_read_b128 v[10:13], v14 offset:2048
	ds_read_b128 v[14:17], v14 offset:3072
	s_add_u32 s30, s68, 0x40000
	s_addc_u32 s31, s69, 0
	s_mov_b32 m0, s54
	v_lshl_add_u64 v[208:209], s[30:31], 0, v[154:155]
	ds_read_b128 v[18:21], v182 offset:32768
	ds_read_b128 v[22:25], v182 offset:33792
	ds_read_b128 v[184:187], v182 offset:34816
	ds_read_b128 v[188:191], v182 offset:35840
	ds_read_b128 v[192:195], v182 offset:36864
	ds_read_b128 v[196:199], v182 offset:37888
	ds_read_b128 v[200:203], v182 offset:38912
	ds_read_b128 v[204:207], v182 offset:39936
	global_load_lds_dwordx4 v[208:209], off
	v_lshl_add_u64 v[208:209], s[30:31], 0, v[156:157]
	s_mov_b32 m0, s70
	s_nop 0
	global_load_lds_dwordx4 v[208:209], off
	s_waitcnt lgkmcnt(8)
	s_barrier
	s_waitcnt lgkmcnt(0)
	s_nop 1
	v_mfma_scale_f32_16x16x128_f8f6f4 v[150:153], v[2:9], v[18:25], v[150:153], v172, v172 op_sel_hi:[0,0,0]
	s_nop 1
	v_mfma_scale_f32_16x16x128_f8f6f4 v[146:149], v[10:17], v[18:25], v[146:149], v172, v172 op_sel_hi:[0,0,0]
	s_nop 1
	v_mfma_scale_f32_16x16x128_f8f6f4 v[134:137], v[2:9], v[184:191], v[134:137], v172, v172 op_sel_hi:[0,0,0]
	s_nop 1
	v_mfma_scale_f32_16x16x128_f8f6f4 v[130:133], v[10:17], v[184:191], v[130:133], v172, v172 op_sel_hi:[0,0,0]
	s_nop 1
	v_mfma_scale_f32_16x16x128_f8f6f4 v[118:121], v[2:9], v[192:199], v[118:121], v172, v172 op_sel_hi:[0,0,0]
	s_nop 1
	v_mfma_scale_f32_16x16x128_f8f6f4 v[114:117], v[10:17], v[192:199], v[114:117], v172, v172 op_sel_hi:[0,0,0]
	s_nop 1
	v_mfma_scale_f32_16x16x128_f8f6f4 v[102:105], v[2:9], v[200:207], v[102:105], v172, v172 op_sel_hi:[0,0,0]
	s_nop 1
	v_mfma_scale_f32_16x16x128_f8f6f4 v[98:101], v[10:17], v[200:207], v[98:101], v172, v172 op_sel_hi:[0,0,0]
	s_barrier
	s_add_i32 s30, 0, 0x1c000
	s_add_i32 s31, s86, s25
	v_add_u32_e32 v183, s30, v174
	v_lshl_add_u64 v[164:165], v[164:165], 0, s[56:57]
	s_mov_b32 m0, s31
	ds_read_b128 v[208:211], v183
	ds_read_b128 v[212:215], v183 offset:1024
	ds_read_b128 v[236:239], v183 offset:2048
	ds_read_b128 v[240:243], v183 offset:3072
	global_load_lds_dwordx4 v[164:165], off
	v_lshl_add_u64 v[164:165], v[166:167], 0, s[56:57]
	s_add_i32 m0, s31, 0x2000
	s_nop 0
	global_load_lds_dwordx4 v[164:165], off
	s_barrier
	s_waitcnt lgkmcnt(0)
	s_nop 1
	v_mfma_scale_f32_16x16x128_f8f6f4 v[142:145], v[208:215], v[18:25], v[142:145], v172, v172 op_sel_hi:[0,0,0]
	s_nop 1
	v_mfma_scale_f32_16x16x128_f8f6f4 v[138:141], v[236:243], v[18:25], v[138:141], v172, v172 op_sel_hi:[0,0,0]
	s_nop 1
	v_mfma_scale_f32_16x16x128_f8f6f4 v[126:129], v[208:215], v[184:191], v[126:129], v172, v172 op_sel_hi:[0,0,0]
	s_nop 1
	v_mfma_scale_f32_16x16x128_f8f6f4 v[122:125], v[236:243], v[184:191], v[122:125], v172, v172 op_sel_hi:[0,0,0]
	s_nop 1
	v_mfma_scale_f32_16x16x128_f8f6f4 v[110:113], v[208:215], v[192:199], v[110:113], v172, v172 op_sel_hi:[0,0,0]
	s_nop 1
	v_mfma_scale_f32_16x16x128_f8f6f4 v[106:109], v[236:243], v[192:199], v[106:109], v172, v172 op_sel_hi:[0,0,0]
	s_nop 1
	v_mfma_scale_f32_16x16x128_f8f6f4 v[94:97], v[208:215], v[200:207], v[94:97], v172, v172 op_sel_hi:[0,0,0]
	s_nop 1
	v_mfma_scale_f32_16x16x128_f8f6f4 v[90:93], v[236:243], v[200:207], v[90:93], v172, v172 op_sel_hi:[0,0,0]
	s_mov_b32 m0, s71
	v_lshl_add_u64 v[164:165], v[168:169], 0, s[56:57]
	s_barrier
; #define PG8_STAGE(bufoff, gbase, voff) do { _Pragma("unroll") for (int _i = 0; _i < 2; ++_i) \
;         __builtin_amdgcn_global_load_lds((const unsigned*)((const char*)(gbase) + (voff)[_i]), (PG8_LAS unsigned*)(lds + (bufoff) + ldsw + _i * 8192), 16, 0, 0); } while (0)
; template <bool FP8, class Epi, class Sched>
; __device__ __forceinline__ void gemm_phase(PG8_LAS unsigned char* lds, const Gemm g, const Sched& S, const Epi& E) {
;     ...
;             PG8_LDA(At, 1, 1); PG8_STAGE(PG8_SA(1, 0), a3, voffA);
;             PG8_BAR; PG8_WAIT_L(0); PG8_MMA(1, 0, At, B0); PG8_BAR; PG8_SCHED;
;             PG8_STAGE(PG8_SB(1, 1), b3 + hstep, voffB);
;             PG8_WAIT_V(6); PG8_BAR; PG8_MMA(1, 1, At, B1); PG8_BAR;
;         }
;   DI void operator()(const f32x4 (&acc)[2][2][4][2], const pg8::Unit& u, int wr, int wc, int fr, int fq) const {
;     const int row0 = u.pm * 256 + wr * 64 + fr, colb = u.pn * 256 + wc * 32 + 8 * fq;
; #pragma unroll
;     for (int ai = 0; ai < 2; ++ai)
; #pragma unroll
;       for (int m = 0; m < 4; ++m) {
;         const int row = row0 + ai * 128 + m * 16;
; #pragma unroll
;         for (int bj = 0; bj < 2; ++bj) {
;           const int col = colb + bj * 128;
;           f32x4 v0 = acc[ai][bj][m][0] * sc, v1 = acc[ai][bj][m][1] * sc;
;           u16* dst = nullptr;
;           if (MODE == 0) { if (col < N) dst = d0 + (size_t)row * ld0 + (col + coff2 + ((col < csplit) ? (coff1 - coff2) : 0)); }
;           else if (MODE == 1) {
;             const int oc = col + coff2 + ((col < csplit) ? (coff1 - coff2) : 0);
;             if (col < N) {
;               if (oc < 2048) dst = d0 + (size_t)row * 2048 + oc;
;               else if (oc < 2112) { rot(v0, v1, row, oc); dst = d2 + (size_t)row * 64 + (oc - 2048); }
;               else dst = d1 + (size_t)row * 4096 + (oc - 2112);
;             }
;           } else if (MODE == 3) {
;             if (col < N) { const bool lo = col < csplit; u16* bp = lo ? d0 : d1; const int ldd = lo ? 2048 : 4096, oc = lo ? col : col + (coff2 - 2112); dst = bp + (size_t)row * ldd + oc + (lo ? coff1 : 0); }
;           } else {
;             if (((col >> 6) % 3) == 2) rot(v0, v1, row, col);
;             dst = d0 + (size_t)row * 3072 + col;
;           }
;           if (dst) { u32x4 w = {pk2(v0[0], v0[1]), pk2(v0[2], v0[3]), pk2(v1[0], v1[1]), pk2(v1[2], v1[3])}; *(u32x4*)dst = w; }
	ds_read_b128 v[18:21], v182 offset:49152
	ds_read_b128 v[22:25], v182 offset:50176
	ds_read_b128 v[184:187], v182 offset:51200
	ds_read_b128 v[188:191], v182 offset:52224
	ds_read_b128 v[192:195], v182 offset:53248
	ds_read_b128 v[196:199], v182 offset:54272
	ds_read_b128 v[200:203], v182 offset:55296
	ds_read_b128 v[204:207], v182 offset:56320
	global_load_lds_dwordx4 v[164:165], off
	v_lshl_add_u64 v[164:165], v[170:171], 0, s[56:57]
	s_mov_b32 m0, s72
	s_nop 0
	global_load_lds_dwordx4 v[164:165], off
	s_barrier
	s_waitcnt lgkmcnt(0)
	s_nop 1
	v_mfma_scale_f32_16x16x128_f8f6f4 v[86:89], v[2:9], v[18:25], v[86:89], v172, v172 op_sel_hi:[0,0,0]
	s_nop 1
	v_mfma_scale_f32_16x16x128_f8f6f4 v[82:85], v[10:17], v[18:25], v[82:85], v172, v172 op_sel_hi:[0,0,0]
	s_nop 1
	v_mfma_scale_f32_16x16x128_f8f6f4 v[70:73], v[2:9], v[184:191], v[70:73], v172, v172 op_sel_hi:[0,0,0]
	s_nop 1
	v_mfma_scale_f32_16x16x128_f8f6f4 v[66:69], v[10:17], v[184:191], v[66:69], v172, v172 op_sel_hi:[0,0,0]
	s_nop 1
	v_mfma_scale_f32_16x16x128_f8f6f4 v[54:57], v[2:9], v[192:199], v[54:57], v172, v172 op_sel_hi:[0,0,0]
	s_nop 1
	v_mfma_scale_f32_16x16x128_f8f6f4 v[50:53], v[10:17], v[192:199], v[50:53], v172, v172 op_sel_hi:[0,0,0]
	s_nop 1
	v_mfma_scale_f32_16x16x128_f8f6f4 v[38:41], v[2:9], v[200:207], v[38:41], v172, v172 op_sel_hi:[0,0,0]
	s_nop 1
	v_mfma_scale_f32_16x16x128_f8f6f4 v[34:37], v[10:17], v[200:207], v[34:37], v172, v172 op_sel_hi:[0,0,0]
	s_barrier
	s_add_u32 s10, s10, 0x40080
	s_addc_u32 s11, s11, 0
	s_add_i32 s30, s30, s25
	v_lshl_add_u64 v[2:3], s[10:11], 0, v[0:1]
	s_mov_b32 m0, s30
	s_nop 0
	global_load_lds_dwordx4 v[2:3], off
	v_lshl_add_u64 v[2:3], s[10:11], 0, v[158:159]
	s_add_i32 m0, s30, 0x2000
	s_nop 0
	global_load_lds_dwordx4 v[2:3], off
	s_waitcnt vmcnt(6)
	s_barrier
	s_nop 1
	v_mfma_scale_f32_16x16x128_f8f6f4 v[78:81], v[208:215], v[18:25], v[78:81], v172, v172 op_sel_hi:[0,0,0]
	s_nop 1
	v_mfma_scale_f32_16x16x128_f8f6f4 v[74:77], v[236:243], v[18:25], v[74:77], v172, v172 op_sel_hi:[0,0,0]
	s_nop 1
	v_mfma_scale_f32_16x16x128_f8f6f4 v[62:65], v[208:215], v[184:191], v[62:65], v172, v172 op_sel_hi:[0,0,0]
	s_nop 1
	v_mfma_scale_f32_16x16x128_f8f6f4 v[58:61], v[236:243], v[184:191], v[58:61], v172, v172 op_sel_hi:[0,0,0]
	s_nop 1
	v_mfma_scale_f32_16x16x128_f8f6f4 v[46:49], v[208:215], v[192:199], v[46:49], v172, v172 op_sel_hi:[0,0,0]
	s_nop 1
	v_mfma_scale_f32_16x16x128_f8f6f4 v[42:45], v[236:243], v[192:199], v[42:45], v172, v172 op_sel_hi:[0,0,0]
	s_nop 1
	v_mfma_scale_f32_16x16x128_f8f6f4 v[30:33], v[208:215], v[200:207], v[30:33], v172, v172 op_sel_hi:[0,0,0]
	s_nop 1
	v_mfma_scale_f32_16x16x128_f8f6f4 v[26:29], v[236:243], v[200:207], v[26:29], v172, v172 op_sel_hi:[0,0,0]
	s_add_i32 vcc_hi, vcc_hi, 2
	s_add_u32 s0, s0, 0x100
	s_addc_u32 s1, s1, 0
	s_add_u32 s95, s95, 0x100
	s_addc_u32 vcc_lo, vcc_lo, 0
	s_cmp_gt_u32 vcc_hi, 13
	s_barrier
	s_cbranch_scc0 .LBB0_226
	s_nop 15
	s_nop 15
	v_lshl_or_b32 v2, s28, 8, v175
	v_lshl_add_u32 v8, s29, 8, v173
	v_cmp_gt_i32_e32 vcc, s34, v2
	v_mov_b64_e32 v[4:5], 0
	v_add_u32_e32 v6, 0x200, v2
	s_and_saveexec_b64 s[10:11], vcc
	v_mov_b64_e32 v[4:5], s[96:97]
	s_movk_i32 s0, 0x3400
	v_mad_i64_i32 v[4:5], s[0:1], v8, s0, v[4:5]
	s_movk_i32 s0, 0x800
	s_nop 0
	v_cmp_gt_i32_e64 s[0:1], s0, v2
	s_nop 1
	v_cndmask_b32_e64 v10, v6, v2, s[0:1]
	v_ashrrev_i32_e32 v11, 31, v10
	v_lshl_add_u64 v[4:5], v[10:11], 1, v[4:5]
	s_or_b64 exec, exec, s[10:11]
	v_cmp_ne_u64_e64 s[0:1], 0, v[4:5]
	s_and_saveexec_b64 s[10:11], s[0:1]
	s_movk_i32 s20, 0x600
	s_mov_b32 s86, 0x800000
	s_movk_i32 s87, 0x3fff
	v_readlane_b32 s3, v254, 29
	s_cbranch_execz .LBB0_231
	v_pk_mul_f32 v[12:13], v[152:153], s[88:89] op_sel_hi:[1,0]
	v_pk_mul_f32 v[10:11], v[150:151], s[88:89] op_sel_hi:[1,0]
	v_pk_mul_f32 v[14:15], v[148:149], s[88:89] op_sel_hi:[1,0]
	v_pk_mul_f32 v[16:17], v[146:147], s[88:89] op_sel_hi:[1,0]
	v_cvt_pk_bf16_f32 v10, v10, v11
	v_cvt_pk_bf16_f32 v11, v12, v13
	v_cvt_pk_bf16_f32 v12, v16, v17
	v_cvt_pk_bf16_f32 v13, v14, v15
	global_store_dwordx4 v[4:5], v[10:13], off

; #define PG8_STAGE(bufoff, gbase, voff) do { _Pragma("unroll") for (int _i = 0; _i < 2; ++_i) \
;         __builtin_amdgcn_global_load_lds((const unsigned*)((const char*)(gbase) + (voff)[_i]), (PG8_LAS unsigned*)(lds + (bufoff) + ldsw + _i * 8192), 16, 0, 0); } while (0)
; #define PG8_LDA(dst, b, h) do { _Pragma("unroll") for (int m = 0; m < 4; ++m) _Pragma("unroll") for (int k = 0; k < 2; ++k) dst[m][k] = *(const PG8_LAS bf16x8*)(lds + PG8_SA(b, h) + aoff + m * 2048 + k * 1024); } while (0)
; #define PG8_LDB(dst, b, h) do { _Pragma("unroll") for (int n = 0; n < 2; ++n) _Pragma("unroll") for (int k = 0; k < 2; ++k) dst[n][k] = *(const PG8_LAS bf16x8*)(lds + PG8_SB(b, h) + boff + n * 2048 + k * 1024); } while (0)
; #define PG8_WAIT_L(n) asm volatile("s_waitcnt lgkmcnt(" #n ")" ::: "memory")
; #define PG8_BAR __builtin_amdgcn_s_barrier()
; #define PG8_SCHED __builtin_amdgcn_sched_barrier(0)
; template <bool FP8, class Epi, class Sched>
; __device__ __forceinline__ void gemm_phase(PG8_LAS unsigned char* lds, const Gemm g, const Sched& S, const Epi& E) {
;     ...
;             PG8_LDB(B0, 0, 0); PG8_SCHED; PG8_LDA(At, 0, 0); PG8_STAGE(PG8_SA(1, 1), a1 + hstepA, voffA);
;             PG8_WAIT_L(8); PG8_BAR; PG8_WAIT_L(0); PG8_MMA(0, 0, At, B0); PG8_BAR; PG8_SCHED;
;             PG8_LDB(B1, 0, 1); PG8_STAGE(PG8_SB(0, 0), b2, voffB);
;             PG8_BAR; PG8_WAIT_L(0); PG8_MMA(0, 1, At, B1); PG8_BAR;
;             PG8_LDA(At, 0, 1); PG8_STAGE(PG8_SA(0, 0), a2, voffA);
;             PG8_BAR; PG8_WAIT_L(0); PG8_MMA(1, 0, At, B0); PG8_BAR; PG8_SCHED;
.LBB0_304:
	s_add_u32 s12, s0, 0xfff80080
	s_addc_u32 s13, s1, -1
	s_add_i32 s30, 0, 0x10000
	v_add_u32_e32 v140, s30, v143
	ds_read_b128 v[146:149], v140
	ds_read_b128 v[150:153], v140 offset:1024
	ds_read_b128 v[154:157], v140 offset:2048
	ds_read_b128 v[158:161], v140 offset:3072
	s_cmp_eq_u32 vcc_hi, 28
	s_cselect_b32 s69, s17, s13
	s_cselect_b32 s68, s87, s12
	s_cselect_b32 s13, s15, vcc_lo
	s_cselect_b32 s12, s94, s95
	v_lshl_add_u64 v[140:141], s[0:1], 0, v[136:137]
	s_add_i32 m0, s26, 0xc000
	ds_read_b128 v[162:165], v145
	ds_read_b128 v[166:169], v145 offset:1024
	ds_read_b128 v[170:173], v145 offset:2048
	ds_read_b128 v[182:185], v145 offset:3072
	ds_read_b128 v[186:189], v145 offset:4096
	ds_read_b128 v[190:193], v145 offset:5120
	ds_read_b128 v[194:197], v145 offset:6144
	ds_read_b128 v[198:201], v145 offset:7168
	global_load_lds_dwordx4 v[140:141], off
	v_lshl_add_u64 v[140:141], s[0:1], 0, v[138:139]
	s_add_i32 m0, s26, 0xe000
	s_nop 0
	global_load_lds_dwordx4 v[140:141], off
	s_waitcnt lgkmcnt(8)
	s_barrier
	s_waitcnt lgkmcnt(0)
	v_mfma_f32_16x16x32_bf16 v[126:129], v[146:149], v[162:165], v[126:129]
	v_mfma_f32_16x16x32_bf16 v[122:125], v[154:157], v[162:165], v[122:125]
	v_mfma_f32_16x16x32_bf16 v[110:113], v[146:149], v[170:173], v[110:113]
	v_mfma_f32_16x16x32_bf16 v[106:109], v[154:157], v[170:173], v[106:109]
	v_mfma_f32_16x16x32_bf16 v[94:97], v[146:149], v[186:189], v[94:97]
	v_mfma_f32_16x16x32_bf16 v[90:93], v[154:157], v[186:189], v[90:93]
	v_mfma_f32_16x16x32_bf16 v[78:81], v[146:149], v[194:197], v[78:81]
	v_mfma_f32_16x16x32_bf16 v[74:77], v[154:157], v[194:197], v[74:77]
	v_mfma_f32_16x16x32_bf16 v[126:129], v[150:153], v[166:169], v[126:129]
	v_mfma_f32_16x16x32_bf16 v[122:125], v[158:161], v[166:169], v[122:125]
	v_mfma_f32_16x16x32_bf16 v[110:113], v[150:153], v[182:185], v[110:113]
	v_mfma_f32_16x16x32_bf16 v[106:109], v[158:161], v[182:185], v[106:109]
	v_mfma_f32_16x16x32_bf16 v[94:97], v[150:153], v[190:193], v[94:97]
	v_mfma_f32_16x16x32_bf16 v[90:93], v[158:161], v[190:193], v[90:93]
	v_mfma_f32_16x16x32_bf16 v[78:81], v[150:153], v[198:201], v[78:81]
	v_mfma_f32_16x16x32_bf16 v[74:77], v[158:161], v[198:201], v[74:77]
	s_barrier
	s_add_i32 s86, 0, 0x14000
	v_add_u32_e32 v140, s86, v143
	s_add_i32 s30, s30, s25
	ds_read_b128 v[202:205], v140
	ds_read_b128 v[206:209], v140 offset:1024
	ds_read_b128 v[210:213], v140 offset:2048
	ds_read_b128 v[214:217], v140 offset:3072
	v_lshl_add_u64 v[140:141], s[12:13], 0, v[0:1]
	s_mov_b32 m0, s30
	v_lshl_add_u64 v[174:175], s[12:13], 0, v[130:131]
	global_load_lds_dwordx4 v[140:141], off
	s_add_i32 m0, s30, 0x2000
	s_nop 0
	global_load_lds_dwordx4 v[174:175], off
	s_barrier
	s_waitcnt lgkmcnt(0)
	v_mfma_f32_16x16x32_bf16 v[118:121], v[202:205], v[162:165], v[118:121]
	v_mfma_f32_16x16x32_bf16 v[114:117], v[210:213], v[162:165], v[114:117]
	v_mfma_f32_16x16x32_bf16 v[102:105], v[202:205], v[170:173], v[102:105]
	v_mfma_f32_16x16x32_bf16 v[98:101], v[210:213], v[170:173], v[98:101]
	v_mfma_f32_16x16x32_bf16 v[86:89], v[202:205], v[186:189], v[86:89]
	v_mfma_f32_16x16x32_bf16 v[82:85], v[210:213], v[186:189], v[82:85]
	v_mfma_f32_16x16x32_bf16 v[70:73], v[202:205], v[194:197], v[70:73]
	v_mfma_f32_16x16x32_bf16 v[66:69], v[210:213], v[194:197], v[66:69]
	v_mfma_f32_16x16x32_bf16 v[118:121], v[206:209], v[166:169], v[118:121]
	v_mfma_f32_16x16x32_bf16 v[114:117], v[214:217], v[166:169], v[114:117]
	v_mfma_f32_16x16x32_bf16 v[102:105], v[206:209], v[182:185], v[102:105]
	v_mfma_f32_16x16x32_bf16 v[98:101], v[214:217], v[182:185], v[98:101]
	v_mfma_f32_16x16x32_bf16 v[86:89], v[206:209], v[190:193], v[86:89]
	v_mfma_f32_16x16x32_bf16 v[82:85], v[214:217], v[190:193], v[82:85]
	v_mfma_f32_16x16x32_bf16 v[70:73], v[206:209], v[198:201], v[70:73]
	v_mfma_f32_16x16x32_bf16 v[66:69], v[214:217], v[198:201], v[66:69]
	s_mov_b32 m0, s26
	v_lshl_add_u64 v[236:237], s[68:69], 0, v[134:135]
	s_barrier
	ds_read_b128 v[162:165], v145 offset:16384
	ds_read_b128 v[166:169], v145 offset:17408
	ds_read_b128 v[170:173], v145 offset:18432
	ds_read_b128 v[182:185], v145 offset:19456
	ds_read_b128 v[186:189], v145 offset:20480
	ds_read_b128 v[190:193], v145 offset:21504
	ds_read_b128 v[194:197], v145 offset:22528
	ds_read_b128 v[198:201], v145 offset:23552
	global_load_lds_dwordx4 v[236:237], off
	v_lshl_add_u64 v[238:239], s[68:69], 0, v[132:133]
	s_mov_b32 m0, s27
	s_nop 0
	global_load_lds_dwordx4 v[238:239], off
	s_barrier
	s_waitcnt lgkmcnt(0)
	v_mfma_f32_16x16x32_bf16 v[62:65], v[146:149], v[162:165], v[62:65]
	v_mfma_f32_16x16x32_bf16 v[58:61], v[154:157], v[162:165], v[58:61]
	v_mfma_f32_16x16x32_bf16 v[46:49], v[146:149], v[170:173], v[46:49]
	v_mfma_f32_16x16x32_bf16 v[42:45], v[154:157], v[170:173], v[42:45]
	v_mfma_f32_16x16x32_bf16 v[30:33], v[146:149], v[186:189], v[30:33]
	v_mfma_f32_16x16x32_bf16 v[26:29], v[154:157], v[186:189], v[26:29]
	v_mfma_f32_16x16x32_bf16 v[14:17], v[146:149], v[194:197], v[14:17]
	v_mfma_f32_16x16x32_bf16 v[10:13], v[154:157], v[194:197], v[10:13]
	v_mfma_f32_16x16x32_bf16 v[62:65], v[150:153], v[166:169], v[62:65]
	v_mfma_f32_16x16x32_bf16 v[58:61], v[158:161], v[166:169], v[58:61]
	v_mfma_f32_16x16x32_bf16 v[46:49], v[150:153], v[182:185], v[46:49]
	v_mfma_f32_16x16x32_bf16 v[42:45], v[158:161], v[182:185], v[42:45]
	v_mfma_f32_16x16x32_bf16 v[30:33], v[150:153], v[190:193], v[30:33]
	v_mfma_f32_16x16x32_bf16 v[26:29], v[158:161], v[190:193], v[26:29]
	v_mfma_f32_16x16x32_bf16 v[14:17], v[150:153], v[198:201], v[14:17]
	v_mfma_f32_16x16x32_bf16 v[10:13], v[158:161], v[198:201], v[10:13]
	s_barrier
; #define PG8_STAGE(bufoff, gbase, voff) do { _Pragma("unroll") for (int _i = 0; _i < 2; ++_i) \
;         __builtin_amdgcn_global_load_lds((const unsigned*)((const char*)(gbase) + (voff)[_i]), (PG8_LAS unsigned*)(lds + (bufoff) + ldsw + _i * 8192), 16, 0, 0); } while (0)
; #define PG8_LDA(dst, b, h) do { _Pragma("unroll") for (int m = 0; m < 4; ++m) _Pragma("unroll") for (int k = 0; k < 2; ++k) dst[m][k] = *(const PG8_LAS bf16x8*)(lds + PG8_SA(b, h) + aoff + m * 2048 + k * 1024); } while (0)
; #define PG8_LDB(dst, b, h) do { _Pragma("unroll") for (int n = 0; n < 2; ++n) _Pragma("unroll") for (int k = 0; k < 2; ++k) dst[n][k] = *(const PG8_LAS bf16x8*)(lds + PG8_SB(b, h) + boff + n * 2048 + k * 1024); } while (0)
; #define PG8_WAIT_V(n) asm volatile("s_waitcnt vmcnt(" #n ")" ::: "memory")
; #define PG8_WAIT_L(n) asm volatile("s_waitcnt lgkmcnt(" #n ")" ::: "memory")
; #define PG8_BAR __builtin_amdgcn_s_barrier()
; #define PG8_SCHED __builtin_amdgcn_sched_barrier(0)
; template <bool FP8, class Epi, class Sched>
; __device__ __forceinline__ void gemm_phase(PG8_LAS unsigned char* lds, const Gemm g, const Sched& S, const Epi& E) {
;     ...
;             PG8_STAGE(PG8_SB(0, 1), b2 + hstep, voffB);
;             PG8_WAIT_V(6); PG8_BAR; PG8_MMA(1, 1, At, B1); PG8_BAR;
;             PG8_LDB(B0, 1, 0); PG8_SCHED; PG8_LDA(At, 1, 0); PG8_STAGE(PG8_SA(0, 1), a2 + hstepA, voffA);
;             PG8_WAIT_L(8); PG8_BAR; PG8_WAIT_L(0); PG8_MMA(0, 0, At, B0); PG8_BAR; PG8_SCHED;
;             PG8_LDB(B1, 1, 1); PG8_STAGE(PG8_SB(1, 0), b3, voffB);
;             PG8_BAR; PG8_WAIT_L(0); PG8_MMA(0, 1, At, B1); PG8_BAR;
	s_add_u32 s30, s12, 0x80000
	s_addc_u32 s31, s13, 0
	s_add_i32 s86, s86, s25
	v_lshl_add_u64 v[146:147], s[30:31], 0, v[0:1]
	s_mov_b32 m0, s86
	s_nop 0
	global_load_lds_dwordx4 v[146:147], off
	v_lshl_add_u64 v[146:147], s[30:31], 0, v[130:131]
	s_add_i32 m0, s86, 0x2000
	s_nop 0
	global_load_lds_dwordx4 v[146:147], off
	s_waitcnt vmcnt(6)
	s_barrier
	v_mfma_f32_16x16x32_bf16 v[54:57], v[202:205], v[162:165], v[54:57]
	v_mfma_f32_16x16x32_bf16 v[50:53], v[210:213], v[162:165], v[50:53]
	v_mfma_f32_16x16x32_bf16 v[38:41], v[202:205], v[170:173], v[38:41]
	v_mfma_f32_16x16x32_bf16 v[34:37], v[210:213], v[170:173], v[34:37]
	v_mfma_f32_16x16x32_bf16 v[22:25], v[202:205], v[186:189], v[22:25]
	v_mfma_f32_16x16x32_bf16 v[18:21], v[210:213], v[186:189], v[18:21]
	v_mfma_f32_16x16x32_bf16 v[6:9], v[202:205], v[194:197], v[6:9]
	v_mfma_f32_16x16x32_bf16 v[2:5], v[210:213], v[194:197], v[2:5]
	v_mfma_f32_16x16x32_bf16 v[54:57], v[206:209], v[166:169], v[54:57]
	v_mfma_f32_16x16x32_bf16 v[50:53], v[214:217], v[166:169], v[50:53]
	v_mfma_f32_16x16x32_bf16 v[38:41], v[206:209], v[182:185], v[38:41]
	v_mfma_f32_16x16x32_bf16 v[34:37], v[214:217], v[182:185], v[34:37]
	v_mfma_f32_16x16x32_bf16 v[22:25], v[206:209], v[190:193], v[22:25]
	v_mfma_f32_16x16x32_bf16 v[18:21], v[214:217], v[190:193], v[18:21]
	v_mfma_f32_16x16x32_bf16 v[6:9], v[206:209], v[198:201], v[6:9]
	v_mfma_f32_16x16x32_bf16 v[2:5], v[214:217], v[198:201], v[2:5]
	s_add_i32 s86, 0, 0x18000
	v_add_u32_e32 v158, s86, v143
	s_barrier
	ds_read_b128 v[146:149], v158
	ds_read_b128 v[150:153], v158 offset:1024
	ds_read_b128 v[154:157], v158 offset:2048
	ds_read_b128 v[158:161], v158 offset:3072
	s_add_u32 s30, s68, 0x80000
	s_addc_u32 s31, s69, 0
	s_mov_b32 m0, s54
	v_lshl_add_u64 v[202:203], s[30:31], 0, v[134:135]
	ds_read_b128 v[162:165], v145 offset:32768
	ds_read_b128 v[166:169], v145 offset:33792
	ds_read_b128 v[170:173], v145 offset:34816
	ds_read_b128 v[182:185], v145 offset:35840
	ds_read_b128 v[186:189], v145 offset:36864
	ds_read_b128 v[190:193], v145 offset:37888
	ds_read_b128 v[194:197], v145 offset:38912
	ds_read_b128 v[198:201], v145 offset:39936
	global_load_lds_dwordx4 v[202:203], off
	v_lshl_add_u64 v[202:203], s[30:31], 0, v[132:133]
	s_mov_b32 m0, s70
	s_nop 0
	global_load_lds_dwordx4 v[202:203], off
	s_waitcnt lgkmcnt(8)
	s_barrier
	s_waitcnt lgkmcnt(0)
	v_mfma_f32_16x16x32_bf16 v[126:129], v[146:149], v[162:165], v[126:129]
	v_mfma_f32_16x16x32_bf16 v[122:125], v[154:157], v[162:165], v[122:125]
	v_mfma_f32_16x16x32_bf16 v[110:113], v[146:149], v[170:173], v[110:113]
	v_mfma_f32_16x16x32_bf16 v[106:109], v[154:157], v[170:173], v[106:109]
	v_mfma_f32_16x16x32_bf16 v[94:97], v[146:149], v[186:189], v[94:97]
	v_mfma_f32_16x16x32_bf16 v[90:93], v[154:157], v[186:189], v[90:93]
	v_mfma_f32_16x16x32_bf16 v[78:81], v[146:149], v[194:197], v[78:81]
	v_mfma_f32_16x16x32_bf16 v[74:77], v[154:157], v[194:197], v[74:77]
	v_mfma_f32_16x16x32_bf16 v[126:129], v[150:153], v[166:169], v[126:129]
	v_mfma_f32_16x16x32_bf16 v[122:125], v[158:161], v[166:169], v[122:125]
	v_mfma_f32_16x16x32_bf16 v[110:113], v[150:153], v[182:185], v[110:113]
	v_mfma_f32_16x16x32_bf16 v[106:109], v[158:161], v[182:185], v[106:109]
	v_mfma_f32_16x16x32_bf16 v[94:97], v[150:153], v[190:193], v[94:97]
	v_mfma_f32_16x16x32_bf16 v[90:93], v[158:161], v[190:193], v[90:93]
	v_mfma_f32_16x16x32_bf16 v[78:81], v[150:153], v[198:201], v[78:81]
	v_mfma_f32_16x16x32_bf16 v[74:77], v[158:161], v[198:201], v[74:77]
	s_barrier
	s_add_i32 s30, 0, 0x1c000
	s_add_i32 s31, s86, s25
	v_add_u32_e32 v214, s30, v143
	v_lshl_add_u64 v[140:141], v[140:141], 0, s[56:57]
	s_mov_b32 m0, s31
	ds_read_b128 v[202:205], v214
	ds_read_b128 v[206:209], v214 offset:1024
	ds_read_b128 v[210:213], v214 offset:2048
	ds_read_b128 v[214:217], v214 offset:3072
	global_load_lds_dwordx4 v[140:141], off
	v_lshl_add_u64 v[140:141], v[174:175], 0, s[56:57]
	s_add_i32 m0, s31, 0x2000
	s_nop 0
	global_load_lds_dwordx4 v[140:141], off
	s_barrier
	s_waitcnt lgkmcnt(0)
	v_mfma_f32_16x16x32_bf16 v[118:121], v[202:205], v[162:165], v[118:121]
	v_mfma_f32_16x16x32_bf16 v[114:117], v[210:213], v[162:165], v[114:117]
	v_mfma_f32_16x16x32_bf16 v[102:105], v[202:205], v[170:173], v[102:105]
	v_mfma_f32_16x16x32_bf16 v[98:101], v[210:213], v[170:173], v[98:101]
	v_mfma_f32_16x16x32_bf16 v[86:89], v[202:205], v[186:189], v[86:89]
	v_mfma_f32_16x16x32_bf16 v[82:85], v[210:213], v[186:189], v[82:85]
	v_mfma_f32_16x16x32_bf16 v[70:73], v[202:205], v[194:197], v[70:73]
	v_mfma_f32_16x16x32_bf16 v[66:69], v[210:213], v[194:197], v[66:69]
	v_mfma_f32_16x16x32_bf16 v[118:121], v[206:209], v[166:169], v[118:121]
	v_mfma_f32_16x16x32_bf16 v[114:117], v[214:217], v[166:169], v[114:117]
	v_mfma_f32_16x16x32_bf16 v[102:105], v[206:209], v[182:185], v[102:105]
	v_mfma_f32_16x16x32_bf16 v[98:101], v[214:217], v[182:185], v[98:101]
	v_mfma_f32_16x16x32_bf16 v[86:89], v[206:209], v[190:193], v[86:89]
	v_mfma_f32_16x16x32_bf16 v[82:85], v[214:217], v[190:193], v[82:85]
	v_mfma_f32_16x16x32_bf16 v[70:73], v[206:209], v[198:201], v[70:73]
	v_mfma_f32_16x16x32_bf16 v[66:69], v[214:217], v[198:201], v[66:69]
	s_mov_b32 m0, s71
	v_lshl_add_u64 v[140:141], v[236:237], 0, s[56:57]
	s_barrier
; #define PG8_STAGE(bufoff, gbase, voff) do { _Pragma("unroll") for (int _i = 0; _i < 2; ++_i) \
;         __builtin_amdgcn_global_load_lds((const unsigned*)((const char*)(gbase) + (voff)[_i]), (PG8_LAS unsigned*)(lds + (bufoff) + ldsw + _i * 8192), 16, 0, 0); } while (0)
; template <bool FP8, class Epi, class Sched>
; __device__ __forceinline__ void gemm_phase(PG8_LAS unsigned char* lds, const Gemm g, const Sched& S, const Epi& E) {
;     ...
;             PG8_LDA(At, 1, 1); PG8_STAGE(PG8_SA(1, 0), a3, voffA);
;             PG8_BAR; PG8_WAIT_L(0); PG8_MMA(1, 0, At, B0); PG8_BAR; PG8_SCHED;
;             PG8_STAGE(PG8_SB(1, 1), b3 + hstep, voffB);
;             PG8_WAIT_V(6); PG8_BAR; PG8_MMA(1, 1, At, B1); PG8_BAR;
;         }
;   DI void operator()(const f32x4 (&acc)[2][2][4][2], const pg8::Unit& u, int wr, int wc, int fr, int fq) const {
;     const int row0 = u.pm * 256 + wr * 64 + fr, colb = u.pn * 256 + wc * 32 + 8 * fq;
; #pragma unroll
;     for (int ai = 0; ai < 2; ++ai)
; #pragma unroll
;       for (int m = 0; m < 4; ++m) {
;         const int row = row0 + ai * 128 + m * 16;
; #pragma unroll
;         for (int bj = 0; bj < 2; ++bj) {
;           const int col = colb + bj * 128;
;           f32x4 v0 = acc[ai][bj][m][0] * sc, v1 = acc[ai][bj][m][1] * sc;
;           u16* dst = nullptr;
;           if (MODE == 0) { if (col < N) dst = d0 + (size_t)row * ld0 + (col + coff2 + ((col < csplit) ? (coff1 - coff2) : 0)); }
;           else if (MODE == 1) {
;             const int oc = col + coff2 + ((col < csplit) ? (coff1 - coff2) : 0);
;             if (col < N) {
;               if (oc < 2048) dst = d0 + (size_t)row * 2048 + oc;
;               else if (oc < 2112) { rot(v0, v1, row, oc); dst = d2 + (size_t)row * 64 + (oc - 2048); }
;               else dst = d1 + (size_t)row * 4096 + (oc - 2112);
;             }
;           } else if (MODE == 3) {
;             if (col < N) { const bool lo = col < csplit; u16* bp = lo ? d0 : d1; const int ldd = lo ? 2048 : 4096, oc = lo ? col : col + (coff2 - 2112); dst = bp + (size_t)row * ldd + oc + (lo ? coff1 : 0); }
;           } else {
;             if (((col >> 6) % 3) == 2) rot(v0, v1, row, col);
;             dst = d0 + (size_t)row * 3072 + col;
;           }
;           if (dst) { u32x4 w = {pk2(v0[0], v0[1]), pk2(v0[2], v0[3]), pk2(v1[0], v1[1]), pk2(v1[2], v1[3])}; *(u32x4*)dst = w; }
	ds_read_b128 v[162:165], v145 offset:49152
	ds_read_b128 v[166:169], v145 offset:50176
	ds_read_b128 v[170:173], v145 offset:51200
	ds_read_b128 v[182:185], v145 offset:52224
	ds_read_b128 v[186:189], v145 offset:53248
	ds_read_b128 v[190:193], v145 offset:54272
	ds_read_b128 v[194:197], v145 offset:55296
	ds_read_b128 v[198:201], v145 offset:56320
	global_load_lds_dwordx4 v[140:141], off
	v_lshl_add_u64 v[140:141], v[238:239], 0, s[56:57]
	s_mov_b32 m0, s72
	s_nop 0
	global_load_lds_dwordx4 v[140:141], off
	s_barrier
	s_waitcnt lgkmcnt(0)
	v_mfma_f32_16x16x32_bf16 v[62:65], v[146:149], v[162:165], v[62:65]
	v_mfma_f32_16x16x32_bf16 v[58:61], v[154:157], v[162:165], v[58:61]
	v_mfma_f32_16x16x32_bf16 v[46:49], v[146:149], v[170:173], v[46:49]
	v_mfma_f32_16x16x32_bf16 v[42:45], v[154:157], v[170:173], v[42:45]
	v_mfma_f32_16x16x32_bf16 v[30:33], v[146:149], v[186:189], v[30:33]
	v_mfma_f32_16x16x32_bf16 v[26:29], v[154:157], v[186:189], v[26:29]
	v_mfma_f32_16x16x32_bf16 v[14:17], v[146:149], v[194:197], v[14:17]
	v_mfma_f32_16x16x32_bf16 v[10:13], v[154:157], v[194:197], v[10:13]
	v_mfma_f32_16x16x32_bf16 v[62:65], v[150:153], v[166:169], v[62:65]
	v_mfma_f32_16x16x32_bf16 v[58:61], v[158:161], v[166:169], v[58:61]
	v_mfma_f32_16x16x32_bf16 v[46:49], v[150:153], v[182:185], v[46:49]
	v_mfma_f32_16x16x32_bf16 v[42:45], v[158:161], v[182:185], v[42:45]
	v_mfma_f32_16x16x32_bf16 v[30:33], v[150:153], v[190:193], v[30:33]
	v_mfma_f32_16x16x32_bf16 v[26:29], v[158:161], v[190:193], v[26:29]
	v_mfma_f32_16x16x32_bf16 v[14:17], v[150:153], v[198:201], v[14:17]
	v_mfma_f32_16x16x32_bf16 v[10:13], v[158:161], v[198:201], v[10:13]
	s_barrier
	s_add_u32 s12, s12, 0x80080
	s_addc_u32 s13, s13, 0
	s_add_i32 s30, s30, s25
	v_lshl_add_u64 v[140:141], s[12:13], 0, v[0:1]
	s_mov_b32 m0, s30
	s_nop 0
	global_load_lds_dwordx4 v[140:141], off
	v_lshl_add_u64 v[140:141], s[12:13], 0, v[130:131]
	s_add_i32 m0, s30, 0x2000
	s_nop 0
	global_load_lds_dwordx4 v[140:141], off
	s_waitcnt vmcnt(6)
	s_barrier
	v_mfma_f32_16x16x32_bf16 v[54:57], v[202:205], v[162:165], v[54:57]
	v_mfma_f32_16x16x32_bf16 v[50:53], v[210:213], v[162:165], v[50:53]
	v_mfma_f32_16x16x32_bf16 v[38:41], v[202:205], v[170:173], v[38:41]
	v_mfma_f32_16x16x32_bf16 v[34:37], v[210:213], v[170:173], v[34:37]
	v_mfma_f32_16x16x32_bf16 v[22:25], v[202:205], v[186:189], v[22:25]
	v_mfma_f32_16x16x32_bf16 v[18:21], v[210:213], v[186:189], v[18:21]
	v_mfma_f32_16x16x32_bf16 v[6:9], v[202:205], v[194:197], v[6:9]
	v_mfma_f32_16x16x32_bf16 v[2:5], v[210:213], v[194:197], v[2:5]
	v_mfma_f32_16x16x32_bf16 v[54:57], v[206:209], v[166:169], v[54:57]
	v_mfma_f32_16x16x32_bf16 v[50:53], v[214:217], v[166:169], v[50:53]
	v_mfma_f32_16x16x32_bf16 v[38:41], v[206:209], v[182:185], v[38:41]
	v_mfma_f32_16x16x32_bf16 v[34:37], v[214:217], v[182:185], v[34:37]
	v_mfma_f32_16x16x32_bf16 v[22:25], v[206:209], v[190:193], v[22:25]
	v_mfma_f32_16x16x32_bf16 v[18:21], v[214:217], v[190:193], v[18:21]
	v_mfma_f32_16x16x32_bf16 v[6:9], v[206:209], v[198:201], v[6:9]
	v_mfma_f32_16x16x32_bf16 v[2:5], v[214:217], v[198:201], v[2:5]
	s_add_i32 vcc_hi, vcc_hi, 2
	s_add_u32 s0, s0, 0x100
	s_addc_u32 s1, s1, 0
	s_add_u32 s95, s95, 0x100
	s_addc_u32 vcc_lo, vcc_lo, 0
	s_cmp_gt_u32 vcc_hi, 29
	s_barrier
	s_cbranch_scc0 .LBB0_304
	v_lshl_or_b32 v146, s29, 8, v144
	s_movk_i32 s0, 0x1250
	v_lshl_add_u32 v147, s73, 8, v142
	v_cmp_gt_i32_e32 vcc, s0, v146
	v_mov_b64_e32 v[140:141], 0
	s_and_saveexec_b64 s[12:13], vcc
	v_mov_b64_e32 v[140:141], s[96:97]
	s_movk_i32 s0, 0x3d00
	v_mad_i64_i32 v[140:141], s[0:1], v147, s0, v[140:141]
	s_movk_i32 s0, 0x650
	s_nop 0
	v_cmp_gt_i32_e64 s[0:1], s0, v146
	s_nop 1
	v_cndmask_b32_e64 v148, 0, v227, s[0:1]
	v_add3_u32 v148, v146, v148, s34
	v_ashrrev_i32_e32 v149, 31, v148
	v_lshl_add_u64 v[140:141], v[148:149], 1, v[140:141]
	s_or_b64 exec, exec, s[12:13]
	v_cmp_ne_u64_e64 s[0:1], 0, v[140:141]
	s_and_saveexec_b64 s[12:13], s[0:1]
	s_movk_i32 s20, 0x600
	s_mov_b32 s86, 0x800000
	s_movk_i32 s87, 0x3fff
	v_readlane_b32 s3, v254, 29
	s_cbranch_execz .LBB0_309
	v_cvt_pk_bf16_f32 v126, v126, v127
	v_cvt_pk_bf16_f32 v127, v128, v129
	v_cvt_pk_bf16_f32 v128, v122, v123
	v_cvt_pk_bf16_f32 v129, v124, v125
	global_store_dwordx4 v[140:141], v[126:129], off

; #define PG8_STAGE(bufoff, gbase, voff) do { _Pragma("unroll") for (int _i = 0; _i < 2; ++_i) \
;         __builtin_amdgcn_global_load_lds((const unsigned*)((const char*)(gbase) + (voff)[_i]), (PG8_LAS unsigned*)(lds + (bufoff) + ldsw + _i * 8192), 16, 0, 0); } while (0)
; #define PG8_LDA(dst, b, h) do { _Pragma("unroll") for (int m = 0; m < 4; ++m) _Pragma("unroll") for (int k = 0; k < 2; ++k) dst[m][k] = *(const PG8_LAS bf16x8*)(lds + PG8_SA(b, h) + aoff + m * 2048 + k * 1024); } while (0)
; #define PG8_LDB(dst, b, h) do { _Pragma("unroll") for (int n = 0; n < 2; ++n) _Pragma("unroll") for (int k = 0; k < 2; ++k) dst[n][k] = *(const PG8_LAS bf16x8*)(lds + PG8_SB(b, h) + boff + n * 2048 + k * 1024); } while (0)
; #define PG8_WAIT_L(n) asm volatile("s_waitcnt lgkmcnt(" #n ")" ::: "memory")
; #define PG8_BAR __builtin_amdgcn_s_barrier()
; #define PG8_SCHED __builtin_amdgcn_sched_barrier(0)
; template <bool FP8, class Epi, class Sched>
; __device__ __forceinline__ void gemm_phase(PG8_LAS unsigned char* lds, const Gemm g, const Sched& S, const Epi& E) {
;     ...
;             PG8_LDB(B0, 0, 0); PG8_SCHED; PG8_LDA(At, 0, 0); PG8_STAGE(PG8_SA(1, 1), a1 + hstepA, voffA);
;             PG8_WAIT_L(8); PG8_BAR; PG8_WAIT_L(0); PG8_MMA(0, 0, At, B0); PG8_BAR; PG8_SCHED;
;             PG8_LDB(B1, 0, 1); PG8_STAGE(PG8_SB(0, 0), b2, voffB);
;             PG8_BAR; PG8_WAIT_L(0); PG8_MMA(0, 1, At, B1); PG8_BAR;
;             PG8_LDA(At, 0, 1); PG8_STAGE(PG8_SA(0, 0), a2, voffA);
;             PG8_BAR; PG8_WAIT_L(0); PG8_MMA(1, 0, At, B0); PG8_BAR; PG8_SCHED;
.LBB0_381:
	s_add_u32 s12, s0, 0xfffc0080
	s_addc_u32 s13, s1, -1
	s_add_i32 s30, 0, 0x10000
	v_add_u32_e32 v6, s30, v174
	ds_read_b128 v[10:13], v6
	ds_read_b128 v[14:17], v6 offset:1024
	ds_read_b128 v[2:5], v6 offset:2048
	ds_read_b128 v[6:9], v6 offset:3072
	s_cmp_eq_u32 vcc_hi, 12
	s_cselect_b32 s69, s17, s13
	s_cselect_b32 s68, s87, s12
	s_cselect_b32 s13, s15, vcc_lo
	s_cselect_b32 s12, s94, s95
	v_lshl_add_u64 v[18:19], s[0:1], 0, v[160:161]
	s_add_i32 m0, s26, 0xc000
	ds_read_b128 v[184:187], v182
	ds_read_b128 v[188:191], v182 offset:1024
	ds_read_b128 v[192:195], v182 offset:2048
	ds_read_b128 v[196:199], v182 offset:3072
	ds_read_b128 v[200:203], v182 offset:4096
	ds_read_b128 v[204:207], v182 offset:5120
	ds_read_b128 v[208:211], v182 offset:6144
	ds_read_b128 v[212:215], v182 offset:7168
	global_load_lds_dwordx4 v[18:19], off
	v_lshl_add_u64 v[18:19], s[0:1], 0, v[162:163]
	s_add_i32 m0, s26, 0xe000
	s_nop 0
	global_load_lds_dwordx4 v[18:19], off
	s_waitcnt lgkmcnt(8)
	s_barrier
	s_waitcnt lgkmcnt(0)
	s_nop 1
	v_mfma_scale_f32_16x16x128_f8f6f4 v[150:153], v[10:17], v[184:191], v[150:153], v172, v172 op_sel_hi:[0,0,0]
	s_nop 1
	v_mfma_scale_f32_16x16x128_f8f6f4 v[146:149], v[2:9], v[184:191], v[146:149], v172, v172 op_sel_hi:[0,0,0]
	s_nop 1
	v_mfma_scale_f32_16x16x128_f8f6f4 v[134:137], v[10:17], v[192:199], v[134:137], v172, v172 op_sel_hi:[0,0,0]
	s_nop 1
	v_mfma_scale_f32_16x16x128_f8f6f4 v[130:133], v[2:9], v[192:199], v[130:133], v172, v172 op_sel_hi:[0,0,0]
	s_nop 1
	v_mfma_scale_f32_16x16x128_f8f6f4 v[118:121], v[10:17], v[200:207], v[118:121], v172, v172 op_sel_hi:[0,0,0]
	s_nop 1
	v_mfma_scale_f32_16x16x128_f8f6f4 v[114:117], v[2:9], v[200:207], v[114:117], v172, v172 op_sel_hi:[0,0,0]
	s_nop 1
	v_mfma_scale_f32_16x16x128_f8f6f4 v[102:105], v[10:17], v[208:215], v[102:105], v172, v172 op_sel_hi:[0,0,0]
	s_nop 1
	v_mfma_scale_f32_16x16x128_f8f6f4 v[98:101], v[2:9], v[208:215], v[98:101], v172, v172 op_sel_hi:[0,0,0]
	s_barrier
	s_add_i32 s86, 0, 0x14000
	s_add_i32 s30, s30, s25
	v_add_u32_e32 v22, s86, v174
	v_lshl_add_u64 v[164:165], s[12:13], 0, v[0:1]
	s_mov_b32 m0, s30
	ds_read_b128 v[236:239], v22
	ds_read_b128 v[240:243], v22 offset:1024
	ds_read_b128 v[18:21], v22 offset:2048
	ds_read_b128 v[22:25], v22 offset:3072
	global_load_lds_dwordx4 v[164:165], off
	v_lshl_add_u64 v[166:167], s[12:13], 0, v[154:155]
	s_add_i32 m0, s30, 0x2000
	s_nop 0
	global_load_lds_dwordx4 v[166:167], off
	s_barrier
	s_waitcnt lgkmcnt(0)
	s_nop 1
	v_mfma_scale_f32_16x16x128_f8f6f4 v[142:145], v[236:243], v[184:191], v[142:145], v172, v172 op_sel_hi:[0,0,0]
	s_nop 1
	v_mfma_scale_f32_16x16x128_f8f6f4 v[138:141], v[18:25], v[184:191], v[138:141], v172, v172 op_sel_hi:[0,0,0]
	s_nop 1
	v_mfma_scale_f32_16x16x128_f8f6f4 v[126:129], v[236:243], v[192:199], v[126:129], v172, v172 op_sel_hi:[0,0,0]
	s_nop 1
	v_mfma_scale_f32_16x16x128_f8f6f4 v[122:125], v[18:25], v[192:199], v[122:125], v172, v172 op_sel_hi:[0,0,0]
	s_nop 1
	v_mfma_scale_f32_16x16x128_f8f6f4 v[110:113], v[236:243], v[200:207], v[110:113], v172, v172 op_sel_hi:[0,0,0]
	s_nop 1
	v_mfma_scale_f32_16x16x128_f8f6f4 v[106:109], v[18:25], v[200:207], v[106:109], v172, v172 op_sel_hi:[0,0,0]
	s_nop 1
	v_mfma_scale_f32_16x16x128_f8f6f4 v[94:97], v[236:243], v[208:215], v[94:97], v172, v172 op_sel_hi:[0,0,0]
	s_nop 1
	v_mfma_scale_f32_16x16x128_f8f6f4 v[90:93], v[18:25], v[208:215], v[90:93], v172, v172 op_sel_hi:[0,0,0]
	s_mov_b32 m0, s26
	v_lshl_add_u64 v[168:169], s[68:69], 0, v[158:159]
	s_barrier
	ds_read_b128 v[184:187], v182 offset:16384
	ds_read_b128 v[188:191], v182 offset:17408
	ds_read_b128 v[192:195], v182 offset:18432
	ds_read_b128 v[196:199], v182 offset:19456
	ds_read_b128 v[200:203], v182 offset:20480
	ds_read_b128 v[204:207], v182 offset:21504
	ds_read_b128 v[208:211], v182 offset:22528
	ds_read_b128 v[212:215], v182 offset:23552
	global_load_lds_dwordx4 v[168:169], off
	v_lshl_add_u64 v[170:171], s[68:69], 0, v[156:157]
	s_mov_b32 m0, s27
	s_nop 0
	global_load_lds_dwordx4 v[170:171], off
	s_barrier
	s_waitcnt lgkmcnt(0)
	s_nop 1
	v_mfma_scale_f32_16x16x128_f8f6f4 v[86:89], v[10:17], v[184:191], v[86:89], v172, v172 op_sel_hi:[0,0,0]
	s_nop 1
	v_mfma_scale_f32_16x16x128_f8f6f4 v[82:85], v[2:9], v[184:191], v[82:85], v172, v172 op_sel_hi:[0,0,0]
	s_nop 1
	v_mfma_scale_f32_16x16x128_f8f6f4 v[70:73], v[10:17], v[192:199], v[70:73], v172, v172 op_sel_hi:[0,0,0]
	s_nop 1
	v_mfma_scale_f32_16x16x128_f8f6f4 v[66:69], v[2:9], v[192:199], v[66:69], v172, v172 op_sel_hi:[0,0,0]
	s_nop 1
	v_mfma_scale_f32_16x16x128_f8f6f4 v[54:57], v[10:17], v[200:207], v[54:57], v172, v172 op_sel_hi:[0,0,0]
	s_nop 1
	v_mfma_scale_f32_16x16x128_f8f6f4 v[50:53], v[2:9], v[200:207], v[50:53], v172, v172 op_sel_hi:[0,0,0]
	s_nop 1
	v_mfma_scale_f32_16x16x128_f8f6f4 v[38:41], v[10:17], v[208:215], v[38:41], v172, v172 op_sel_hi:[0,0,0]
	s_nop 1
	v_mfma_scale_f32_16x16x128_f8f6f4 v[34:37], v[2:9], v[208:215], v[34:37], v172, v172 op_sel_hi:[0,0,0]
	s_barrier
	s_add_u32 s30, s12, 0x40000
	s_addc_u32 s31, s13, 0
	s_add_i32 s86, s86, s25
	v_lshl_add_u64 v[2:3], s[30:31], 0, v[0:1]
	s_mov_b32 m0, s86
	s_nop 0
	global_load_lds_dwordx4 v[2:3], off
	v_lshl_add_u64 v[2:3], s[30:31], 0, v[154:155]
	s_add_i32 m0, s86, 0x2000
	s_nop 0
	global_load_lds_dwordx4 v[2:3], off
	s_waitcnt vmcnt(6)
	s_barrier
; #define PG8_STAGE(bufoff, gbase, voff) do { _Pragma("unroll") for (int _i = 0; _i < 2; ++_i) \
;         __builtin_amdgcn_global_load_lds((const unsigned*)((const char*)(gbase) + (voff)[_i]), (PG8_LAS unsigned*)(lds + (bufoff) + ldsw + _i * 8192), 16, 0, 0); } while (0)
; #define PG8_LDA(dst, b, h) do { _Pragma("unroll") for (int m = 0; m < 4; ++m) _Pragma("unroll") for (int k = 0; k < 2; ++k) dst[m][k] = *(const PG8_LAS bf16x8*)(lds + PG8_SA(b, h) + aoff + m * 2048 + k * 1024); } while (0)
; #define PG8_LDB(dst, b, h) do { _Pragma("unroll") for (int n = 0; n < 2; ++n) _Pragma("unroll") for (int k = 0; k < 2; ++k) dst[n][k] = *(const PG8_LAS bf16x8*)(lds + PG8_SB(b, h) + boff + n * 2048 + k * 1024); } while (0)
; #define PG8_WAIT_V(n) asm volatile("s_waitcnt vmcnt(" #n ")" ::: "memory")
; #define PG8_WAIT_L(n) asm volatile("s_waitcnt lgkmcnt(" #n ")" ::: "memory")
; #define PG8_BAR __builtin_amdgcn_s_barrier()
; #define PG8_SCHED __builtin_amdgcn_sched_barrier(0)
; template <bool FP8, class Epi, class Sched>
; __device__ __forceinline__ void gemm_phase(PG8_LAS unsigned char* lds, const Gemm g, const Sched& S, const Epi& E) {
;     ...
;             PG8_STAGE(PG8_SB(0, 1), b2 + hstep, voffB);
;             PG8_WAIT_V(6); PG8_BAR; PG8_MMA(1, 1, At, B1); PG8_BAR;
;             PG8_LDB(B0, 1, 0); PG8_SCHED; PG8_LDA(At, 1, 0); PG8_STAGE(PG8_SA(0, 1), a2 + hstepA, voffA);
;             PG8_WAIT_L(8); PG8_BAR; PG8_WAIT_L(0); PG8_MMA(0, 0, At, B0); PG8_BAR; PG8_SCHED;
;             PG8_LDB(B1, 1, 1); PG8_STAGE(PG8_SB(1, 0), b3, voffB);
;             PG8_BAR; PG8_WAIT_L(0); PG8_MMA(0, 1, At, B1); PG8_BAR;
	s_nop 1
	v_mfma_scale_f32_16x16x128_f8f6f4 v[78:81], v[236:243], v[184:191], v[78:81], v172, v172 op_sel_hi:[0,0,0]
	s_nop 1
	v_mfma_scale_f32_16x16x128_f8f6f4 v[74:77], v[18:25], v[184:191], v[74:77], v172, v172 op_sel_hi:[0,0,0]
	s_nop 1
	v_mfma_scale_f32_16x16x128_f8f6f4 v[62:65], v[236:243], v[192:199], v[62:65], v172, v172 op_sel_hi:[0,0,0]
	s_nop 1
	v_mfma_scale_f32_16x16x128_f8f6f4 v[58:61], v[18:25], v[192:199], v[58:61], v172, v172 op_sel_hi:[0,0,0]
	s_nop 1
	v_mfma_scale_f32_16x16x128_f8f6f4 v[46:49], v[236:243], v[200:207], v[46:49], v172, v172 op_sel_hi:[0,0,0]
	s_nop 1
	v_mfma_scale_f32_16x16x128_f8f6f4 v[42:45], v[18:25], v[200:207], v[42:45], v172, v172 op_sel_hi:[0,0,0]
	s_nop 1
	v_mfma_scale_f32_16x16x128_f8f6f4 v[30:33], v[236:243], v[208:215], v[30:33], v172, v172 op_sel_hi:[0,0,0]
	s_nop 1
	v_mfma_scale_f32_16x16x128_f8f6f4 v[26:29], v[18:25], v[208:215], v[26:29], v172, v172 op_sel_hi:[0,0,0]
	s_add_i32 s86, 0, 0x18000
	v_add_u32_e32 v14, s86, v174
	s_barrier
	ds_read_b128 v[2:5], v14
	ds_read_b128 v[6:9], v14 offset:1024
	ds_read_b128 v[10:13], v14 offset:2048
	ds_read_b128 v[14:17], v14 offset:3072
	s_add_u32 s30, s68, 0x40000
	s_addc_u32 s31, s69, 0
	s_mov_b32 m0, s54
	v_lshl_add_u64 v[208:209], s[30:31], 0, v[158:159]
	ds_read_b128 v[18:21], v182 offset:32768
	ds_read_b128 v[22:25], v182 offset:33792
	ds_read_b128 v[184:187], v182 offset:34816
	ds_read_b128 v[188:191], v182 offset:35840
	ds_read_b128 v[192:195], v182 offset:36864
	ds_read_b128 v[196:199], v182 offset:37888
	ds_read_b128 v[200:203], v182 offset:38912
	ds_read_b128 v[204:207], v182 offset:39936
	global_load_lds_dwordx4 v[208:209], off
	v_lshl_add_u64 v[208:209], s[30:31], 0, v[156:157]
	s_mov_b32 m0, s70
	s_nop 0
	global_load_lds_dwordx4 v[208:209], off
	s_waitcnt lgkmcnt(8)
	s_barrier
	s_waitcnt lgkmcnt(0)
	s_nop 1
	v_mfma_scale_f32_16x16x128_f8f6f4 v[150:153], v[2:9], v[18:25], v[150:153], v172, v172 op_sel_hi:[0,0,0]
	s_nop 1
	v_mfma_scale_f32_16x16x128_f8f6f4 v[146:149], v[10:17], v[18:25], v[146:149], v172, v172 op_sel_hi:[0,0,0]
	s_nop 1
	v_mfma_scale_f32_16x16x128_f8f6f4 v[134:137], v[2:9], v[184:191], v[134:137], v172, v172 op_sel_hi:[0,0,0]
	s_nop 1
	v_mfma_scale_f32_16x16x128_f8f6f4 v[130:133], v[10:17], v[184:191], v[130:133], v172, v172 op_sel_hi:[0,0,0]
	s_nop 1
	v_mfma_scale_f32_16x16x128_f8f6f4 v[118:121], v[2:9], v[192:199], v[118:121], v172, v172 op_sel_hi:[0,0,0]
	s_nop 1
	v_mfma_scale_f32_16x16x128_f8f6f4 v[114:117], v[10:17], v[192:199], v[114:117], v172, v172 op_sel_hi:[0,0,0]
	s_nop 1
	v_mfma_scale_f32_16x16x128_f8f6f4 v[102:105], v[2:9], v[200:207], v[102:105], v172, v172 op_sel_hi:[0,0,0]
	s_nop 1
	v_mfma_scale_f32_16x16x128_f8f6f4 v[98:101], v[10:17], v[200:207], v[98:101], v172, v172 op_sel_hi:[0,0,0]
	s_barrier
	s_add_i32 s30, 0, 0x1c000
	s_add_i32 s31, s86, s25
	v_add_u32_e32 v183, s30, v174
	v_lshl_add_u64 v[164:165], v[164:165], 0, s[56:57]
	s_mov_b32 m0, s31
	ds_read_b128 v[208:211], v183
	ds_read_b128 v[212:215], v183 offset:1024
	ds_read_b128 v[236:239], v183 offset:2048
	ds_read_b128 v[240:243], v183 offset:3072
	global_load_lds_dwordx4 v[164:165], off
	v_lshl_add_u64 v[164:165], v[166:167], 0, s[56:57]
	s_add_i32 m0, s31, 0x2000
	s_nop 0
	global_load_lds_dwordx4 v[164:165], off
	s_barrier
	s_waitcnt lgkmcnt(0)
	s_nop 1
	v_mfma_scale_f32_16x16x128_f8f6f4 v[142:145], v[208:215], v[18:25], v[142:145], v172, v172 op_sel_hi:[0,0,0]
	s_nop 1
	v_mfma_scale_f32_16x16x128_f8f6f4 v[138:141], v[236:243], v[18:25], v[138:141], v172, v172 op_sel_hi:[0,0,0]
	s_nop 1
	v_mfma_scale_f32_16x16x128_f8f6f4 v[126:129], v[208:215], v[184:191], v[126:129], v172, v172 op_sel_hi:[0,0,0]
	s_nop 1
	v_mfma_scale_f32_16x16x128_f8f6f4 v[122:125], v[236:243], v[184:191], v[122:125], v172, v172 op_sel_hi:[0,0,0]
	s_nop 1
	v_mfma_scale_f32_16x16x128_f8f6f4 v[110:113], v[208:215], v[192:199], v[110:113], v172, v172 op_sel_hi:[0,0,0]
	s_nop 1
	v_mfma_scale_f32_16x16x128_f8f6f4 v[106:109], v[236:243], v[192:199], v[106:109], v172, v172 op_sel_hi:[0,0,0]
	s_nop 1
	v_mfma_scale_f32_16x16x128_f8f6f4 v[94:97], v[208:215], v[200:207], v[94:97], v172, v172 op_sel_hi:[0,0,0]
	s_nop 1
	v_mfma_scale_f32_16x16x128_f8f6f4 v[90:93], v[236:243], v[200:207], v[90:93], v172, v172 op_sel_hi:[0,0,0]
	s_mov_b32 m0, s71
	v_lshl_add_u64 v[164:165], v[168:169], 0, s[56:57]
	s_barrier
; #define PG8_STAGE(bufoff, gbase, voff) do { _Pragma("unroll") for (int _i = 0; _i < 2; ++_i) \
;         __builtin_amdgcn_global_load_lds((const unsigned*)((const char*)(gbase) + (voff)[_i]), (PG8_LAS unsigned*)(lds + (bufoff) + ldsw + _i * 8192), 16, 0, 0); } while (0)
; template <bool FP8, class Epi, class Sched>
; __device__ __forceinline__ void gemm_phase(PG8_LAS unsigned char* lds, const Gemm g, const Sched& S, const Epi& E) {
;     ...
;             PG8_LDA(At, 1, 1); PG8_STAGE(PG8_SA(1, 0), a3, voffA);
;             PG8_BAR; PG8_WAIT_L(0); PG8_MMA(1, 0, At, B0); PG8_BAR; PG8_SCHED;
;             PG8_STAGE(PG8_SB(1, 1), b3 + hstep, voffB);
;             PG8_WAIT_V(6); PG8_BAR; PG8_MMA(1, 1, At, B1); PG8_BAR;
;         }
;   DI void operator()(const f32x4 (&acc)[2][2][4][2], const pg8::Unit& u, int wr, int wc, int fr, int fq) const {
;     const int row0 = u.pm * 256 + wr * 64 + fr, colb = u.pn * 256 + wc * 32 + 8 * fq;
; #pragma unroll
;     for (int ai = 0; ai < 2; ++ai)
; #pragma unroll
;       for (int m = 0; m < 4; ++m) {
;         const int row = row0 + ai * 128 + m * 16;
; #pragma unroll
;         for (int bj = 0; bj < 2; ++bj) {
;           const int col = colb + bj * 128;
;           f32x4 v0 = acc[ai][bj][m][0] * sc, v1 = acc[ai][bj][m][1] * sc;
;           u16* dst = nullptr;
;           if (MODE == 0) { if (col < N) dst = d0 + (size_t)row * ld0 + (col + coff2 + ((col < csplit) ? (coff1 - coff2) : 0)); }
;           else if (MODE == 1) {
;             const int oc = col + coff2 + ((col < csplit) ? (coff1 - coff2) : 0);
;             if (col < N) {
;               if (oc < 2048) dst = d0 + (size_t)row * 2048 + oc;
;               else if (oc < 2112) { rot(v0, v1, row, oc); dst = d2 + (size_t)row * 64 + (oc - 2048); }
;               else dst = d1 + (size_t)row * 4096 + (oc - 2112);
;             }
;           } else if (MODE == 3) {
;             if (col < N) { const bool lo = col < csplit; u16* bp = lo ? d0 : d1; const int ldd = lo ? 2048 : 4096, oc = lo ? col : col + (coff2 - 2112); dst = bp + (size_t)row * ldd + oc + (lo ? coff1 : 0); }
;           } else {
;             if (((col >> 6) % 3) == 2) rot(v0, v1, row, col);
;             dst = d0 + (size_t)row * 3072 + col;
;           }
;           if (dst) { u32x4 w = {pk2(v0[0], v0[1]), pk2(v0[2], v0[3]), pk2(v1[0], v1[1]), pk2(v1[2], v1[3])}; *(u32x4*)dst = w; }
	ds_read_b128 v[18:21], v182 offset:49152
	ds_read_b128 v[22:25], v182 offset:50176
	ds_read_b128 v[184:187], v182 offset:51200
	ds_read_b128 v[188:191], v182 offset:52224
	ds_read_b128 v[192:195], v182 offset:53248
	ds_read_b128 v[196:199], v182 offset:54272
	ds_read_b128 v[200:203], v182 offset:55296
	ds_read_b128 v[204:207], v182 offset:56320
	global_load_lds_dwordx4 v[164:165], off
	v_lshl_add_u64 v[164:165], v[170:171], 0, s[56:57]
	s_mov_b32 m0, s72
	s_nop 0
	global_load_lds_dwordx4 v[164:165], off
	s_barrier
	s_waitcnt lgkmcnt(0)
	s_nop 1
	v_mfma_scale_f32_16x16x128_f8f6f4 v[86:89], v[2:9], v[18:25], v[86:89], v172, v172 op_sel_hi:[0,0,0]
	s_nop 1
	v_mfma_scale_f32_16x16x128_f8f6f4 v[82:85], v[10:17], v[18:25], v[82:85], v172, v172 op_sel_hi:[0,0,0]
	s_nop 1
	v_mfma_scale_f32_16x16x128_f8f6f4 v[70:73], v[2:9], v[184:191], v[70:73], v172, v172 op_sel_hi:[0,0,0]
	s_nop 1
	v_mfma_scale_f32_16x16x128_f8f6f4 v[66:69], v[10:17], v[184:191], v[66:69], v172, v172 op_sel_hi:[0,0,0]
	s_nop 1
	v_mfma_scale_f32_16x16x128_f8f6f4 v[54:57], v[2:9], v[192:199], v[54:57], v172, v172 op_sel_hi:[0,0,0]
	s_nop 1
	v_mfma_scale_f32_16x16x128_f8f6f4 v[50:53], v[10:17], v[192:199], v[50:53], v172, v172 op_sel_hi:[0,0,0]
	s_nop 1
	v_mfma_scale_f32_16x16x128_f8f6f4 v[38:41], v[2:9], v[200:207], v[38:41], v172, v172 op_sel_hi:[0,0,0]
	s_nop 1
	v_mfma_scale_f32_16x16x128_f8f6f4 v[34:37], v[10:17], v[200:207], v[34:37], v172, v172 op_sel_hi:[0,0,0]
	s_barrier
	s_add_u32 s12, s12, 0x40080
	s_addc_u32 s13, s13, 0
	s_add_i32 s30, s30, s25
	v_lshl_add_u64 v[2:3], s[12:13], 0, v[0:1]
	s_mov_b32 m0, s30
	s_nop 0
	global_load_lds_dwordx4 v[2:3], off
	v_lshl_add_u64 v[2:3], s[12:13], 0, v[154:155]
	s_add_i32 m0, s30, 0x2000
	s_nop 0
	global_load_lds_dwordx4 v[2:3], off
	s_waitcnt vmcnt(6)
	s_barrier
	s_nop 1
	v_mfma_scale_f32_16x16x128_f8f6f4 v[78:81], v[208:215], v[18:25], v[78:81], v172, v172 op_sel_hi:[0,0,0]
	s_nop 1
	v_mfma_scale_f32_16x16x128_f8f6f4 v[74:77], v[236:243], v[18:25], v[74:77], v172, v172 op_sel_hi:[0,0,0]
	s_nop 1
	v_mfma_scale_f32_16x16x128_f8f6f4 v[62:65], v[208:215], v[184:191], v[62:65], v172, v172 op_sel_hi:[0,0,0]
	s_nop 1
	v_mfma_scale_f32_16x16x128_f8f6f4 v[58:61], v[236:243], v[184:191], v[58:61], v172, v172 op_sel_hi:[0,0,0]
	s_nop 1
	v_mfma_scale_f32_16x16x128_f8f6f4 v[46:49], v[208:215], v[192:199], v[46:49], v172, v172 op_sel_hi:[0,0,0]
	s_nop 1
	v_mfma_scale_f32_16x16x128_f8f6f4 v[42:45], v[236:243], v[192:199], v[42:45], v172, v172 op_sel_hi:[0,0,0]
	s_nop 1
	v_mfma_scale_f32_16x16x128_f8f6f4 v[30:33], v[208:215], v[200:207], v[30:33], v172, v172 op_sel_hi:[0,0,0]
	s_nop 1
	v_mfma_scale_f32_16x16x128_f8f6f4 v[26:29], v[236:243], v[200:207], v[26:29], v172, v172 op_sel_hi:[0,0,0]
	s_add_i32 vcc_hi, vcc_hi, 2
	s_add_u32 s0, s0, 0x100
	s_addc_u32 s1, s1, 0
	s_add_u32 s95, s95, 0x100
	s_addc_u32 vcc_lo, vcc_lo, 0
	s_cmp_gt_u32 vcc_hi, 13
	s_barrier
	s_cbranch_scc0 .LBB0_381
	s_nop 15
	s_nop 15
	v_lshl_or_b32 v2, s28, 8, v175
	v_lshl_add_u32 v8, s29, 8, v173
	v_cmp_gt_i32_e32 vcc, s34, v2
	v_mov_b64_e32 v[4:5], 0
	v_add_u32_e32 v6, 0x650, v2
	s_and_saveexec_b64 s[12:13], vcc
	v_mov_b64_e32 v[4:5], s[96:97]
	s_movk_i32 s0, 0x3d00
	v_mad_i64_i32 v[4:5], s[0:1], v8, s0, v[4:5]
	s_movk_i32 s0, 0x800
	s_nop 0
	v_cmp_gt_i32_e64 s[0:1], s0, v2
	s_nop 1
	v_cndmask_b32_e64 v10, v6, v2, s[0:1]
	v_ashrrev_i32_e32 v11, 31, v10
	v_lshl_add_u64 v[4:5], v[10:11], 1, v[4:5]
	s_or_b64 exec, exec, s[12:13]
	v_cmp_ne_u64_e64 s[0:1], 0, v[4:5]
	s_and_saveexec_b64 s[12:13], s[0:1]
	s_movk_i32 s20, 0x600
	s_mov_b32 s86, 0x800000
	s_movk_i32 s87, 0x3fff
	v_readlane_b32 s3, v254, 29
	s_cbranch_execz .LBB0_386
	v_pk_mul_f32 v[12:13], v[152:153], s[88:89] op_sel_hi:[1,0]
	v_pk_mul_f32 v[10:11], v[150:151], s[88:89] op_sel_hi:[1,0]
	v_pk_mul_f32 v[14:15], v[148:149], s[88:89] op_sel_hi:[1,0]
	v_pk_mul_f32 v[16:17], v[146:147], s[88:89] op_sel_hi:[1,0]
	v_cvt_pk_bf16_f32 v10, v10, v11
	v_cvt_pk_bf16_f32 v11, v12, v13
	v_cvt_pk_bf16_f32 v12, v16, v17
	v_cvt_pk_bf16_f32 v13, v14, v15
	global_store_dwordx4 v[4:5], v[10:13], off

; #define PG8_STAGE(bufoff, gbase, voff) do { _Pragma("unroll") for (int _i = 0; _i < 2; ++_i) \
;         __builtin_amdgcn_global_load_lds((const unsigned*)((const char*)(gbase) + (voff)[_i]), (PG8_LAS unsigned*)(lds + (bufoff) + ldsw + _i * 8192), 16, 0, 0); } while (0)
; #define PG8_LDA(dst, b, h) do { _Pragma("unroll") for (int m = 0; m < 4; ++m) _Pragma("unroll") for (int k = 0; k < 2; ++k) dst[m][k] = *(const PG8_LAS bf16x8*)(lds + PG8_SA(b, h) + aoff + m * 2048 + k * 1024); } while (0)
; #define PG8_LDB(dst, b, h) do { _Pragma("unroll") for (int n = 0; n < 2; ++n) _Pragma("unroll") for (int k = 0; k < 2; ++k) dst[n][k] = *(const PG8_LAS bf16x8*)(lds + PG8_SB(b, h) + boff + n * 2048 + k * 1024); } while (0)
; #define PG8_WAIT_L(n) asm volatile("s_waitcnt lgkmcnt(" #n ")" ::: "memory")
; #define PG8_BAR __builtin_amdgcn_s_barrier()
; #define PG8_SCHED __builtin_amdgcn_sched_barrier(0)
; template <bool FP8, class Epi, class Sched>
; __device__ __forceinline__ void gemm_phase(PG8_LAS unsigned char* lds, const Gemm g, const Sched& S, const Epi& E) {
;     ...
;             PG8_LDB(B0, 0, 0); PG8_SCHED; PG8_LDA(At, 0, 0); PG8_STAGE(PG8_SA(1, 1), a1 + hstepA, voffA);
;             PG8_WAIT_L(8); PG8_BAR; PG8_WAIT_L(0); PG8_MMA(0, 0, At, B0); PG8_BAR; PG8_SCHED;
;             PG8_LDB(B1, 0, 1); PG8_STAGE(PG8_SB(0, 0), b2, voffB);
;             PG8_BAR; PG8_WAIT_L(0); PG8_MMA(0, 1, At, B1); PG8_BAR;
;             PG8_LDA(At, 0, 1); PG8_STAGE(PG8_SA(0, 0), a2, voffA);
;             PG8_BAR; PG8_WAIT_L(0); PG8_MMA(1, 0, At, B0); PG8_BAR; PG8_SCHED;
.LBB0_458:
	s_add_u32 s12, s0, 0xfff80080
	s_addc_u32 s13, s1, -1
	s_add_i32 s30, 0, 0x10000
	v_add_u32_e32 v0, s30, v167
	ds_read_b128 v[142:145], v0
	ds_read_b128 v[146:149], v0 offset:1024
	ds_read_b128 v[150:153], v0 offset:2048
	ds_read_b128 v[154:157], v0 offset:3072
	s_cmp_eq_u32 vcc_hi, 28
	s_cselect_b32 s69, s17, s13
	s_cselect_b32 s68, s70, s12
	s_cselect_b32 s13, s15, vcc_lo
	s_cselect_b32 s12, s71, s95
	v_lshl_add_u64 v[174:175], s[0:1], 0, v[138:139]
	s_add_i32 m0, s26, 0xc000
	ds_read_b128 v[158:161], v169
	ds_read_b128 v[162:165], v169 offset:1024
	ds_read_b128 v[170:173], v169 offset:2048
	ds_read_b128 v[182:185], v169 offset:3072
	ds_read_b128 v[186:189], v169 offset:4096
	ds_read_b128 v[190:193], v169 offset:5120
	ds_read_b128 v[194:197], v169 offset:6144
	ds_read_b128 v[198:201], v169 offset:7168
	global_load_lds_dwordx4 v[174:175], off
	v_lshl_add_u64 v[174:175], s[0:1], 0, v[140:141]
	s_add_i32 m0, s26, 0xe000
	s_nop 0
	global_load_lds_dwordx4 v[174:175], off
	s_waitcnt lgkmcnt(8)
	s_barrier
	s_waitcnt lgkmcnt(0)
	v_mfma_f32_16x16x32_bf16 v[126:129], v[142:145], v[158:161], v[126:129]
	v_mfma_f32_16x16x32_bf16 v[122:125], v[150:153], v[158:161], v[122:125]
	v_mfma_f32_16x16x32_bf16 v[110:113], v[142:145], v[170:173], v[110:113]
	v_mfma_f32_16x16x32_bf16 v[106:109], v[150:153], v[170:173], v[106:109]
	v_mfma_f32_16x16x32_bf16 v[94:97], v[142:145], v[186:189], v[94:97]
	v_mfma_f32_16x16x32_bf16 v[90:93], v[150:153], v[186:189], v[90:93]
	v_mfma_f32_16x16x32_bf16 v[78:81], v[142:145], v[194:197], v[78:81]
	v_mfma_f32_16x16x32_bf16 v[74:77], v[150:153], v[194:197], v[74:77]
	v_mfma_f32_16x16x32_bf16 v[126:129], v[146:149], v[162:165], v[126:129]
	v_mfma_f32_16x16x32_bf16 v[122:125], v[154:157], v[162:165], v[122:125]
	v_mfma_f32_16x16x32_bf16 v[110:113], v[146:149], v[182:185], v[110:113]
	v_mfma_f32_16x16x32_bf16 v[106:109], v[154:157], v[182:185], v[106:109]
	v_mfma_f32_16x16x32_bf16 v[94:97], v[146:149], v[190:193], v[94:97]
	v_mfma_f32_16x16x32_bf16 v[90:93], v[154:157], v[190:193], v[90:93]
	v_mfma_f32_16x16x32_bf16 v[78:81], v[146:149], v[198:201], v[78:81]
	v_mfma_f32_16x16x32_bf16 v[74:77], v[154:157], v[198:201], v[74:77]
	s_barrier
	s_add_i32 s86, 0, 0x14000
	s_add_i32 s30, s30, s25
	v_add_u32_e32 v0, s86, v167
	v_lshl_add_u64 v[174:175], s[12:13], 0, v[134:135]
	s_mov_b32 m0, s30
	ds_read_b128 v[202:205], v0
	ds_read_b128 v[206:209], v0 offset:1024
	ds_read_b128 v[210:213], v0 offset:2048
	ds_read_b128 v[214:217], v0 offset:3072
	global_load_lds_dwordx4 v[174:175], off
	v_lshl_add_u64 v[236:237], s[12:13], 0, v[130:131]
	s_add_i32 m0, s30, 0x2000
	s_nop 0
	global_load_lds_dwordx4 v[236:237], off
	s_barrier
	s_waitcnt lgkmcnt(0)
	v_mfma_f32_16x16x32_bf16 v[118:121], v[202:205], v[158:161], v[118:121]
	v_mfma_f32_16x16x32_bf16 v[114:117], v[210:213], v[158:161], v[114:117]
	v_mfma_f32_16x16x32_bf16 v[102:105], v[202:205], v[170:173], v[102:105]
	v_mfma_f32_16x16x32_bf16 v[98:101], v[210:213], v[170:173], v[98:101]
	v_mfma_f32_16x16x32_bf16 v[86:89], v[202:205], v[186:189], v[86:89]
	v_mfma_f32_16x16x32_bf16 v[82:85], v[210:213], v[186:189], v[82:85]
	v_mfma_f32_16x16x32_bf16 v[70:73], v[202:205], v[194:197], v[70:73]
	v_mfma_f32_16x16x32_bf16 v[66:69], v[210:213], v[194:197], v[66:69]
	v_mfma_f32_16x16x32_bf16 v[118:121], v[206:209], v[162:165], v[118:121]
	v_mfma_f32_16x16x32_bf16 v[114:117], v[214:217], v[162:165], v[114:117]
	v_mfma_f32_16x16x32_bf16 v[102:105], v[206:209], v[182:185], v[102:105]
	v_mfma_f32_16x16x32_bf16 v[98:101], v[214:217], v[182:185], v[98:101]
	v_mfma_f32_16x16x32_bf16 v[86:89], v[206:209], v[190:193], v[86:89]
	v_mfma_f32_16x16x32_bf16 v[82:85], v[214:217], v[190:193], v[82:85]
	v_mfma_f32_16x16x32_bf16 v[70:73], v[206:209], v[198:201], v[70:73]
	v_mfma_f32_16x16x32_bf16 v[66:69], v[214:217], v[198:201], v[66:69]
	s_mov_b32 m0, s26
	v_lshl_add_u64 v[238:239], s[68:69], 0, v[136:137]
	s_barrier
	ds_read_b128 v[158:161], v169 offset:16384
	ds_read_b128 v[162:165], v169 offset:17408
	ds_read_b128 v[170:173], v169 offset:18432
	ds_read_b128 v[182:185], v169 offset:19456
	ds_read_b128 v[186:189], v169 offset:20480
	ds_read_b128 v[190:193], v169 offset:21504
	ds_read_b128 v[194:197], v169 offset:22528
	ds_read_b128 v[198:201], v169 offset:23552
	global_load_lds_dwordx4 v[238:239], off
	v_lshl_add_u64 v[240:241], s[68:69], 0, v[132:133]
	s_mov_b32 m0, s27
	s_nop 0
	global_load_lds_dwordx4 v[240:241], off
	s_barrier
	s_waitcnt lgkmcnt(0)
	v_mfma_f32_16x16x32_bf16 v[62:65], v[142:145], v[158:161], v[62:65]
	v_mfma_f32_16x16x32_bf16 v[58:61], v[150:153], v[158:161], v[58:61]
	v_mfma_f32_16x16x32_bf16 v[46:49], v[142:145], v[170:173], v[46:49]
	v_mfma_f32_16x16x32_bf16 v[42:45], v[150:153], v[170:173], v[42:45]
	v_mfma_f32_16x16x32_bf16 v[30:33], v[142:145], v[186:189], v[30:33]
	v_mfma_f32_16x16x32_bf16 v[26:29], v[150:153], v[186:189], v[26:29]
	v_mfma_f32_16x16x32_bf16 v[14:17], v[142:145], v[194:197], v[14:17]
	v_mfma_f32_16x16x32_bf16 v[10:13], v[150:153], v[194:197], v[10:13]
	v_mfma_f32_16x16x32_bf16 v[62:65], v[146:149], v[162:165], v[62:65]
	v_mfma_f32_16x16x32_bf16 v[58:61], v[154:157], v[162:165], v[58:61]
	v_mfma_f32_16x16x32_bf16 v[46:49], v[146:149], v[182:185], v[46:49]
	v_mfma_f32_16x16x32_bf16 v[42:45], v[154:157], v[182:185], v[42:45]
	v_mfma_f32_16x16x32_bf16 v[30:33], v[146:149], v[190:193], v[30:33]
	v_mfma_f32_16x16x32_bf16 v[26:29], v[154:157], v[190:193], v[26:29]
	v_mfma_f32_16x16x32_bf16 v[14:17], v[146:149], v[198:201], v[14:17]
	v_mfma_f32_16x16x32_bf16 v[10:13], v[154:157], v[198:201], v[10:13]
	s_barrier
; #define PG8_STAGE(bufoff, gbase, voff) do { _Pragma("unroll") for (int _i = 0; _i < 2; ++_i) \
;         __builtin_amdgcn_global_load_lds((const unsigned*)((const char*)(gbase) + (voff)[_i]), (PG8_LAS unsigned*)(lds + (bufoff) + ldsw + _i * 8192), 16, 0, 0); } while (0)
; #define PG8_LDA(dst, b, h) do { _Pragma("unroll") for (int m = 0; m < 4; ++m) _Pragma("unroll") for (int k = 0; k < 2; ++k) dst[m][k] = *(const PG8_LAS bf16x8*)(lds + PG8_SA(b, h) + aoff + m * 2048 + k * 1024); } while (0)
; #define PG8_LDB(dst, b, h) do { _Pragma("unroll") for (int n = 0; n < 2; ++n) _Pragma("unroll") for (int k = 0; k < 2; ++k) dst[n][k] = *(const PG8_LAS bf16x8*)(lds + PG8_SB(b, h) + boff + n * 2048 + k * 1024); } while (0)
; #define PG8_WAIT_V(n) asm volatile("s_waitcnt vmcnt(" #n ")" ::: "memory")
; #define PG8_WAIT_L(n) asm volatile("s_waitcnt lgkmcnt(" #n ")" ::: "memory")
; #define PG8_BAR __builtin_amdgcn_s_barrier()
; #define PG8_SCHED __builtin_amdgcn_sched_barrier(0)
; template <bool FP8, class Epi, class Sched>
; __device__ __forceinline__ void gemm_phase(PG8_LAS unsigned char* lds, const Gemm g, const Sched& S, const Epi& E) {
;     ...
;             PG8_LDB(B0, 0, 0); PG8_SCHED; PG8_LDA(At, 0, 0); PG8_STAGE(PG8_SA(1, 1), a1 + hstepA, voffA);
;             PG8_WAIT_L(8); PG8_BAR; PG8_WAIT_L(0); PG8_MMA(0, 0, At, B0); PG8_BAR; PG8_SCHED;
;             PG8_LDB(B1, 0, 1); PG8_STAGE(PG8_SB(0, 0), b2, voffB);
;             PG8_BAR; PG8_WAIT_L(0); PG8_MMA(0, 1, At, B1); PG8_BAR;
;             PG8_LDA(At, 0, 1); PG8_STAGE(PG8_SA(0, 0), a2, voffA);
;             PG8_BAR; PG8_WAIT_L(0); PG8_MMA(1, 0, At, B0); PG8_BAR; PG8_SCHED;
;             PG8_STAGE(PG8_SB(0, 1), b2 + hstep, voffB);
;             PG8_WAIT_V(6); PG8_BAR; PG8_MMA(1, 1, At, B1); PG8_BAR;
;             PG8_LDB(B0, 1, 0); PG8_SCHED; PG8_LDA(At, 1, 0); PG8_STAGE(PG8_SA(0, 1), a2 + hstepA, voffA);
;             PG8_WAIT_L(8); PG8_BAR; PG8_WAIT_L(0); PG8_MMA(0, 0, At, B0); PG8_BAR; PG8_SCHED;
;             PG8_LDB(B1, 1, 1); PG8_STAGE(PG8_SB(1, 0), b3, voffB);
;             PG8_BAR; PG8_WAIT_L(0); PG8_MMA(0, 1, At, B1); PG8_BAR;
;             PG8_LDA(At, 1, 1); PG8_STAGE(PG8_SA(1, 0), a3, voffA);
;             PG8_BAR; PG8_WAIT_L(0); PG8_MMA(1, 0, At, B0); PG8_BAR; PG8_SCHED;
;             PG8_STAGE(PG8_SB(1, 1), b3 + hstep, voffB);
;             PG8_WAIT_V(6); PG8_BAR; PG8_MMA(1, 1, At, B1); PG8_BAR;
	s_add_u32 s30, s12, 0x80000
	s_addc_u32 s31, s13, 0
	s_add_i32 s86, s86, s25
	v_lshl_add_u64 v[142:143], s[30:31], 0, v[134:135]
	s_mov_b32 m0, s86
	s_nop 0
	global_load_lds_dwordx4 v[142:143], off
	v_lshl_add_u64 v[142:143], s[30:31], 0, v[130:131]
	s_add_i32 m0, s86, 0x2000
	s_nop 0
	global_load_lds_dwordx4 v[142:143], off
	s_waitcnt vmcnt(6)
	s_barrier
	v_mfma_f32_16x16x32_bf16 v[54:57], v[202:205], v[158:161], v[54:57]
	v_mfma_f32_16x16x32_bf16 v[50:53], v[210:213], v[158:161], v[50:53]
	v_mfma_f32_16x16x32_bf16 v[38:41], v[202:205], v[170:173], v[38:41]
	v_mfma_f32_16x16x32_bf16 v[34:37], v[210:213], v[170:173], v[34:37]
	v_mfma_f32_16x16x32_bf16 v[22:25], v[202:205], v[186:189], v[22:25]
	v_mfma_f32_16x16x32_bf16 v[18:21], v[210:213], v[186:189], v[18:21]
	v_mfma_f32_16x16x32_bf16 v[6:9], v[202:205], v[194:197], v[6:9]
	v_mfma_f32_16x16x32_bf16 v[2:5], v[210:213], v[194:197], v[2:5]
	v_mfma_f32_16x16x32_bf16 v[54:57], v[206:209], v[162:165], v[54:57]
	v_mfma_f32_16x16x32_bf16 v[50:53], v[214:217], v[162:165], v[50:53]
	v_mfma_f32_16x16x32_bf16 v[38:41], v[206:209], v[182:185], v[38:41]
	v_mfma_f32_16x16x32_bf16 v[34:37], v[214:217], v[182:185], v[34:37]
	v_mfma_f32_16x16x32_bf16 v[22:25], v[206:209], v[190:193], v[22:25]
	v_mfma_f32_16x16x32_bf16 v[18:21], v[214:217], v[190:193], v[18:21]
	v_mfma_f32_16x16x32_bf16 v[6:9], v[206:209], v[198:201], v[6:9]
	v_mfma_f32_16x16x32_bf16 v[2:5], v[214:217], v[198:201], v[2:5]
	s_add_i32 s86, 0, 0x18000
	v_add_u32_e32 v0, s86, v167
	s_barrier
	ds_read_b128 v[142:145], v0
	ds_read_b128 v[146:149], v0 offset:1024
	ds_read_b128 v[150:153], v0 offset:2048
	ds_read_b128 v[154:157], v0 offset:3072
	s_add_u32 s30, s68, 0x80000
	s_addc_u32 s31, s69, 0
	s_mov_b32 m0, s54
	v_lshl_add_u64 v[202:203], s[30:31], 0, v[136:137]
	ds_read_b128 v[158:161], v169 offset:32768
	ds_read_b128 v[162:165], v169 offset:33792
	ds_read_b128 v[170:173], v169 offset:34816
	ds_read_b128 v[182:185], v169 offset:35840
	ds_read_b128 v[186:189], v169 offset:36864
	ds_read_b128 v[190:193], v169 offset:37888
	ds_read_b128 v[194:197], v169 offset:38912
	ds_read_b128 v[198:201], v169 offset:39936
	global_load_lds_dwordx4 v[202:203], off
	v_lshl_add_u64 v[202:203], s[30:31], 0, v[132:133]
	s_mov_b32 m0, s72
	s_nop 0
	global_load_lds_dwordx4 v[202:203], off
	s_waitcnt lgkmcnt(8)
	s_barrier
	s_waitcnt lgkmcnt(0)
	v_mfma_f32_16x16x32_bf16 v[126:129], v[142:145], v[158:161], v[126:129]
	v_mfma_f32_16x16x32_bf16 v[122:125], v[150:153], v[158:161], v[122:125]
	v_mfma_f32_16x16x32_bf16 v[110:113], v[142:145], v[170:173], v[110:113]
	v_mfma_f32_16x16x32_bf16 v[106:109], v[150:153], v[170:173], v[106:109]
	v_mfma_f32_16x16x32_bf16 v[94:97], v[142:145], v[186:189], v[94:97]
	v_mfma_f32_16x16x32_bf16 v[90:93], v[150:153], v[186:189], v[90:93]
	v_mfma_f32_16x16x32_bf16 v[78:81], v[142:145], v[194:197], v[78:81]
	v_mfma_f32_16x16x32_bf16 v[74:77], v[150:153], v[194:197], v[74:77]
	v_mfma_f32_16x16x32_bf16 v[126:129], v[146:149], v[162:165], v[126:129]
	v_mfma_f32_16x16x32_bf16 v[122:125], v[154:157], v[162:165], v[122:125]
	v_mfma_f32_16x16x32_bf16 v[110:113], v[146:149], v[182:185], v[110:113]
	v_mfma_f32_16x16x32_bf16 v[106:109], v[154:157], v[182:185], v[106:109]
	v_mfma_f32_16x16x32_bf16 v[94:97], v[146:149], v[190:193], v[94:97]
	v_mfma_f32_16x16x32_bf16 v[90:93], v[154:157], v[190:193], v[90:93]
	v_mfma_f32_16x16x32_bf16 v[78:81], v[146:149], v[198:201], v[78:81]
	v_mfma_f32_16x16x32_bf16 v[74:77], v[154:157], v[198:201], v[74:77]
	s_barrier
	s_add_i32 s30, 0, 0x1c000
	s_add_i32 s31, s86, s25
	v_add_u32_e32 v0, s30, v167
	v_lshl_add_u64 v[174:175], v[174:175], 0, s[56:57]
	s_mov_b32 m0, s31
	ds_read_b128 v[202:205], v0
	ds_read_b128 v[206:209], v0 offset:1024
	ds_read_b128 v[210:213], v0 offset:2048
	ds_read_b128 v[214:217], v0 offset:3072
	global_load_lds_dwordx4 v[174:175], off
	v_lshl_add_u64 v[174:175], v[236:237], 0, s[56:57]
	s_add_i32 m0, s31, 0x2000
	s_nop 0
	global_load_lds_dwordx4 v[174:175], off
	s_barrier
	s_waitcnt lgkmcnt(0)
	v_mfma_f32_16x16x32_bf16 v[118:121], v[202:205], v[158:161], v[118:121]
	v_mfma_f32_16x16x32_bf16 v[114:117], v[210:213], v[158:161], v[114:117]
	v_mfma_f32_16x16x32_bf16 v[102:105], v[202:205], v[170:173], v[102:105]
	v_mfma_f32_16x16x32_bf16 v[98:101], v[210:213], v[170:173], v[98:101]
	v_mfma_f32_16x16x32_bf16 v[86:89], v[202:205], v[186:189], v[86:89]
	v_mfma_f32_16x16x32_bf16 v[82:85], v[210:213], v[186:189], v[82:85]
	v_mfma_f32_16x16x32_bf16 v[70:73], v[202:205], v[194:197], v[70:73]
	v_mfma_f32_16x16x32_bf16 v[66:69], v[210:213], v[194:197], v[66:69]
	v_mfma_f32_16x16x32_bf16 v[118:121], v[206:209], v[162:165], v[118:121]
	v_mfma_f32_16x16x32_bf16 v[114:117], v[214:217], v[162:165], v[114:117]
	v_mfma_f32_16x16x32_bf16 v[102:105], v[206:209], v[182:185], v[102:105]
	v_mfma_f32_16x16x32_bf16 v[98:101], v[214:217], v[182:185], v[98:101]
	v_mfma_f32_16x16x32_bf16 v[86:89], v[206:209], v[190:193], v[86:89]
	v_mfma_f32_16x16x32_bf16 v[82:85], v[214:217], v[190:193], v[82:85]
	v_mfma_f32_16x16x32_bf16 v[70:73], v[206:209], v[198:201], v[70:73]
	v_mfma_f32_16x16x32_bf16 v[66:69], v[214:217], v[198:201], v[66:69]
	s_mov_b32 m0, s73
	v_lshl_add_u64 v[174:175], v[238:239], 0, s[56:57]
	s_barrier
	ds_read_b128 v[158:161], v169 offset:49152
	ds_read_b128 v[162:165], v169 offset:50176
	ds_read_b128 v[170:173], v169 offset:51200
	ds_read_b128 v[182:185], v169 offset:52224
	ds_read_b128 v[186:189], v169 offset:53248
	ds_read_b128 v[190:193], v169 offset:54272
	ds_read_b128 v[194:197], v169 offset:55296
	ds_read_b128 v[198:201], v169 offset:56320
	global_load_lds_dwordx4 v[174:175], off
	v_lshl_add_u64 v[174:175], v[240:241], 0, s[56:57]
	s_mov_b32 m0, s87
	s_nop 0
	global_load_lds_dwordx4 v[174:175], off
	s_barrier
; #define PG8_BAR __builtin_amdgcn_s_barrier()
; template <bool FP8, class Epi, class Sched>
; __device__ __forceinline__ void gemm_phase(PG8_LAS unsigned char* lds, const Gemm g, const Sched& S, const Epi& E) {
;     ...
;             PG8_LDB(B0, 0, 0); PG8_SCHED; PG8_LDA(At, 0, 0); PG8_STAGE(PG8_SA(1, 1), a1 + hstepA, voffA);
;             PG8_WAIT_L(8); PG8_BAR; PG8_WAIT_L(0); PG8_MMA(0, 0, At, B0); PG8_BAR; PG8_SCHED;
;             PG8_LDB(B1, 0, 1); PG8_STAGE(PG8_SB(0, 0), b2, voffB);
;             PG8_BAR; PG8_WAIT_L(0); PG8_MMA(0, 1, At, B1); PG8_BAR;
;             PG8_LDA(At, 0, 1); PG8_STAGE(PG8_SA(0, 0), a2, voffA);
;             PG8_BAR; PG8_WAIT_L(0); PG8_MMA(1, 0, At, B0); PG8_BAR; PG8_SCHED;
;             PG8_STAGE(PG8_SB(0, 1), b2 + hstep, voffB);
;             PG8_WAIT_V(6); PG8_BAR; PG8_MMA(1, 1, At, B1); PG8_BAR;
;             PG8_LDB(B0, 1, 0); PG8_SCHED; PG8_LDA(At, 1, 0); PG8_STAGE(PG8_SA(0, 1), a2 + hstepA, voffA);
;             PG8_WAIT_L(8); PG8_BAR; PG8_WAIT_L(0); PG8_MMA(0, 0, At, B0); PG8_BAR; PG8_SCHED;
;             PG8_LDB(B1, 1, 1); PG8_STAGE(PG8_SB(1, 0), b3, voffB);
;             PG8_BAR; PG8_WAIT_L(0); PG8_MMA(0, 1, At, B1); PG8_BAR;
;             PG8_LDA(At, 1, 1); PG8_STAGE(PG8_SA(1, 0), a3, voffA);
;             PG8_BAR; PG8_WAIT_L(0); PG8_MMA(1, 0, At, B0); PG8_BAR; PG8_SCHED;
;             PG8_STAGE(PG8_SB(1, 1), b3 + hstep, voffB);
;             PG8_WAIT_V(6); PG8_BAR; PG8_MMA(1, 1, At, B1); PG8_BAR;
;   DI void operator()(const f32x4 (&acc)[2][2][4][2], const pg8::Unit& u, int wr, int wc, int fr, int fq) const {
;     const int row0 = u.pm * 256 + wr * 64 + fr, colb = u.pn * 256 + wc * 32 + 8 * fq;
; #pragma unroll
;     for (int ai = 0; ai < 2; ++ai)
; #pragma unroll
;       for (int m = 0; m < 4; ++m) {
;         const int row = row0 + ai * 128 + m * 16;
; #pragma unroll
;         for (int bj = 0; bj < 2; ++bj) {
;           const int col = colb + bj * 128;
;           f32x4 v0 = acc[ai][bj][m][0] * sc, v1 = acc[ai][bj][m][1] * sc;
;           u16* dst = nullptr;
;           if (MODE == 0) { if (col < N) dst = d0 + (size_t)row * ld0 + (col + coff2 + ((col < csplit) ? (coff1 - coff2) : 0)); }
;           else if (MODE == 1) {
;             const int oc = col + coff2 + ((col < csplit) ? (coff1 - coff2) : 0);
;             if (col < N) {
;               if (oc < 2048) dst = d0 + (size_t)row * 2048 + oc;
	s_waitcnt lgkmcnt(0)
	v_mfma_f32_16x16x32_bf16 v[62:65], v[142:145], v[158:161], v[62:65]
	v_mfma_f32_16x16x32_bf16 v[58:61], v[150:153], v[158:161], v[58:61]
	v_mfma_f32_16x16x32_bf16 v[46:49], v[142:145], v[170:173], v[46:49]
	v_mfma_f32_16x16x32_bf16 v[42:45], v[150:153], v[170:173], v[42:45]
	v_mfma_f32_16x16x32_bf16 v[30:33], v[142:145], v[186:189], v[30:33]
	v_mfma_f32_16x16x32_bf16 v[26:29], v[150:153], v[186:189], v[26:29]
	v_mfma_f32_16x16x32_bf16 v[14:17], v[142:145], v[194:197], v[14:17]
	v_mfma_f32_16x16x32_bf16 v[10:13], v[150:153], v[194:197], v[10:13]
	v_mfma_f32_16x16x32_bf16 v[62:65], v[146:149], v[162:165], v[62:65]
	v_mfma_f32_16x16x32_bf16 v[58:61], v[154:157], v[162:165], v[58:61]
	v_mfma_f32_16x16x32_bf16 v[46:49], v[146:149], v[182:185], v[46:49]
	v_mfma_f32_16x16x32_bf16 v[42:45], v[154:157], v[182:185], v[42:45]
	v_mfma_f32_16x16x32_bf16 v[30:33], v[146:149], v[190:193], v[30:33]
	v_mfma_f32_16x16x32_bf16 v[26:29], v[154:157], v[190:193], v[26:29]
	v_mfma_f32_16x16x32_bf16 v[14:17], v[146:149], v[198:201], v[14:17]
	v_mfma_f32_16x16x32_bf16 v[10:13], v[154:157], v[198:201], v[10:13]
	s_barrier
	s_add_u32 s12, s12, 0x80080
	s_addc_u32 s13, s13, 0
	s_add_i32 s30, s30, s25
	v_lshl_add_u64 v[142:143], s[12:13], 0, v[134:135]
	s_mov_b32 m0, s30
	s_nop 0
	global_load_lds_dwordx4 v[142:143], off
	v_lshl_add_u64 v[142:143], s[12:13], 0, v[130:131]
	s_add_i32 m0, s30, 0x2000
	s_nop 0
	global_load_lds_dwordx4 v[142:143], off
	s_waitcnt vmcnt(6)
	s_barrier
	v_mfma_f32_16x16x32_bf16 v[54:57], v[202:205], v[158:161], v[54:57]
	v_mfma_f32_16x16x32_bf16 v[50:53], v[210:213], v[158:161], v[50:53]
	v_mfma_f32_16x16x32_bf16 v[38:41], v[202:205], v[170:173], v[38:41]
	v_mfma_f32_16x16x32_bf16 v[34:37], v[210:213], v[170:173], v[34:37]
	v_mfma_f32_16x16x32_bf16 v[22:25], v[202:205], v[186:189], v[22:25]
	v_mfma_f32_16x16x32_bf16 v[18:21], v[210:213], v[186:189], v[18:21]
	v_mfma_f32_16x16x32_bf16 v[6:9], v[202:205], v[194:197], v[6:9]
	v_mfma_f32_16x16x32_bf16 v[2:5], v[210:213], v[194:197], v[2:5]
	v_mfma_f32_16x16x32_bf16 v[54:57], v[206:209], v[162:165], v[54:57]
	v_mfma_f32_16x16x32_bf16 v[50:53], v[214:217], v[162:165], v[50:53]
	v_mfma_f32_16x16x32_bf16 v[38:41], v[206:209], v[182:185], v[38:41]
	v_mfma_f32_16x16x32_bf16 v[34:37], v[214:217], v[182:185], v[34:37]
	v_mfma_f32_16x16x32_bf16 v[22:25], v[206:209], v[190:193], v[22:25]
	v_mfma_f32_16x16x32_bf16 v[18:21], v[214:217], v[190:193], v[18:21]
	v_mfma_f32_16x16x32_bf16 v[6:9], v[206:209], v[198:201], v[6:9]
	v_mfma_f32_16x16x32_bf16 v[2:5], v[214:217], v[198:201], v[2:5]
	s_add_i32 vcc_hi, vcc_hi, 2
	s_add_u32 s0, s0, 0x100
	s_addc_u32 s1, s1, 0
	s_add_u32 s95, s95, 0x100
	s_addc_u32 vcc_lo, vcc_lo, 0
	s_cmp_gt_u32 vcc_hi, 29
	s_barrier
	s_cbranch_scc0 .LBB0_458
	v_lshl_add_u32 v144, s29, 8, v166
	v_lshl_or_b32 v170, s28, 8, v168
	s_movk_i32 s0, 0x240
	v_lshlrev_b32_e32 v0, 5, v144
	v_cmp_gt_i32_e32 vcc, s0, v170
	v_and_b32_e32 v171, 0xf9e0, v0
	s_movk_i32 s0, 0xa00
	v_cndmask_b32_e32 v0, 0, v227, vcc
	v_ashrrev_i32_e32 v145, 31, v144
	v_add3_u32 v142, v170, v0, s0
	s_movk_i32 s0, 0xe40
	v_lshlrev_b64 v[150:151], 13, v[144:145]
	v_lshlrev_b64 v[146:147], 7, v[144:145]
	v_lshlrev_b64 v[148:149], 12, v[144:145]
	v_cmp_gt_i32_e32 vcc, s0, v170
	v_mov_b64_e32 v[164:165], 0
	s_and_saveexec_b64 s[12:13], vcc
	s_movk_i32 s15, 0x7ff
	s_movk_i32 s17, 0x83f
	v_readlane_b32 s3, v254, 29
	s_cbranch_execz .LBB0_469
	v_cmp_lt_i32_e64 s[0:1], s15, v142
	s_and_saveexec_b64 s[28:29], s[0:1]
	s_xor_b64 s[68:69], exec, s[28:29]
	s_cbranch_execz .LBB0_466
	v_cmp_lt_u32_e64 s[0:1], s17, v142
	s_and_saveexec_b64 s[28:29], s[0:1]
	s_xor_b64 s[0:1], exec, s[28:29]
	v_lshl_add_u64 v[152:153], s[4:5], 0, v[150:151]
	v_mov_b32_e32 v143, v1
	s_movk_i32 s28, 0xef80
	v_lshl_add_u64 v[152:153], v[142:143], 1, v[152:153]
	s_mov_b32 s29, -1
	v_lshl_add_u64 v[164:165], v[152:153], 0, s[28:29]
	s_or_saveexec_b64 s[0:1], s[0:1]
	v_mov_b32_e32 v152, v129
	v_mov_b32_e32 v154, v128
	v_mov_b32_e32 v157, v127
	v_mov_b32_e32 v0, v126
	v_mov_b32_e32 v158, v125
	v_mov_b32_e32 v160, v124
	v_mov_b32_e32 v163, v123
	v_mov_b32_e32 v143, v122
	s_xor_b64 exec, exec, s[0:1]
	s_cbranch_execz .LBB0_465
	v_lshlrev_b32_e32 v0, 3, v171
	v_lshl_add_u64 v[152:153], s[52:53], 0, v[0:1]
	v_lshlrev_b32_e32 v0, 2, v170
	v_and_b32_e32 v0, 0xe0, v0
	v_lshl_add_u64 v[152:153], v[152:153], 0, v[0:1]
	global_load_dwordx4 v[162:165], v[152:153], off offset:16
	global_load_dwordx4 v[156:159], v[152:153], off
	v_readlane_b32 s28, v250, 44
	v_readlane_b32 s29, v250, 45
	v_mov_b32_e32 v143, v1
	s_waitcnt vmcnt(0)
	v_pk_mul_f32 v[182:183], v[122:123], v[162:163]
	v_mul_f32_e32 v0, v129, v159
	v_pk_fma_f32 v[154:155], v[128:129], v[158:159], v[0:1] op_sel_hi:[1,1,0] neg_lo:[0,0,1] neg_hi:[0,0,1]
	v_mul_f32_e32 v0, v128, v159
	v_pk_fma_f32 v[152:153], v[128:129], v[158:159], v[0:1] op_sel:[1,0,0] op_sel_hi:[0,1,0]
	v_mul_f32_e32 v0, v125, v165
	v_pk_fma_f32 v[160:161], v[124:125], v[164:165], v[0:1] op_sel_hi:[1,1,0] neg_lo:[0,0,1] neg_hi:[0,0,1]
	v_mul_f32_e32 v0, v124, v165
	v_pk_fma_f32 v[158:159], v[124:125], v[164:165], v[0:1] op_sel:[1,0,0] op_sel_hi:[0,1,0]
	v_lshl_add_u64 v[164:165], s[28:29], 0, v[146:147]
	s_movk_i32 s28, 0xf000
	v_pk_mul_f32 v[172:173], v[126:127], v[156:157]
	v_pk_mul_f32 v[174:175], v[126:127], v[156:157] op_sel:[1,1] op_sel_hi:[0,1]
	v_pk_mul_f32 v[184:185], v[122:123], v[162:163] op_sel:[1,1] op_sel_hi:[0,1]
	v_lshl_add_u64 v[164:165], v[142:143], 1, v[164:165]
	s_mov_b32 s29, -1
	v_pk_fma_f32 v[156:157], v[126:127], v[156:157], v[174:175] op_sel_hi:[1,0,1]
	v_pk_fma_f32 v[162:163], v[122:123], v[162:163], v[184:185] op_sel_hi:[1,0,1]
	v_lshl_add_u64 v[164:165], v[164:165], 0, s[28:29]
	v_sub_f32_e32 v143, v182, v184
	v_sub_f32_e32 v0, v172, v174

; #define PG8_STAGE(bufoff, gbase, voff) do { _Pragma("unroll") for (int _i = 0; _i < 2; ++_i) \
;         __builtin_amdgcn_global_load_lds((const unsigned*)((const char*)(gbase) + (voff)[_i]), (PG8_LAS unsigned*)(lds + (bufoff) + ldsw + _i * 8192), 16, 0, 0); } while (0)
; #define PG8_LDA(dst, b, h) do { _Pragma("unroll") for (int m = 0; m < 4; ++m) _Pragma("unroll") for (int k = 0; k < 2; ++k) dst[m][k] = *(const PG8_LAS bf16x8*)(lds + PG8_SA(b, h) + aoff + m * 2048 + k * 1024); } while (0)
; #define PG8_LDB(dst, b, h) do { _Pragma("unroll") for (int n = 0; n < 2; ++n) _Pragma("unroll") for (int k = 0; k < 2; ++k) dst[n][k] = *(const PG8_LAS bf16x8*)(lds + PG8_SB(b, h) + boff + n * 2048 + k * 1024); } while (0)
; #define PG8_WAIT_V(n) asm volatile("s_waitcnt vmcnt(" #n ")" ::: "memory")
; #define PG8_WAIT_L(n) asm volatile("s_waitcnt lgkmcnt(" #n ")" ::: "memory")
; #define PG8_BAR __builtin_amdgcn_s_barrier()
; #define PG8_SCHED __builtin_amdgcn_sched_barrier(0)
; template <bool FP8, class Epi, class Sched>
; __device__ __forceinline__ void gemm_phase(PG8_LAS unsigned char* lds, const Gemm g, const Sched& S, const Epi& E) {
;     ...
;             PG8_LDB(B0, 0, 0); PG8_SCHED; PG8_LDA(At, 0, 0); PG8_STAGE(PG8_SA(1, 1), a1 + hstepA, voffA);
;             PG8_WAIT_L(8); PG8_BAR; PG8_WAIT_L(0); PG8_MMA(0, 0, At, B0); PG8_BAR; PG8_SCHED;
;             PG8_LDB(B1, 0, 1); PG8_STAGE(PG8_SB(0, 0), b2, voffB);
;             PG8_BAR; PG8_WAIT_L(0); PG8_MMA(0, 1, At, B1); PG8_BAR;
;             PG8_LDA(At, 0, 1); PG8_STAGE(PG8_SA(0, 0), a2, voffA);
;             PG8_BAR; PG8_WAIT_L(0); PG8_MMA(1, 0, At, B0); PG8_BAR; PG8_SCHED;
;             PG8_STAGE(PG8_SB(0, 1), b2 + hstep, voffB);
;             PG8_WAIT_V(6); PG8_BAR; PG8_MMA(1, 1, At, B1); PG8_BAR;
;             PG8_LDB(B0, 1, 0); PG8_SCHED; PG8_LDA(At, 1, 0); PG8_STAGE(PG8_SA(0, 1), a2 + hstepA, voffA);
;             PG8_WAIT_L(8); PG8_BAR; PG8_WAIT_L(0); PG8_MMA(0, 0, At, B0); PG8_BAR; PG8_SCHED;
;             PG8_LDB(B1, 1, 1); PG8_STAGE(PG8_SB(1, 0), b3, voffB);
;             PG8_BAR; PG8_WAIT_L(0); PG8_MMA(0, 1, At, B1); PG8_BAR;
;             PG8_LDA(At, 1, 1); PG8_STAGE(PG8_SA(1, 0), a3, voffA);
;             PG8_BAR; PG8_WAIT_L(0); PG8_MMA(1, 0, At, B0); PG8_BAR; PG8_SCHED;
.LBB0_672:
	s_add_u32 s10, s0, 0xfffc0080
	s_addc_u32 s11, s1, -1
	s_add_i32 s30, 0, 0x10000
	v_add_u32_e32 v6, s30, v174
	ds_read_b128 v[10:13], v6
	ds_read_b128 v[14:17], v6 offset:1024
	ds_read_b128 v[2:5], v6 offset:2048
	ds_read_b128 v[6:9], v6 offset:3072
	s_cmp_eq_u32 vcc_hi, 12
	s_cselect_b32 s69, s15, s11
	s_cselect_b32 s68, s87, s10
	s_cselect_b32 s11, s13, vcc_lo
	s_cselect_b32 s10, s94, s95
	v_lshl_add_u64 v[18:19], s[0:1], 0, v[160:161]
	s_add_i32 m0, s26, 0xc000
	ds_read_b128 v[184:187], v182
	ds_read_b128 v[188:191], v182 offset:1024
	ds_read_b128 v[192:195], v182 offset:2048
	ds_read_b128 v[196:199], v182 offset:3072
	ds_read_b128 v[200:203], v182 offset:4096
	ds_read_b128 v[204:207], v182 offset:5120
	ds_read_b128 v[236:239], v182 offset:6144
	ds_read_b128 v[240:243], v182 offset:7168
	global_load_lds_dwordx4 v[18:19], off
	v_lshl_add_u64 v[18:19], s[0:1], 0, v[162:163]
	s_add_i32 m0, s26, 0xe000
	s_nop 0
	global_load_lds_dwordx4 v[18:19], off
	s_waitcnt lgkmcnt(8)
	s_barrier
	s_waitcnt lgkmcnt(0)
	s_nop 1
	v_mfma_scale_f32_16x16x128_f8f6f4 v[150:153], v[10:17], v[184:191], v[150:153], v172, v172 op_sel_hi:[0,0,0]
	s_nop 1
	v_mfma_scale_f32_16x16x128_f8f6f4 v[146:149], v[2:9], v[184:191], v[146:149], v172, v172 op_sel_hi:[0,0,0]
	s_nop 1
	v_mfma_scale_f32_16x16x128_f8f6f4 v[134:137], v[10:17], v[192:199], v[134:137], v172, v172 op_sel_hi:[0,0,0]
	s_nop 1
	v_mfma_scale_f32_16x16x128_f8f6f4 v[130:133], v[2:9], v[192:199], v[130:133], v172, v172 op_sel_hi:[0,0,0]
	s_nop 1
	v_mfma_scale_f32_16x16x128_f8f6f4 v[118:121], v[10:17], v[200:207], v[118:121], v172, v172 op_sel_hi:[0,0,0]
	s_nop 1
	v_mfma_scale_f32_16x16x128_f8f6f4 v[114:117], v[2:9], v[200:207], v[114:117], v172, v172 op_sel_hi:[0,0,0]
	s_nop 1
	v_mfma_scale_f32_16x16x128_f8f6f4 v[102:105], v[10:17], v[236:243], v[102:105], v172, v172 op_sel_hi:[0,0,0]
	s_nop 1
	v_mfma_scale_f32_16x16x128_f8f6f4 v[98:101], v[2:9], v[236:243], v[98:101], v172, v172 op_sel_hi:[0,0,0]
	s_barrier
	s_add_i32 s86, 0, 0x14000
	s_add_i32 s30, s30, s25
	v_add_u32_e32 v22, s86, v174
	v_lshl_add_u64 v[164:165], s[10:11], 0, v[0:1]
	s_mov_b32 m0, s30
	ds_read_b128 v[208:211], v22
	ds_read_b128 v[212:215], v22 offset:1024
	ds_read_b128 v[18:21], v22 offset:2048
	ds_read_b128 v[22:25], v22 offset:3072
	global_load_lds_dwordx4 v[164:165], off
	v_lshl_add_u64 v[166:167], s[10:11], 0, v[154:155]
	s_add_i32 m0, s30, 0x2000
	s_nop 0
	global_load_lds_dwordx4 v[166:167], off
	s_barrier
	s_waitcnt lgkmcnt(0)
	s_nop 1
	v_mfma_scale_f32_16x16x128_f8f6f4 v[142:145], v[208:215], v[184:191], v[142:145], v172, v172 op_sel_hi:[0,0,0]
	s_nop 1
	v_mfma_scale_f32_16x16x128_f8f6f4 v[138:141], v[18:25], v[184:191], v[138:141], v172, v172 op_sel_hi:[0,0,0]
	s_nop 1
	v_mfma_scale_f32_16x16x128_f8f6f4 v[126:129], v[208:215], v[192:199], v[126:129], v172, v172 op_sel_hi:[0,0,0]
	s_nop 1
	v_mfma_scale_f32_16x16x128_f8f6f4 v[122:125], v[18:25], v[192:199], v[122:125], v172, v172 op_sel_hi:[0,0,0]
	s_nop 1
	v_mfma_scale_f32_16x16x128_f8f6f4 v[110:113], v[208:215], v[200:207], v[110:113], v172, v172 op_sel_hi:[0,0,0]
	s_nop 1
	v_mfma_scale_f32_16x16x128_f8f6f4 v[106:109], v[18:25], v[200:207], v[106:109], v172, v172 op_sel_hi:[0,0,0]
	s_nop 1
	v_mfma_scale_f32_16x16x128_f8f6f4 v[94:97], v[208:215], v[236:243], v[94:97], v172, v172 op_sel_hi:[0,0,0]
	s_nop 1
	v_mfma_scale_f32_16x16x128_f8f6f4 v[90:93], v[18:25], v[236:243], v[90:93], v172, v172 op_sel_hi:[0,0,0]
	s_mov_b32 m0, s26
	v_lshl_add_u64 v[168:169], s[68:69], 0, v[158:159]
	s_barrier
	ds_read_b128 v[184:187], v182 offset:16384
	ds_read_b128 v[188:191], v182 offset:17408
	ds_read_b128 v[192:195], v182 offset:18432
	ds_read_b128 v[196:199], v182 offset:19456
	ds_read_b128 v[200:203], v182 offset:20480
	ds_read_b128 v[204:207], v182 offset:21504
	ds_read_b128 v[236:239], v182 offset:22528
	ds_read_b128 v[240:243], v182 offset:23552
	global_load_lds_dwordx4 v[168:169], off
	v_lshl_add_u64 v[170:171], s[68:69], 0, v[156:157]
	s_mov_b32 m0, s27
	s_nop 0
	global_load_lds_dwordx4 v[170:171], off
	s_barrier
	s_waitcnt lgkmcnt(0)
	s_nop 1
	v_mfma_scale_f32_16x16x128_f8f6f4 v[86:89], v[10:17], v[184:191], v[86:89], v172, v172 op_sel_hi:[0,0,0]
	s_nop 1
	v_mfma_scale_f32_16x16x128_f8f6f4 v[82:85], v[2:9], v[184:191], v[82:85], v172, v172 op_sel_hi:[0,0,0]
	s_nop 1
	v_mfma_scale_f32_16x16x128_f8f6f4 v[70:73], v[10:17], v[192:199], v[70:73], v172, v172 op_sel_hi:[0,0,0]
	s_nop 1
	v_mfma_scale_f32_16x16x128_f8f6f4 v[66:69], v[2:9], v[192:199], v[66:69], v172, v172 op_sel_hi:[0,0,0]
	s_nop 1
	v_mfma_scale_f32_16x16x128_f8f6f4 v[54:57], v[10:17], v[200:207], v[54:57], v172, v172 op_sel_hi:[0,0,0]
	s_nop 1
	v_mfma_scale_f32_16x16x128_f8f6f4 v[50:53], v[2:9], v[200:207], v[50:53], v172, v172 op_sel_hi:[0,0,0]
	s_nop 1
	v_mfma_scale_f32_16x16x128_f8f6f4 v[38:41], v[10:17], v[236:243], v[38:41], v172, v172 op_sel_hi:[0,0,0]
	s_nop 1
	v_mfma_scale_f32_16x16x128_f8f6f4 v[34:37], v[2:9], v[236:243], v[34:37], v172, v172 op_sel_hi:[0,0,0]
	s_barrier
	s_add_u32 s30, s10, 0x40000
	s_addc_u32 s31, s11, 0
	s_add_i32 s86, s86, s25
	v_lshl_add_u64 v[2:3], s[30:31], 0, v[0:1]
	s_mov_b32 m0, s86
	s_nop 0
	global_load_lds_dwordx4 v[2:3], off
	v_lshl_add_u64 v[2:3], s[30:31], 0, v[154:155]
	s_add_i32 m0, s86, 0x2000
	s_nop 0
	global_load_lds_dwordx4 v[2:3], off
	s_waitcnt vmcnt(6)
	s_barrier
; #define PG8_STAGE(bufoff, gbase, voff) do { _Pragma("unroll") for (int _i = 0; _i < 2; ++_i) \
;         __builtin_amdgcn_global_load_lds((const unsigned*)((const char*)(gbase) + (voff)[_i]), (PG8_LAS unsigned*)(lds + (bufoff) + ldsw + _i * 8192), 16, 0, 0); } while (0)
; #define PG8_LDA(dst, b, h) do { _Pragma("unroll") for (int m = 0; m < 4; ++m) _Pragma("unroll") for (int k = 0; k < 2; ++k) dst[m][k] = *(const PG8_LAS bf16x8*)(lds + PG8_SA(b, h) + aoff + m * 2048 + k * 1024); } while (0)
; #define PG8_LDB(dst, b, h) do { _Pragma("unroll") for (int n = 0; n < 2; ++n) _Pragma("unroll") for (int k = 0; k < 2; ++k) dst[n][k] = *(const PG8_LAS bf16x8*)(lds + PG8_SB(b, h) + boff + n * 2048 + k * 1024); } while (0)
; #define PG8_WAIT_V(n) asm volatile("s_waitcnt vmcnt(" #n ")" ::: "memory")
; #define PG8_WAIT_L(n) asm volatile("s_waitcnt lgkmcnt(" #n ")" ::: "memory")
; #define PG8_BAR __builtin_amdgcn_s_barrier()
; #define PG8_SCHED __builtin_amdgcn_sched_barrier(0)
; template <bool FP8, class Epi, class Sched>
; __device__ __forceinline__ void gemm_phase(PG8_LAS unsigned char* lds, const Gemm g, const Sched& S, const Epi& E) {
;     ...
;             PG8_WAIT_V(6); PG8_BAR; PG8_MMA(1, 1, At, B1); PG8_BAR;
;             PG8_LDB(B0, 1, 0); PG8_SCHED; PG8_LDA(At, 1, 0); PG8_STAGE(PG8_SA(0, 1), a2 + hstepA, voffA);
;             PG8_WAIT_L(8); PG8_BAR; PG8_WAIT_L(0); PG8_MMA(0, 0, At, B0); PG8_BAR; PG8_SCHED;
;             PG8_LDB(B1, 1, 1); PG8_STAGE(PG8_SB(1, 0), b3, voffB);
;             PG8_BAR; PG8_WAIT_L(0); PG8_MMA(0, 1, At, B1); PG8_BAR;
	s_nop 1
	v_mfma_scale_f32_16x16x128_f8f6f4 v[78:81], v[208:215], v[184:191], v[78:81], v172, v172 op_sel_hi:[0,0,0]
	s_nop 1
	v_mfma_scale_f32_16x16x128_f8f6f4 v[74:77], v[18:25], v[184:191], v[74:77], v172, v172 op_sel_hi:[0,0,0]
	s_nop 1
	v_mfma_scale_f32_16x16x128_f8f6f4 v[62:65], v[208:215], v[192:199], v[62:65], v172, v172 op_sel_hi:[0,0,0]
	s_nop 1
	v_mfma_scale_f32_16x16x128_f8f6f4 v[58:61], v[18:25], v[192:199], v[58:61], v172, v172 op_sel_hi:[0,0,0]
	s_nop 1
	v_mfma_scale_f32_16x16x128_f8f6f4 v[46:49], v[208:215], v[200:207], v[46:49], v172, v172 op_sel_hi:[0,0,0]
	s_nop 1
	v_mfma_scale_f32_16x16x128_f8f6f4 v[42:45], v[18:25], v[200:207], v[42:45], v172, v172 op_sel_hi:[0,0,0]
	s_nop 1
	v_mfma_scale_f32_16x16x128_f8f6f4 v[30:33], v[208:215], v[236:243], v[30:33], v172, v172 op_sel_hi:[0,0,0]
	s_nop 1
	v_mfma_scale_f32_16x16x128_f8f6f4 v[26:29], v[18:25], v[236:243], v[26:29], v172, v172 op_sel_hi:[0,0,0]
	s_add_i32 s86, 0, 0x18000
	v_add_u32_e32 v14, s86, v174
	s_barrier
	ds_read_b128 v[2:5], v14
	ds_read_b128 v[6:9], v14 offset:1024
	ds_read_b128 v[10:13], v14 offset:2048
	ds_read_b128 v[14:17], v14 offset:3072
	s_add_u32 s30, s68, 0x40000
	s_addc_u32 s31, s69, 0
	s_mov_b32 m0, s54
	v_lshl_add_u64 v[208:209], s[30:31], 0, v[158:159]
	ds_read_b128 v[18:21], v182 offset:32768
	ds_read_b128 v[22:25], v182 offset:33792
	ds_read_b128 v[184:187], v182 offset:34816
	ds_read_b128 v[188:191], v182 offset:35840
	ds_read_b128 v[192:195], v182 offset:36864
	ds_read_b128 v[196:199], v182 offset:37888
	ds_read_b128 v[200:203], v182 offset:38912
	ds_read_b128 v[204:207], v182 offset:39936
	global_load_lds_dwordx4 v[208:209], off
	v_lshl_add_u64 v[208:209], s[30:31], 0, v[156:157]
	s_mov_b32 m0, s70
	s_nop 0
	global_load_lds_dwordx4 v[208:209], off
	s_waitcnt lgkmcnt(8)
	s_barrier
	s_waitcnt lgkmcnt(0)
	s_nop 1
	v_mfma_scale_f32_16x16x128_f8f6f4 v[150:153], v[2:9], v[18:25], v[150:153], v172, v172 op_sel_hi:[0,0,0]
	s_nop 1
	v_mfma_scale_f32_16x16x128_f8f6f4 v[146:149], v[10:17], v[18:25], v[146:149], v172, v172 op_sel_hi:[0,0,0]
	s_nop 1
	v_mfma_scale_f32_16x16x128_f8f6f4 v[134:137], v[2:9], v[184:191], v[134:137], v172, v172 op_sel_hi:[0,0,0]
	s_nop 1
	v_mfma_scale_f32_16x16x128_f8f6f4 v[130:133], v[10:17], v[184:191], v[130:133], v172, v172 op_sel_hi:[0,0,0]
	s_nop 1
	v_mfma_scale_f32_16x16x128_f8f6f4 v[118:121], v[2:9], v[192:199], v[118:121], v172, v172 op_sel_hi:[0,0,0]
	s_nop 1
	v_mfma_scale_f32_16x16x128_f8f6f4 v[114:117], v[10:17], v[192:199], v[114:117], v172, v172 op_sel_hi:[0,0,0]
	s_nop 1
	v_mfma_scale_f32_16x16x128_f8f6f4 v[102:105], v[2:9], v[200:207], v[102:105], v172, v172 op_sel_hi:[0,0,0]
	s_nop 1
	v_mfma_scale_f32_16x16x128_f8f6f4 v[98:101], v[10:17], v[200:207], v[98:101], v172, v172 op_sel_hi:[0,0,0]
	s_barrier
	s_add_i32 s30, 0, 0x1c000
	s_add_i32 s31, s86, s25
	v_add_u32_e32 v183, s30, v174
	v_lshl_add_u64 v[164:165], v[164:165], 0, s[56:57]
	s_mov_b32 m0, s31
	ds_read_b128 v[208:211], v183
	ds_read_b128 v[212:215], v183 offset:1024
	ds_read_b128 v[236:239], v183 offset:2048
	ds_read_b128 v[240:243], v183 offset:3072
	global_load_lds_dwordx4 v[164:165], off
	v_lshl_add_u64 v[164:165], v[166:167], 0, s[56:57]
	s_add_i32 m0, s31, 0x2000
	s_nop 0
	global_load_lds_dwordx4 v[164:165], off
	s_barrier
	s_waitcnt lgkmcnt(0)
	s_nop 1
	v_mfma_scale_f32_16x16x128_f8f6f4 v[142:145], v[208:215], v[18:25], v[142:145], v172, v172 op_sel_hi:[0,0,0]
	s_nop 1
	v_mfma_scale_f32_16x16x128_f8f6f4 v[138:141], v[236:243], v[18:25], v[138:141], v172, v172 op_sel_hi:[0,0,0]
	s_nop 1
	v_mfma_scale_f32_16x16x128_f8f6f4 v[126:129], v[208:215], v[184:191], v[126:129], v172, v172 op_sel_hi:[0,0,0]
	s_nop 1
	v_mfma_scale_f32_16x16x128_f8f6f4 v[122:125], v[236:243], v[184:191], v[122:125], v172, v172 op_sel_hi:[0,0,0]
	s_nop 1
	v_mfma_scale_f32_16x16x128_f8f6f4 v[110:113], v[208:215], v[192:199], v[110:113], v172, v172 op_sel_hi:[0,0,0]
	s_nop 1
	v_mfma_scale_f32_16x16x128_f8f6f4 v[106:109], v[236:243], v[192:199], v[106:109], v172, v172 op_sel_hi:[0,0,0]
	s_nop 1
	v_mfma_scale_f32_16x16x128_f8f6f4 v[94:97], v[208:215], v[200:207], v[94:97], v172, v172 op_sel_hi:[0,0,0]
	s_nop 1
	v_mfma_scale_f32_16x16x128_f8f6f4 v[90:93], v[236:243], v[200:207], v[90:93], v172, v172 op_sel_hi:[0,0,0]
	s_mov_b32 m0, s71
	v_lshl_add_u64 v[164:165], v[168:169], 0, s[56:57]
	s_barrier
; #define PG8_STAGE(bufoff, gbase, voff) do { _Pragma("unroll") for (int _i = 0; _i < 2; ++_i) \
;         __builtin_amdgcn_global_load_lds((const unsigned*)((const char*)(gbase) + (voff)[_i]), (PG8_LAS unsigned*)(lds + (bufoff) + ldsw + _i * 8192), 16, 0, 0); } while (0)
; #define PG8_LDA(dst, b, h) do { _Pragma("unroll") for (int m = 0; m < 4; ++m) _Pragma("unroll") for (int k = 0; k < 2; ++k) dst[m][k] = *(const PG8_LAS bf16x8*)(lds + PG8_SA(b, h) + aoff + m * 2048 + k * 1024); } while (0)
; #define PG8_WAIT_V(n) asm volatile("s_waitcnt vmcnt(" #n ")" ::: "memory")
; #define PG8_WAIT_L(n) asm volatile("s_waitcnt lgkmcnt(" #n ")" ::: "memory")
; template <bool FP8, class Epi, class Sched>
; __device__ __forceinline__ void gemm_phase(PG8_LAS unsigned char* lds, const Gemm g, const Sched& S, const Epi& E) {
;     ...
;             PG8_LDA(At, 1, 1); PG8_STAGE(PG8_SA(1, 0), a3, voffA);
;             PG8_BAR; PG8_WAIT_L(0); PG8_MMA(1, 0, At, B0); PG8_BAR; PG8_SCHED;
;             PG8_STAGE(PG8_SB(1, 1), b3 + hstep, voffB);
;             PG8_WAIT_V(6); PG8_BAR; PG8_MMA(1, 1, At, B1); PG8_BAR;
;         }
;         if constexpr (FP8) asm volatile("s_nop 15\n\ts_nop 15" ::: "memory");
;   DI void operator()(const f32x4 (&acc)[2][2][4][2], const pg8::Unit& u, int wr, int wc, int fr, int fq) const {
;     ...
;           if (MODE == 0) { if (col < N) dst = d0 + (size_t)row * ld0 + (col + coff2 + ((col < csplit) ? (coff1 - coff2) : 0)); }
;           else if (MODE == 1) {
;             const int oc = col + coff2 + ((col < csplit) ? (coff1 - coff2) : 0);
;             if (col < N) {
;               if (oc < 2048) dst = d0 + (size_t)row * 2048 + oc;
;               else if (oc < 2112) { rot(v0, v1, row, oc); dst = d2 + (size_t)row * 64 + (oc - 2048); }
;               else dst = d1 + (size_t)row * 4096 + (oc - 2112);
;             }
;           } else if (MODE == 3) {
;             if (col < N) { const bool lo = col < csplit; u16* bp = lo ? d0 : d1; const int ldd = lo ? 2048 : 4096, oc = lo ? col : col + (coff2 - 2112); dst = bp + (size_t)row * ldd + oc + (lo ? coff1 : 0); }
;           } else {
;             if (((col >> 6) % 3) == 2) rot(v0, v1, row, col);
;             dst = d0 + (size_t)row * 3072 + col;
;           }
;           if (dst) { u32x4 w = {pk2(v0[0], v0[1]), pk2(v0[2], v0[3]), pk2(v1[0], v1[1]), pk2(v1[2], v1[3])}; *(u32x4*)dst = w; }
	ds_read_b128 v[18:21], v182 offset:49152
	ds_read_b128 v[22:25], v182 offset:50176
	ds_read_b128 v[184:187], v182 offset:51200
	ds_read_b128 v[188:191], v182 offset:52224
	ds_read_b128 v[192:195], v182 offset:53248
	ds_read_b128 v[196:199], v182 offset:54272
	ds_read_b128 v[200:203], v182 offset:55296
	ds_read_b128 v[204:207], v182 offset:56320
	global_load_lds_dwordx4 v[164:165], off
	v_lshl_add_u64 v[164:165], v[170:171], 0, s[56:57]
	s_mov_b32 m0, s72
	s_nop 0
	global_load_lds_dwordx4 v[164:165], off
	s_barrier
	s_waitcnt lgkmcnt(0)
	s_nop 1
	v_mfma_scale_f32_16x16x128_f8f6f4 v[86:89], v[2:9], v[18:25], v[86:89], v172, v172 op_sel_hi:[0,0,0]
	s_nop 1
	v_mfma_scale_f32_16x16x128_f8f6f4 v[82:85], v[10:17], v[18:25], v[82:85], v172, v172 op_sel_hi:[0,0,0]
	s_nop 1
	v_mfma_scale_f32_16x16x128_f8f6f4 v[70:73], v[2:9], v[184:191], v[70:73], v172, v172 op_sel_hi:[0,0,0]
	s_nop 1
	v_mfma_scale_f32_16x16x128_f8f6f4 v[66:69], v[10:17], v[184:191], v[66:69], v172, v172 op_sel_hi:[0,0,0]
	s_nop 1
	v_mfma_scale_f32_16x16x128_f8f6f4 v[54:57], v[2:9], v[192:199], v[54:57], v172, v172 op_sel_hi:[0,0,0]
	s_nop 1
	v_mfma_scale_f32_16x16x128_f8f6f4 v[50:53], v[10:17], v[192:199], v[50:53], v172, v172 op_sel_hi:[0,0,0]
	s_nop 1
	v_mfma_scale_f32_16x16x128_f8f6f4 v[38:41], v[2:9], v[200:207], v[38:41], v172, v172 op_sel_hi:[0,0,0]
	s_nop 1
	v_mfma_scale_f32_16x16x128_f8f6f4 v[34:37], v[10:17], v[200:207], v[34:37], v172, v172 op_sel_hi:[0,0,0]
	s_barrier
	s_add_u32 s10, s10, 0x40080
	s_addc_u32 s11, s11, 0
	s_add_i32 s30, s30, s25
	v_lshl_add_u64 v[2:3], s[10:11], 0, v[0:1]
	s_mov_b32 m0, s30
	s_nop 0
	global_load_lds_dwordx4 v[2:3], off
	v_lshl_add_u64 v[2:3], s[10:11], 0, v[154:155]
	s_add_i32 m0, s30, 0x2000
	s_nop 0
	global_load_lds_dwordx4 v[2:3], off
	s_waitcnt vmcnt(6)
	s_barrier
	s_nop 1
	v_mfma_scale_f32_16x16x128_f8f6f4 v[78:81], v[208:215], v[18:25], v[78:81], v172, v172 op_sel_hi:[0,0,0]
	s_nop 1
	v_mfma_scale_f32_16x16x128_f8f6f4 v[74:77], v[236:243], v[18:25], v[74:77], v172, v172 op_sel_hi:[0,0,0]
	s_nop 1
	v_mfma_scale_f32_16x16x128_f8f6f4 v[62:65], v[208:215], v[184:191], v[62:65], v172, v172 op_sel_hi:[0,0,0]
	s_nop 1
	v_mfma_scale_f32_16x16x128_f8f6f4 v[58:61], v[236:243], v[184:191], v[58:61], v172, v172 op_sel_hi:[0,0,0]
	s_nop 1
	v_mfma_scale_f32_16x16x128_f8f6f4 v[46:49], v[208:215], v[192:199], v[46:49], v172, v172 op_sel_hi:[0,0,0]
	s_nop 1
	v_mfma_scale_f32_16x16x128_f8f6f4 v[42:45], v[236:243], v[192:199], v[42:45], v172, v172 op_sel_hi:[0,0,0]
	s_nop 1
	v_mfma_scale_f32_16x16x128_f8f6f4 v[30:33], v[208:215], v[200:207], v[30:33], v172, v172 op_sel_hi:[0,0,0]
	s_nop 1
	v_mfma_scale_f32_16x16x128_f8f6f4 v[26:29], v[236:243], v[200:207], v[26:29], v172, v172 op_sel_hi:[0,0,0]
	s_add_i32 vcc_hi, vcc_hi, 2
	s_add_u32 s0, s0, 0x100
	s_addc_u32 s1, s1, 0
	s_add_u32 s95, s95, 0x100
	s_addc_u32 vcc_lo, vcc_lo, 0
	s_cmp_gt_u32 vcc_hi, 13
	s_barrier
	s_cbranch_scc0 .LBB0_672
	s_nop 15
	s_nop 15
	v_lshl_add_u32 v4, s29, 8, v173
	v_lshl_or_b32 v2, s28, 8, v175
	s_movk_i32 s0, 0xa00
	v_ashrrev_i32_e32 v5, 31, v4
	v_cmp_gt_i32_e32 vcc, s0, v2
	v_mov_b64_e32 v[6:7], 0
	s_and_saveexec_b64 s[10:11], vcc
	s_movk_i32 s20, 0x600
	s_cbranch_execz .LBB0_675
	v_mov_b32_e32 v3, s5
	v_mov_b32_e32 v6, s83
	v_cmp_gt_i32_e64 s[0:1], s20, v2
	s_nop 1
	v_cndmask_b32_e64 v7, v3, v6, s[0:1]
	v_mov_b32_e32 v3, s4
	v_mov_b32_e32 v6, s82
	v_cndmask_b32_e64 v6, v3, v6, s[0:1]
	v_cndmask_b32_e64 v3, v230, 0, s[0:1]
	v_add_u32_e32 v8, v3, v2
	v_cndmask_b32_e64 v3, 12, 11, s[0:1]
	v_lshlrev_b64 v[10:11], v3, v[4:5]
	v_lshl_add_u64 v[6:7], v[10:11], 1, v[6:7]
	v_ashrrev_i32_e32 v9, 31, v8
	v_lshl_add_u64 v[6:7], v[8:9], 1, v[6:7]

; #define PG8_STAGE(bufoff, gbase, voff) do { _Pragma("unroll") for (int _i = 0; _i < 2; ++_i) \
;         __builtin_amdgcn_global_load_lds((const unsigned*)((const char*)(gbase) + (voff)[_i]), (PG8_LAS unsigned*)(lds + (bufoff) + ldsw + _i * 8192), 16, 0, 0); } while (0)
; #define PG8_LDA(dst, b, h) do { _Pragma("unroll") for (int m = 0; m < 4; ++m) _Pragma("unroll") for (int k = 0; k < 2; ++k) dst[m][k] = *(const PG8_LAS bf16x8*)(lds + PG8_SA(b, h) + aoff + m * 2048 + k * 1024); } while (0)
; #define PG8_LDB(dst, b, h) do { _Pragma("unroll") for (int n = 0; n < 2; ++n) _Pragma("unroll") for (int k = 0; k < 2; ++k) dst[n][k] = *(const PG8_LAS bf16x8*)(lds + PG8_SB(b, h) + boff + n * 2048 + k * 1024); } while (0)
; #define PG8_WAIT_V(n) asm volatile("s_waitcnt vmcnt(" #n ")" ::: "memory")
; #define PG8_WAIT_L(n) asm volatile("s_waitcnt lgkmcnt(" #n ")" ::: "memory")
; #define PG8_BAR __builtin_amdgcn_s_barrier()
; #define PG8_SCHED __builtin_amdgcn_sched_barrier(0)
; template <bool FP8, class Epi, class Sched>
; __device__ __forceinline__ void gemm_phase(PG8_LAS unsigned char* lds, const Gemm g, const Sched& S, const Epi& E) {
;     ...
;             PG8_LDB(B0, 0, 0); PG8_SCHED; PG8_LDA(At, 0, 0); PG8_STAGE(PG8_SA(1, 1), a1 + hstepA, voffA);
;             PG8_WAIT_L(8); PG8_BAR; PG8_WAIT_L(0); PG8_MMA(0, 0, At, B0); PG8_BAR; PG8_SCHED;
;             PG8_LDB(B1, 0, 1); PG8_STAGE(PG8_SB(0, 0), b2, voffB);
;             PG8_BAR; PG8_WAIT_L(0); PG8_MMA(0, 1, At, B1); PG8_BAR;
;             PG8_LDA(At, 0, 1); PG8_STAGE(PG8_SA(0, 0), a2, voffA);
;             PG8_BAR; PG8_WAIT_L(0); PG8_MMA(1, 0, At, B0); PG8_BAR; PG8_SCHED;
;             PG8_STAGE(PG8_SB(0, 1), b2 + hstep, voffB);
;             PG8_WAIT_V(6); PG8_BAR; PG8_MMA(1, 1, At, B1); PG8_BAR;
;             PG8_LDB(B0, 1, 0); PG8_SCHED; PG8_LDA(At, 1, 0); PG8_STAGE(PG8_SA(0, 1), a2 + hstepA, voffA);
;             PG8_WAIT_L(8); PG8_BAR; PG8_WAIT_L(0); PG8_MMA(0, 0, At, B0); PG8_BAR; PG8_SCHED;
.LBB0_753:
	s_add_u32 s18, s0, 0xfff80080
	s_addc_u32 s19, s1, -1
	s_add_i32 s30, 0, 0x10000
	v_add_u32_e32 v144, s30, v147
	ds_read_b128 v[140:143], v144
	ds_read_b128 v[150:153], v144 offset:1024
	ds_read_b128 v[154:157], v144 offset:2048
	ds_read_b128 v[158:161], v144 offset:3072
	s_cmp_eq_u32 s87, 28
	s_cselect_b32 s67, s13, s19
	s_cselect_b32 s66, s70, s18
	s_cselect_b32 s19, s11, s73
	s_cselect_b32 s18, s71, s72
	v_lshl_add_u64 v[144:145], s[0:1], 0, v[136:137]
	s_add_i32 m0, s24, 0xc000
	ds_read_b128 v[162:165], v149
	ds_read_b128 v[166:169], v149 offset:1024
	ds_read_b128 v[170:173], v149 offset:2048
	ds_read_b128 v[182:185], v149 offset:3072
	ds_read_b128 v[186:189], v149 offset:4096
	ds_read_b128 v[190:193], v149 offset:5120
	ds_read_b128 v[194:197], v149 offset:6144
	ds_read_b128 v[198:201], v149 offset:7168
	global_load_lds_dwordx4 v[144:145], off
	v_lshl_add_u64 v[144:145], s[0:1], 0, v[138:139]
	s_add_i32 m0, s24, 0xe000
	s_nop 0
	global_load_lds_dwordx4 v[144:145], off
	s_waitcnt lgkmcnt(8)
	s_barrier
	s_waitcnt lgkmcnt(0)
	v_mfma_f32_16x16x32_bf16 v[126:129], v[140:143], v[162:165], v[126:129]
	v_mfma_f32_16x16x32_bf16 v[122:125], v[154:157], v[162:165], v[122:125]
	v_mfma_f32_16x16x32_bf16 v[114:117], v[140:143], v[170:173], v[114:117]
	v_mfma_f32_16x16x32_bf16 v[106:109], v[154:157], v[170:173], v[106:109]
	v_mfma_f32_16x16x32_bf16 v[98:101], v[140:143], v[186:189], v[98:101]
	v_mfma_f32_16x16x32_bf16 v[90:93], v[154:157], v[186:189], v[90:93]
	v_mfma_f32_16x16x32_bf16 v[82:85], v[140:143], v[194:197], v[82:85]
	v_mfma_f32_16x16x32_bf16 v[74:77], v[154:157], v[194:197], v[74:77]
	v_mfma_f32_16x16x32_bf16 v[126:129], v[150:153], v[166:169], v[126:129]
	v_mfma_f32_16x16x32_bf16 v[122:125], v[158:161], v[166:169], v[122:125]
	v_mfma_f32_16x16x32_bf16 v[114:117], v[150:153], v[182:185], v[114:117]
	v_mfma_f32_16x16x32_bf16 v[106:109], v[158:161], v[182:185], v[106:109]
	v_mfma_f32_16x16x32_bf16 v[98:101], v[150:153], v[190:193], v[98:101]
	v_mfma_f32_16x16x32_bf16 v[90:93], v[158:161], v[190:193], v[90:93]
	v_mfma_f32_16x16x32_bf16 v[82:85], v[150:153], v[198:201], v[82:85]
	v_mfma_f32_16x16x32_bf16 v[74:77], v[158:161], v[198:201], v[74:77]
	s_barrier
	s_add_i32 s86, 0, 0x14000
	v_add_u32_e32 v144, s86, v147
	s_add_i32 s30, s30, s23
	ds_read_b128 v[202:205], v144
	ds_read_b128 v[206:209], v144 offset:1024
	ds_read_b128 v[210:213], v144 offset:2048
	ds_read_b128 v[214:217], v144 offset:3072
	v_lshl_add_u64 v[144:145], s[18:19], 0, v[0:1]
	s_mov_b32 m0, s30
	v_lshl_add_u64 v[174:175], s[18:19], 0, v[130:131]
	global_load_lds_dwordx4 v[144:145], off
	s_add_i32 m0, s30, 0x2000
	s_nop 0
	global_load_lds_dwordx4 v[174:175], off
	s_barrier
	s_waitcnt lgkmcnt(0)
	v_mfma_f32_16x16x32_bf16 v[118:121], v[202:205], v[162:165], v[118:121]
	v_mfma_f32_16x16x32_bf16 v[110:113], v[210:213], v[162:165], v[110:113]
	v_mfma_f32_16x16x32_bf16 v[102:105], v[202:205], v[170:173], v[102:105]
	v_mfma_f32_16x16x32_bf16 v[94:97], v[210:213], v[170:173], v[94:97]
	v_mfma_f32_16x16x32_bf16 v[86:89], v[202:205], v[186:189], v[86:89]
	v_mfma_f32_16x16x32_bf16 v[78:81], v[210:213], v[186:189], v[78:81]
	v_mfma_f32_16x16x32_bf16 v[70:73], v[202:205], v[194:197], v[70:73]
	v_mfma_f32_16x16x32_bf16 v[66:69], v[210:213], v[194:197], v[66:69]
	v_mfma_f32_16x16x32_bf16 v[118:121], v[206:209], v[166:169], v[118:121]
	v_mfma_f32_16x16x32_bf16 v[110:113], v[214:217], v[166:169], v[110:113]
	v_mfma_f32_16x16x32_bf16 v[102:105], v[206:209], v[182:185], v[102:105]
	v_mfma_f32_16x16x32_bf16 v[94:97], v[214:217], v[182:185], v[94:97]
	v_mfma_f32_16x16x32_bf16 v[86:89], v[206:209], v[190:193], v[86:89]
	v_mfma_f32_16x16x32_bf16 v[78:81], v[214:217], v[190:193], v[78:81]
	v_mfma_f32_16x16x32_bf16 v[70:73], v[206:209], v[198:201], v[70:73]
	v_mfma_f32_16x16x32_bf16 v[66:69], v[214:217], v[198:201], v[66:69]
	s_mov_b32 m0, s24
	v_lshl_add_u64 v[236:237], s[66:67], 0, v[134:135]
	s_barrier
	ds_read_b128 v[162:165], v149 offset:16384
	ds_read_b128 v[166:169], v149 offset:17408
	ds_read_b128 v[170:173], v149 offset:18432
	ds_read_b128 v[182:185], v149 offset:19456
	ds_read_b128 v[186:189], v149 offset:20480
	ds_read_b128 v[190:193], v149 offset:21504
	ds_read_b128 v[194:197], v149 offset:22528
	ds_read_b128 v[198:201], v149 offset:23552
	global_load_lds_dwordx4 v[236:237], off
	v_lshl_add_u64 v[238:239], s[66:67], 0, v[132:133]
	s_mov_b32 m0, s25
	s_nop 0
	global_load_lds_dwordx4 v[238:239], off
	s_barrier
	s_waitcnt lgkmcnt(0)
	v_mfma_f32_16x16x32_bf16 v[62:65], v[140:143], v[162:165], v[62:65]
	v_mfma_f32_16x16x32_bf16 v[58:61], v[154:157], v[162:165], v[58:61]
	v_mfma_f32_16x16x32_bf16 v[50:53], v[140:143], v[170:173], v[50:53]
	v_mfma_f32_16x16x32_bf16 v[42:45], v[154:157], v[170:173], v[42:45]
	v_mfma_f32_16x16x32_bf16 v[34:37], v[140:143], v[186:189], v[34:37]
	v_mfma_f32_16x16x32_bf16 v[26:29], v[154:157], v[186:189], v[26:29]
	v_mfma_f32_16x16x32_bf16 v[18:21], v[140:143], v[194:197], v[18:21]
	v_mfma_f32_16x16x32_bf16 v[10:13], v[154:157], v[194:197], v[10:13]
	v_mfma_f32_16x16x32_bf16 v[62:65], v[150:153], v[166:169], v[62:65]
	v_mfma_f32_16x16x32_bf16 v[58:61], v[158:161], v[166:169], v[58:61]
	v_mfma_f32_16x16x32_bf16 v[50:53], v[150:153], v[182:185], v[50:53]
	v_mfma_f32_16x16x32_bf16 v[42:45], v[158:161], v[182:185], v[42:45]
	v_mfma_f32_16x16x32_bf16 v[34:37], v[150:153], v[190:193], v[34:37]
	v_mfma_f32_16x16x32_bf16 v[26:29], v[158:161], v[190:193], v[26:29]
	v_mfma_f32_16x16x32_bf16 v[18:21], v[150:153], v[198:201], v[18:21]
	v_mfma_f32_16x16x32_bf16 v[10:13], v[158:161], v[198:201], v[10:13]
	s_barrier
; #define PG8_STAGE(bufoff, gbase, voff) do { _Pragma("unroll") for (int _i = 0; _i < 2; ++_i) \
;         __builtin_amdgcn_global_load_lds((const unsigned*)((const char*)(gbase) + (voff)[_i]), (PG8_LAS unsigned*)(lds + (bufoff) + ldsw + _i * 8192), 16, 0, 0); } while (0)
; #define PG8_LDA(dst, b, h) do { _Pragma("unroll") for (int m = 0; m < 4; ++m) _Pragma("unroll") for (int k = 0; k < 2; ++k) dst[m][k] = *(const PG8_LAS bf16x8*)(lds + PG8_SA(b, h) + aoff + m * 2048 + k * 1024); } while (0)
; #define PG8_LDB(dst, b, h) do { _Pragma("unroll") for (int n = 0; n < 2; ++n) _Pragma("unroll") for (int k = 0; k < 2; ++k) dst[n][k] = *(const PG8_LAS bf16x8*)(lds + PG8_SB(b, h) + boff + n * 2048 + k * 1024); } while (0)
; #define PG8_WAIT_V(n) asm volatile("s_waitcnt vmcnt(" #n ")" ::: "memory")
; #define PG8_WAIT_L(n) asm volatile("s_waitcnt lgkmcnt(" #n ")" ::: "memory")
; #define PG8_BAR __builtin_amdgcn_s_barrier()
; #define PG8_SCHED __builtin_amdgcn_sched_barrier(0)
; template <bool FP8, class Epi, class Sched>
; __device__ __forceinline__ void gemm_phase(PG8_LAS unsigned char* lds, const Gemm g, const Sched& S, const Epi& E) {
;     ...
;             PG8_STAGE(PG8_SB(0, 1), b2 + hstep, voffB);
;             PG8_WAIT_V(6); PG8_BAR; PG8_MMA(1, 1, At, B1); PG8_BAR;
;             PG8_LDB(B0, 1, 0); PG8_SCHED; PG8_LDA(At, 1, 0); PG8_STAGE(PG8_SA(0, 1), a2 + hstepA, voffA);
;             PG8_WAIT_L(8); PG8_BAR; PG8_WAIT_L(0); PG8_MMA(0, 0, At, B0); PG8_BAR; PG8_SCHED;
;             PG8_LDB(B1, 1, 1); PG8_STAGE(PG8_SB(1, 0), b3, voffB);
	s_add_u32 s30, s18, 0x80000
	s_addc_u32 s31, s19, 0
	s_add_i32 s86, s86, s23
	v_lshl_add_u64 v[140:141], s[30:31], 0, v[0:1]
	s_mov_b32 m0, s86
	s_nop 0
	global_load_lds_dwordx4 v[140:141], off
	v_lshl_add_u64 v[140:141], s[30:31], 0, v[130:131]
	s_add_i32 m0, s86, 0x2000
	s_nop 0
	global_load_lds_dwordx4 v[140:141], off
	s_waitcnt vmcnt(6)
	s_barrier
	v_mfma_f32_16x16x32_bf16 v[54:57], v[202:205], v[162:165], v[54:57]
	v_mfma_f32_16x16x32_bf16 v[46:49], v[210:213], v[162:165], v[46:49]
	v_mfma_f32_16x16x32_bf16 v[38:41], v[202:205], v[170:173], v[38:41]
	v_mfma_f32_16x16x32_bf16 v[30:33], v[210:213], v[170:173], v[30:33]
	v_mfma_f32_16x16x32_bf16 v[22:25], v[202:205], v[186:189], v[22:25]
	v_mfma_f32_16x16x32_bf16 v[14:17], v[210:213], v[186:189], v[14:17]
	v_mfma_f32_16x16x32_bf16 v[6:9], v[202:205], v[194:197], v[6:9]
	v_mfma_f32_16x16x32_bf16 v[2:5], v[210:213], v[194:197], v[2:5]
	v_mfma_f32_16x16x32_bf16 v[54:57], v[206:209], v[166:169], v[54:57]
	v_mfma_f32_16x16x32_bf16 v[46:49], v[214:217], v[166:169], v[46:49]
	v_mfma_f32_16x16x32_bf16 v[38:41], v[206:209], v[182:185], v[38:41]
	v_mfma_f32_16x16x32_bf16 v[30:33], v[214:217], v[182:185], v[30:33]
	v_mfma_f32_16x16x32_bf16 v[22:25], v[206:209], v[190:193], v[22:25]
	v_mfma_f32_16x16x32_bf16 v[14:17], v[214:217], v[190:193], v[14:17]
	v_mfma_f32_16x16x32_bf16 v[6:9], v[206:209], v[198:201], v[6:9]
	v_mfma_f32_16x16x32_bf16 v[2:5], v[214:217], v[198:201], v[2:5]
	s_add_i32 s86, 0, 0x18000
	v_add_u32_e32 v158, s86, v147
	s_barrier
	ds_read_b128 v[140:143], v158
	ds_read_b128 v[150:153], v158 offset:1024
	ds_read_b128 v[154:157], v158 offset:2048
	ds_read_b128 v[158:161], v158 offset:3072
	s_add_u32 s30, s66, 0x80000
	s_addc_u32 s31, s67, 0
	s_mov_b32 m0, s26
	v_lshl_add_u64 v[202:203], s[30:31], 0, v[134:135]
	ds_read_b128 v[162:165], v149 offset:32768
	ds_read_b128 v[166:169], v149 offset:33792
	ds_read_b128 v[170:173], v149 offset:34816
	ds_read_b128 v[182:185], v149 offset:35840
	ds_read_b128 v[186:189], v149 offset:36864
	ds_read_b128 v[190:193], v149 offset:37888
	ds_read_b128 v[194:197], v149 offset:38912
	ds_read_b128 v[198:201], v149 offset:39936
	global_load_lds_dwordx4 v[202:203], off
	v_lshl_add_u64 v[202:203], s[30:31], 0, v[132:133]
	s_mov_b32 m0, s27
	s_nop 0
	global_load_lds_dwordx4 v[202:203], off
	s_waitcnt lgkmcnt(8)
	s_barrier
	s_waitcnt lgkmcnt(0)
	v_mfma_f32_16x16x32_bf16 v[126:129], v[140:143], v[162:165], v[126:129]
	v_mfma_f32_16x16x32_bf16 v[122:125], v[154:157], v[162:165], v[122:125]
	v_mfma_f32_16x16x32_bf16 v[114:117], v[140:143], v[170:173], v[114:117]
	v_mfma_f32_16x16x32_bf16 v[106:109], v[154:157], v[170:173], v[106:109]
	v_mfma_f32_16x16x32_bf16 v[98:101], v[140:143], v[186:189], v[98:101]
	v_mfma_f32_16x16x32_bf16 v[90:93], v[154:157], v[186:189], v[90:93]
	v_mfma_f32_16x16x32_bf16 v[82:85], v[140:143], v[194:197], v[82:85]
	v_mfma_f32_16x16x32_bf16 v[74:77], v[154:157], v[194:197], v[74:77]
	v_mfma_f32_16x16x32_bf16 v[126:129], v[150:153], v[166:169], v[126:129]
	v_mfma_f32_16x16x32_bf16 v[122:125], v[158:161], v[166:169], v[122:125]
	v_mfma_f32_16x16x32_bf16 v[114:117], v[150:153], v[182:185], v[114:117]
	v_mfma_f32_16x16x32_bf16 v[106:109], v[158:161], v[182:185], v[106:109]
	v_mfma_f32_16x16x32_bf16 v[98:101], v[150:153], v[190:193], v[98:101]
	v_mfma_f32_16x16x32_bf16 v[90:93], v[158:161], v[190:193], v[90:93]
	v_mfma_f32_16x16x32_bf16 v[82:85], v[150:153], v[198:201], v[82:85]
	v_mfma_f32_16x16x32_bf16 v[74:77], v[158:161], v[198:201], v[74:77]
	s_barrier
	s_add_i32 s30, 0, 0x1c000
	s_add_i32 s31, s86, s23
	v_add_u32_e32 v214, s30, v147
	v_lshl_add_u64 v[144:145], v[144:145], 0, s[56:57]
	s_mov_b32 m0, s31
	ds_read_b128 v[202:205], v214
	ds_read_b128 v[206:209], v214 offset:1024
	ds_read_b128 v[210:213], v214 offset:2048
	ds_read_b128 v[214:217], v214 offset:3072
	global_load_lds_dwordx4 v[144:145], off
	v_lshl_add_u64 v[144:145], v[174:175], 0, s[56:57]
	s_add_i32 m0, s31, 0x2000
	s_nop 0
	global_load_lds_dwordx4 v[144:145], off
	s_barrier
; #define PG8_STAGE(bufoff, gbase, voff) do { _Pragma("unroll") for (int _i = 0; _i < 2; ++_i) \
;         __builtin_amdgcn_global_load_lds((const unsigned*)((const char*)(gbase) + (voff)[_i]), (PG8_LAS unsigned*)(lds + (bufoff) + ldsw + _i * 8192), 16, 0, 0); } while (0)
; #define PG8_LDA(dst, b, h) do { _Pragma("unroll") for (int m = 0; m < 4; ++m) _Pragma("unroll") for (int k = 0; k < 2; ++k) dst[m][k] = *(const PG8_LAS bf16x8*)(lds + PG8_SA(b, h) + aoff + m * 2048 + k * 1024); } while (0)
; #define PG8_WAIT_V(n) asm volatile("s_waitcnt vmcnt(" #n ")" ::: "memory")
; #define PG8_WAIT_L(n) asm volatile("s_waitcnt lgkmcnt(" #n ")" ::: "memory")
; #define PG8_BAR __builtin_amdgcn_s_barrier()
; #define PG8_SCHED __builtin_amdgcn_sched_barrier(0)
; template <bool FP8, class Epi, class Sched>
; __device__ __forceinline__ void gemm_phase(PG8_LAS unsigned char* lds, const Gemm g, const Sched& S, const Epi& E) {
;     ...
;             PG8_BAR; PG8_WAIT_L(0); PG8_MMA(0, 1, At, B1); PG8_BAR;
;             PG8_LDA(At, 1, 1); PG8_STAGE(PG8_SA(1, 0), a3, voffA);
;             PG8_BAR; PG8_WAIT_L(0); PG8_MMA(1, 0, At, B0); PG8_BAR; PG8_SCHED;
;             PG8_STAGE(PG8_SB(1, 1), b3 + hstep, voffB);
;             PG8_WAIT_V(6); PG8_BAR; PG8_MMA(1, 1, At, B1); PG8_BAR;
;         }
;         if constexpr (FP8) asm volatile("s_nop 15\n\ts_nop 15" ::: "memory");
;         if constexpr (!Epi::AFTER_DRAIN) { E(acc, cur, wr, wc, fr, fq); S.done(cur); }
;   DI void operator()(const f32x4 (&acc)[2][2][4][2], const pg8::Unit& u, int wr, int wc, int fr, int fq) const {
;     ...
;           if (MODE == 0) { if (col < N) dst = d0 + (size_t)row * ld0 + (col + coff2 + ((col < csplit) ? (coff1 - coff2) : 0)); }
;     ...
;           if (dst) { u32x4 w = {pk2(v0[0], v0[1]), pk2(v0[2], v0[3]), pk2(v1[0], v1[1]), pk2(v1[2], v1[3])}; *(u32x4*)dst = w; }
	s_waitcnt lgkmcnt(0)
	v_mfma_f32_16x16x32_bf16 v[118:121], v[202:205], v[162:165], v[118:121]
	v_mfma_f32_16x16x32_bf16 v[110:113], v[210:213], v[162:165], v[110:113]
	v_mfma_f32_16x16x32_bf16 v[102:105], v[202:205], v[170:173], v[102:105]
	v_mfma_f32_16x16x32_bf16 v[94:97], v[210:213], v[170:173], v[94:97]
	v_mfma_f32_16x16x32_bf16 v[86:89], v[202:205], v[186:189], v[86:89]
	v_mfma_f32_16x16x32_bf16 v[78:81], v[210:213], v[186:189], v[78:81]
	v_mfma_f32_16x16x32_bf16 v[70:73], v[202:205], v[194:197], v[70:73]
	v_mfma_f32_16x16x32_bf16 v[66:69], v[210:213], v[194:197], v[66:69]
	v_mfma_f32_16x16x32_bf16 v[118:121], v[206:209], v[166:169], v[118:121]
	v_mfma_f32_16x16x32_bf16 v[110:113], v[214:217], v[166:169], v[110:113]
	v_mfma_f32_16x16x32_bf16 v[102:105], v[206:209], v[182:185], v[102:105]
	v_mfma_f32_16x16x32_bf16 v[94:97], v[214:217], v[182:185], v[94:97]
	v_mfma_f32_16x16x32_bf16 v[86:89], v[206:209], v[190:193], v[86:89]
	v_mfma_f32_16x16x32_bf16 v[78:81], v[214:217], v[190:193], v[78:81]
	v_mfma_f32_16x16x32_bf16 v[70:73], v[206:209], v[198:201], v[70:73]
	v_mfma_f32_16x16x32_bf16 v[66:69], v[214:217], v[198:201], v[66:69]
	s_mov_b32 m0, s28
	v_lshl_add_u64 v[144:145], v[236:237], 0, s[56:57]
	s_barrier
	ds_read_b128 v[162:165], v149 offset:49152
	ds_read_b128 v[166:169], v149 offset:50176
	ds_read_b128 v[170:173], v149 offset:51200
	ds_read_b128 v[182:185], v149 offset:52224
	ds_read_b128 v[186:189], v149 offset:53248
	ds_read_b128 v[190:193], v149 offset:54272
	ds_read_b128 v[194:197], v149 offset:55296
	ds_read_b128 v[198:201], v149 offset:56320
	global_load_lds_dwordx4 v[144:145], off
	v_lshl_add_u64 v[144:145], v[238:239], 0, s[56:57]
	s_mov_b32 m0, s29
	s_nop 0
	global_load_lds_dwordx4 v[144:145], off
	s_barrier
	s_waitcnt lgkmcnt(0)
	v_mfma_f32_16x16x32_bf16 v[62:65], v[140:143], v[162:165], v[62:65]
	v_mfma_f32_16x16x32_bf16 v[58:61], v[154:157], v[162:165], v[58:61]
	v_mfma_f32_16x16x32_bf16 v[50:53], v[140:143], v[170:173], v[50:53]
	v_mfma_f32_16x16x32_bf16 v[42:45], v[154:157], v[170:173], v[42:45]
	v_mfma_f32_16x16x32_bf16 v[34:37], v[140:143], v[186:189], v[34:37]
	v_mfma_f32_16x16x32_bf16 v[26:29], v[154:157], v[186:189], v[26:29]
	v_mfma_f32_16x16x32_bf16 v[18:21], v[140:143], v[194:197], v[18:21]
	v_mfma_f32_16x16x32_bf16 v[10:13], v[154:157], v[194:197], v[10:13]
	v_mfma_f32_16x16x32_bf16 v[62:65], v[150:153], v[166:169], v[62:65]
	v_mfma_f32_16x16x32_bf16 v[58:61], v[158:161], v[166:169], v[58:61]
	v_mfma_f32_16x16x32_bf16 v[50:53], v[150:153], v[182:185], v[50:53]
	v_mfma_f32_16x16x32_bf16 v[42:45], v[158:161], v[182:185], v[42:45]
	v_mfma_f32_16x16x32_bf16 v[34:37], v[150:153], v[190:193], v[34:37]
	v_mfma_f32_16x16x32_bf16 v[26:29], v[158:161], v[190:193], v[26:29]
	v_mfma_f32_16x16x32_bf16 v[18:21], v[150:153], v[198:201], v[18:21]
	v_mfma_f32_16x16x32_bf16 v[10:13], v[158:161], v[198:201], v[10:13]
	s_barrier
	s_add_u32 s18, s18, 0x80080
	s_addc_u32 s19, s19, 0
	s_add_i32 s30, s30, s23
	v_lshl_add_u64 v[140:141], s[18:19], 0, v[0:1]
	s_mov_b32 m0, s30
	s_nop 0
	global_load_lds_dwordx4 v[140:141], off
	v_lshl_add_u64 v[140:141], s[18:19], 0, v[130:131]
	s_add_i32 m0, s30, 0x2000
	s_nop 0
	global_load_lds_dwordx4 v[140:141], off
	s_waitcnt vmcnt(6)
	s_barrier
	v_mfma_f32_16x16x32_bf16 v[54:57], v[202:205], v[162:165], v[54:57]
	v_mfma_f32_16x16x32_bf16 v[46:49], v[210:213], v[162:165], v[46:49]
	v_mfma_f32_16x16x32_bf16 v[38:41], v[202:205], v[170:173], v[38:41]
	v_mfma_f32_16x16x32_bf16 v[30:33], v[210:213], v[170:173], v[30:33]
	v_mfma_f32_16x16x32_bf16 v[22:25], v[202:205], v[186:189], v[22:25]
	v_mfma_f32_16x16x32_bf16 v[14:17], v[210:213], v[186:189], v[14:17]
	v_mfma_f32_16x16x32_bf16 v[6:9], v[202:205], v[194:197], v[6:9]
	v_mfma_f32_16x16x32_bf16 v[2:5], v[210:213], v[194:197], v[2:5]
	v_mfma_f32_16x16x32_bf16 v[54:57], v[206:209], v[166:169], v[54:57]
	v_mfma_f32_16x16x32_bf16 v[46:49], v[214:217], v[166:169], v[46:49]
	v_mfma_f32_16x16x32_bf16 v[38:41], v[206:209], v[182:185], v[38:41]
	v_mfma_f32_16x16x32_bf16 v[30:33], v[214:217], v[182:185], v[30:33]
	v_mfma_f32_16x16x32_bf16 v[22:25], v[206:209], v[190:193], v[22:25]
	v_mfma_f32_16x16x32_bf16 v[14:17], v[214:217], v[190:193], v[14:17]
	v_mfma_f32_16x16x32_bf16 v[6:9], v[206:209], v[198:201], v[6:9]
	v_mfma_f32_16x16x32_bf16 v[2:5], v[214:217], v[198:201], v[2:5]
	s_add_i32 s87, s87, 2
	s_add_u32 s0, s0, 0x100
	s_addc_u32 s1, s1, 0
	s_add_u32 s72, s72, 0x100
	s_addc_u32 s73, s73, 0
	s_cmp_gt_u32 s87, 29
	s_barrier
	s_cbranch_scc0 .LBB0_753
	v_lshl_add_u32 v142, s69, 8, v146
	v_ashrrev_i32_e32 v143, 31, v142
	v_lshl_or_b32 v140, s68, 8, v148
	s_movk_i32 s11, 0x2000
	v_lshlrev_b64 v[144:145], 14, v[142:143]
	v_cmp_gt_i32_e32 vcc, s11, v140
	v_ashrrev_i32_e32 v141, 31, v140
	v_lshl_add_u64 v[144:145], s[76:77], 0, v[144:145]
	s_and_saveexec_b64 s[0:1], vcc
	s_cbranch_execz .LBB0_756
	v_lshl_add_u64 v[150:151], v[140:141], 1, v[144:145]
	v_cvt_pk_bf16_f32 v126, v126, v127
	v_cvt_pk_bf16_f32 v127, v128, v129
	v_cvt_pk_bf16_f32 v128, v122, v123
	v_cvt_pk_bf16_f32 v129, v124, v125
	global_store_dwordx4 v[150:151], v[126:129], off

; #define PG8_STAGE(bufoff, gbase, voff) do { _Pragma("unroll") for (int _i = 0; _i < 2; ++_i) \
;         __builtin_amdgcn_global_load_lds((const unsigned*)((const char*)(gbase) + (voff)[_i]), (PG8_LAS unsigned*)(lds + (bufoff) + ldsw + _i * 8192), 16, 0, 0); } while (0)
; #define PG8_LDA(dst, b, h) do { _Pragma("unroll") for (int m = 0; m < 4; ++m) _Pragma("unroll") for (int k = 0; k < 2; ++k) dst[m][k] = *(const PG8_LAS bf16x8*)(lds + PG8_SA(b, h) + aoff + m * 2048 + k * 1024); } while (0)
; #define PG8_LDB(dst, b, h) do { _Pragma("unroll") for (int n = 0; n < 2; ++n) _Pragma("unroll") for (int k = 0; k < 2; ++k) dst[n][k] = *(const PG8_LAS bf16x8*)(lds + PG8_SB(b, h) + boff + n * 2048 + k * 1024); } while (0)
; #define PG8_WAIT_V(n) asm volatile("s_waitcnt vmcnt(" #n ")" ::: "memory")
; #define PG8_WAIT_L(n) asm volatile("s_waitcnt lgkmcnt(" #n ")" ::: "memory")
; #define PG8_BAR __builtin_amdgcn_s_barrier()
; #define PG8_SCHED __builtin_amdgcn_sched_barrier(0)
; template <bool FP8, class Epi, class Sched>
; __device__ __forceinline__ void gemm_phase(PG8_LAS unsigned char* lds, const Gemm g, const Sched& S, const Epi& E) {
;     ...
;             PG8_LDB(B0, 0, 0); PG8_SCHED; PG8_LDA(At, 0, 0); PG8_STAGE(PG8_SA(1, 1), a1 + hstepA, voffA);
;             PG8_WAIT_L(8); PG8_BAR; PG8_WAIT_L(0); PG8_MMA(0, 0, At, B0); PG8_BAR; PG8_SCHED;
;             PG8_LDB(B1, 0, 1); PG8_STAGE(PG8_SB(0, 0), b2, voffB);
;             PG8_BAR; PG8_WAIT_L(0); PG8_MMA(0, 1, At, B1); PG8_BAR;
;             PG8_LDA(At, 0, 1); PG8_STAGE(PG8_SA(0, 0), a2, voffA);
;             PG8_BAR; PG8_WAIT_L(0); PG8_MMA(1, 0, At, B0); PG8_BAR; PG8_SCHED;
;             PG8_STAGE(PG8_SB(0, 1), b2 + hstep, voffB);
;             PG8_WAIT_V(6); PG8_BAR; PG8_MMA(1, 1, At, B1); PG8_BAR;
;             PG8_LDB(B0, 1, 0); PG8_SCHED; PG8_LDA(At, 1, 0); PG8_STAGE(PG8_SA(0, 1), a2 + hstepA, voffA);
;             PG8_WAIT_L(8); PG8_BAR; PG8_WAIT_L(0); PG8_MMA(0, 0, At, B0); PG8_BAR; PG8_SCHED;
.LBB0_1090:
	s_add_u32 s10, s16, 0x100
	s_addc_u32 s11, s17, 0
	s_add_i32 s30, 0, 0x10000
	v_add_u32_e32 v0, s30, v183
	ds_read_b128 v[10:13], v0
	ds_read_b128 v[14:17], v0 offset:1024
	ds_read_b128 v[2:5], v0 offset:2048
	ds_read_b128 v[6:9], v0 offset:3072
	s_cmp_eq_u32 s73, 8
	s_cselect_b32 s19, s1, s11
	s_cselect_b32 s18, s0, s10
	s_cselect_b32 s13, s15, s72
	s_cselect_b32 s12, s14, s71
	v_lshl_add_u64 v[18:19], s[16:17], 0, v[162:163]
	s_add_i32 m0, s24, 0xc000
	ds_read_b128 v[186:189], v184
	ds_read_b128 v[190:193], v184 offset:1024
	ds_read_b128 v[194:197], v184 offset:2048
	ds_read_b128 v[198:201], v184 offset:3072
	ds_read_b128 v[202:205], v184 offset:4096
	ds_read_b128 v[206:209], v184 offset:5120
	ds_read_b128 v[236:239], v184 offset:6144
	ds_read_b128 v[240:243], v184 offset:7168
	global_load_lds_dwordx4 v[18:19], off
	v_lshl_add_u64 v[18:19], s[16:17], 0, v[164:165]
	s_add_i32 m0, s24, 0xe000
	s_nop 0
	global_load_lds_dwordx4 v[18:19], off
	s_waitcnt lgkmcnt(8)
	s_barrier
	s_waitcnt lgkmcnt(0)
	s_nop 1
	v_mfma_scale_f32_16x16x128_f8f6f4 v[150:153], v[10:17], v[186:193], v[150:153], v174, v174 op_sel_hi:[0,0,0]
	s_nop 1
	v_mfma_scale_f32_16x16x128_f8f6f4 v[146:149], v[2:9], v[186:193], v[146:149], v174, v174 op_sel_hi:[0,0,0]
	s_nop 1
	v_mfma_scale_f32_16x16x128_f8f6f4 v[134:137], v[10:17], v[194:201], v[134:137], v174, v174 op_sel_hi:[0,0,0]
	s_nop 1
	v_mfma_scale_f32_16x16x128_f8f6f4 v[130:133], v[2:9], v[194:201], v[130:133], v174, v174 op_sel_hi:[0,0,0]
	s_nop 1
	v_mfma_scale_f32_16x16x128_f8f6f4 v[118:121], v[10:17], v[202:209], v[118:121], v174, v174 op_sel_hi:[0,0,0]
	s_nop 1
	v_mfma_scale_f32_16x16x128_f8f6f4 v[114:117], v[2:9], v[202:209], v[114:117], v174, v174 op_sel_hi:[0,0,0]
	s_nop 1
	v_mfma_scale_f32_16x16x128_f8f6f4 v[102:105], v[10:17], v[236:243], v[102:105], v174, v174 op_sel_hi:[0,0,0]
	s_nop 1
	v_mfma_scale_f32_16x16x128_f8f6f4 v[98:101], v[2:9], v[236:243], v[98:101], v174, v174 op_sel_hi:[0,0,0]
	s_barrier
	s_add_i32 s31, 0, 0x14000
	s_add_i32 s16, s30, s23
	v_add_u32_e32 v0, s31, v183
	v_lshl_add_u64 v[166:167], s[12:13], 0, v[158:159]
	s_mov_b32 m0, s16
	ds_read_b128 v[210:213], v0
	ds_read_b128 v[214:217], v0 offset:1024
	ds_read_b128 v[18:21], v0 offset:2048
	ds_read_b128 v[22:25], v0 offset:3072
	global_load_lds_dwordx4 v[166:167], off
	v_lshl_add_u64 v[168:169], s[12:13], 0, v[154:155]
	s_add_i32 m0, s16, 0x2000
	s_nop 0
	global_load_lds_dwordx4 v[168:169], off
	s_barrier
	s_waitcnt lgkmcnt(0)
	s_nop 1
	v_mfma_scale_f32_16x16x128_f8f6f4 v[142:145], v[210:217], v[186:193], v[142:145], v174, v174 op_sel_hi:[0,0,0]
	s_nop 1
	v_mfma_scale_f32_16x16x128_f8f6f4 v[138:141], v[18:25], v[186:193], v[138:141], v174, v174 op_sel_hi:[0,0,0]
	s_nop 1
	v_mfma_scale_f32_16x16x128_f8f6f4 v[126:129], v[210:217], v[194:201], v[126:129], v174, v174 op_sel_hi:[0,0,0]
	s_nop 1
	v_mfma_scale_f32_16x16x128_f8f6f4 v[122:125], v[18:25], v[194:201], v[122:125], v174, v174 op_sel_hi:[0,0,0]
	s_nop 1
	v_mfma_scale_f32_16x16x128_f8f6f4 v[110:113], v[210:217], v[202:209], v[110:113], v174, v174 op_sel_hi:[0,0,0]
	s_nop 1
	v_mfma_scale_f32_16x16x128_f8f6f4 v[106:109], v[18:25], v[202:209], v[106:109], v174, v174 op_sel_hi:[0,0,0]
	s_nop 1
	v_mfma_scale_f32_16x16x128_f8f6f4 v[94:97], v[210:217], v[236:243], v[94:97], v174, v174 op_sel_hi:[0,0,0]
	s_nop 1
	v_mfma_scale_f32_16x16x128_f8f6f4 v[90:93], v[18:25], v[236:243], v[90:93], v174, v174 op_sel_hi:[0,0,0]
	s_mov_b32 m0, s24
	v_lshl_add_u64 v[170:171], s[18:19], 0, v[160:161]
	s_barrier
	ds_read_b128 v[186:189], v184 offset:16384
	ds_read_b128 v[190:193], v184 offset:17408
	ds_read_b128 v[194:197], v184 offset:18432
	ds_read_b128 v[198:201], v184 offset:19456
	ds_read_b128 v[202:205], v184 offset:20480
	ds_read_b128 v[206:209], v184 offset:21504
	ds_read_b128 v[236:239], v184 offset:22528
	ds_read_b128 v[240:243], v184 offset:23552
	global_load_lds_dwordx4 v[170:171], off
	v_lshl_add_u64 v[172:173], s[18:19], 0, v[156:157]
	s_mov_b32 m0, s25
	s_nop 0
	global_load_lds_dwordx4 v[172:173], off
	s_barrier
	s_waitcnt lgkmcnt(0)
	s_nop 1
	v_mfma_scale_f32_16x16x128_f8f6f4 v[86:89], v[10:17], v[186:193], v[86:89], v174, v174 op_sel_hi:[0,0,0]
	s_nop 1
	v_mfma_scale_f32_16x16x128_f8f6f4 v[82:85], v[2:9], v[186:193], v[82:85], v174, v174 op_sel_hi:[0,0,0]
	s_nop 1
	v_mfma_scale_f32_16x16x128_f8f6f4 v[70:73], v[10:17], v[194:201], v[70:73], v174, v174 op_sel_hi:[0,0,0]
	s_nop 1
	v_mfma_scale_f32_16x16x128_f8f6f4 v[66:69], v[2:9], v[194:201], v[66:69], v174, v174 op_sel_hi:[0,0,0]
	s_nop 1
	v_mfma_scale_f32_16x16x128_f8f6f4 v[54:57], v[10:17], v[202:209], v[54:57], v174, v174 op_sel_hi:[0,0,0]
	s_nop 1
	v_mfma_scale_f32_16x16x128_f8f6f4 v[50:53], v[2:9], v[202:209], v[50:53], v174, v174 op_sel_hi:[0,0,0]
	s_nop 1
	v_mfma_scale_f32_16x16x128_f8f6f4 v[38:41], v[10:17], v[236:243], v[38:41], v174, v174 op_sel_hi:[0,0,0]
	s_nop 1
	v_mfma_scale_f32_16x16x128_f8f6f4 v[34:37], v[2:9], v[236:243], v[34:37], v174, v174 op_sel_hi:[0,0,0]
	s_barrier
	s_add_u32 s16, s12, 0x30000
	s_addc_u32 s17, s13, 0
	s_add_i32 s30, s31, s23
	v_lshl_add_u64 v[2:3], s[16:17], 0, v[158:159]
	s_mov_b32 m0, s30
	s_nop 0
	global_load_lds_dwordx4 v[2:3], off
	v_lshl_add_u64 v[2:3], s[16:17], 0, v[154:155]
	s_add_i32 m0, s30, 0x2000
	s_nop 0
	global_load_lds_dwordx4 v[2:3], off
	s_waitcnt vmcnt(6)
	s_barrier
; #define PG8_STAGE(bufoff, gbase, voff) do { _Pragma("unroll") for (int _i = 0; _i < 2; ++_i) \
;         __builtin_amdgcn_global_load_lds((const unsigned*)((const char*)(gbase) + (voff)[_i]), (PG8_LAS unsigned*)(lds + (bufoff) + ldsw + _i * 8192), 16, 0, 0); } while (0)
; #define PG8_LDA(dst, b, h) do { _Pragma("unroll") for (int m = 0; m < 4; ++m) _Pragma("unroll") for (int k = 0; k < 2; ++k) dst[m][k] = *(const PG8_LAS bf16x8*)(lds + PG8_SA(b, h) + aoff + m * 2048 + k * 1024); } while (0)
; #define PG8_LDB(dst, b, h) do { _Pragma("unroll") for (int n = 0; n < 2; ++n) _Pragma("unroll") for (int k = 0; k < 2; ++k) dst[n][k] = *(const PG8_LAS bf16x8*)(lds + PG8_SB(b, h) + boff + n * 2048 + k * 1024); } while (0)
; #define PG8_WAIT_V(n) asm volatile("s_waitcnt vmcnt(" #n ")" ::: "memory")
; #define PG8_WAIT_L(n) asm volatile("s_waitcnt lgkmcnt(" #n ")" ::: "memory")
; #define PG8_BAR __builtin_amdgcn_s_barrier()
; #define PG8_SCHED __builtin_amdgcn_sched_barrier(0)
; template <bool FP8, class Epi, class Sched>
; __device__ __forceinline__ void gemm_phase(PG8_LAS unsigned char* lds, const Gemm g, const Sched& S, const Epi& E) {
;     ...
;             PG8_WAIT_V(6); PG8_BAR; PG8_MMA(1, 1, At, B1); PG8_BAR;
;             PG8_LDB(B0, 1, 0); PG8_SCHED; PG8_LDA(At, 1, 0); PG8_STAGE(PG8_SA(0, 1), a2 + hstepA, voffA);
;             PG8_WAIT_L(8); PG8_BAR; PG8_WAIT_L(0); PG8_MMA(0, 0, At, B0); PG8_BAR; PG8_SCHED;
;             PG8_LDB(B1, 1, 1); PG8_STAGE(PG8_SB(1, 0), b3, voffB);
;             PG8_BAR; PG8_WAIT_L(0); PG8_MMA(0, 1, At, B1); PG8_BAR;
;             PG8_LDA(At, 1, 1); PG8_STAGE(PG8_SA(1, 0), a3, voffA);
;             PG8_BAR; PG8_WAIT_L(0); PG8_MMA(1, 0, At, B0); PG8_BAR; PG8_SCHED;
	s_nop 1
	v_mfma_scale_f32_16x16x128_f8f6f4 v[78:81], v[210:217], v[186:193], v[78:81], v174, v174 op_sel_hi:[0,0,0]
	s_nop 1
	v_mfma_scale_f32_16x16x128_f8f6f4 v[74:77], v[18:25], v[186:193], v[74:77], v174, v174 op_sel_hi:[0,0,0]
	s_nop 1
	v_mfma_scale_f32_16x16x128_f8f6f4 v[62:65], v[210:217], v[194:201], v[62:65], v174, v174 op_sel_hi:[0,0,0]
	s_nop 1
	v_mfma_scale_f32_16x16x128_f8f6f4 v[58:61], v[18:25], v[194:201], v[58:61], v174, v174 op_sel_hi:[0,0,0]
	s_nop 1
	v_mfma_scale_f32_16x16x128_f8f6f4 v[46:49], v[210:217], v[202:209], v[46:49], v174, v174 op_sel_hi:[0,0,0]
	s_nop 1
	v_mfma_scale_f32_16x16x128_f8f6f4 v[42:45], v[18:25], v[202:209], v[42:45], v174, v174 op_sel_hi:[0,0,0]
	s_nop 1
	v_mfma_scale_f32_16x16x128_f8f6f4 v[30:33], v[210:217], v[236:243], v[30:33], v174, v174 op_sel_hi:[0,0,0]
	s_nop 1
	v_mfma_scale_f32_16x16x128_f8f6f4 v[26:29], v[18:25], v[236:243], v[26:29], v174, v174 op_sel_hi:[0,0,0]
	s_add_i32 s30, 0, 0x18000
	v_add_u32_e32 v0, s30, v183
	s_barrier
	ds_read_b128 v[2:5], v0
	ds_read_b128 v[6:9], v0 offset:1024
	ds_read_b128 v[10:13], v0 offset:2048
	ds_read_b128 v[14:17], v0 offset:3072
	s_add_u32 s16, s18, 0x30000
	s_addc_u32 s17, s19, 0
	s_mov_b32 m0, s26
	v_lshl_add_u64 v[210:211], s[16:17], 0, v[160:161]
	ds_read_b128 v[18:21], v184 offset:32768
	ds_read_b128 v[22:25], v184 offset:33792
	ds_read_b128 v[186:189], v184 offset:34816
	ds_read_b128 v[190:193], v184 offset:35840
	ds_read_b128 v[194:197], v184 offset:36864
	ds_read_b128 v[198:201], v184 offset:37888
	ds_read_b128 v[202:205], v184 offset:38912
	ds_read_b128 v[206:209], v184 offset:39936
	global_load_lds_dwordx4 v[210:211], off
	v_lshl_add_u64 v[210:211], s[16:17], 0, v[156:157]
	s_mov_b32 m0, s27
	s_nop 0
	global_load_lds_dwordx4 v[210:211], off
	s_waitcnt lgkmcnt(8)
	s_barrier
	s_waitcnt lgkmcnt(0)
	s_nop 1
	v_mfma_scale_f32_16x16x128_f8f6f4 v[150:153], v[2:9], v[18:25], v[150:153], v174, v174 op_sel_hi:[0,0,0]
	s_nop 1
	v_mfma_scale_f32_16x16x128_f8f6f4 v[146:149], v[10:17], v[18:25], v[146:149], v174, v174 op_sel_hi:[0,0,0]
	s_nop 1
	v_mfma_scale_f32_16x16x128_f8f6f4 v[134:137], v[2:9], v[186:193], v[134:137], v174, v174 op_sel_hi:[0,0,0]
	s_nop 1
	v_mfma_scale_f32_16x16x128_f8f6f4 v[130:133], v[10:17], v[186:193], v[130:133], v174, v174 op_sel_hi:[0,0,0]
	s_nop 1
	v_mfma_scale_f32_16x16x128_f8f6f4 v[118:121], v[2:9], v[194:201], v[118:121], v174, v174 op_sel_hi:[0,0,0]
	s_nop 1
	v_mfma_scale_f32_16x16x128_f8f6f4 v[114:117], v[10:17], v[194:201], v[114:117], v174, v174 op_sel_hi:[0,0,0]
	s_nop 1
	v_mfma_scale_f32_16x16x128_f8f6f4 v[102:105], v[2:9], v[202:209], v[102:105], v174, v174 op_sel_hi:[0,0,0]
	s_nop 1
	v_mfma_scale_f32_16x16x128_f8f6f4 v[98:101], v[10:17], v[202:209], v[98:101], v174, v174 op_sel_hi:[0,0,0]
	s_barrier
	s_add_i32 s16, 0, 0x1c000
	s_add_i32 s17, s30, s23
	v_add_u32_e32 v0, s16, v183
	v_lshl_add_u64 v[166:167], v[166:167], 0, s[56:57]
	s_mov_b32 m0, s17
	ds_read_b128 v[210:213], v0
	ds_read_b128 v[214:217], v0 offset:1024
	ds_read_b128 v[236:239], v0 offset:2048
	ds_read_b128 v[240:243], v0 offset:3072
	global_load_lds_dwordx4 v[166:167], off
	v_lshl_add_u64 v[166:167], v[168:169], 0, s[56:57]
	s_add_i32 m0, s17, 0x2000
	s_nop 0
	global_load_lds_dwordx4 v[166:167], off
	s_barrier
	s_waitcnt lgkmcnt(0)
	s_nop 1
	v_mfma_scale_f32_16x16x128_f8f6f4 v[142:145], v[210:217], v[18:25], v[142:145], v174, v174 op_sel_hi:[0,0,0]
	s_nop 1
	v_mfma_scale_f32_16x16x128_f8f6f4 v[138:141], v[236:243], v[18:25], v[138:141], v174, v174 op_sel_hi:[0,0,0]
	s_nop 1
	v_mfma_scale_f32_16x16x128_f8f6f4 v[126:129], v[210:217], v[186:193], v[126:129], v174, v174 op_sel_hi:[0,0,0]
	s_nop 1
	v_mfma_scale_f32_16x16x128_f8f6f4 v[122:125], v[236:243], v[186:193], v[122:125], v174, v174 op_sel_hi:[0,0,0]
	s_nop 1
	v_mfma_scale_f32_16x16x128_f8f6f4 v[110:113], v[210:217], v[194:201], v[110:113], v174, v174 op_sel_hi:[0,0,0]
	s_nop 1
	v_mfma_scale_f32_16x16x128_f8f6f4 v[106:109], v[236:243], v[194:201], v[106:109], v174, v174 op_sel_hi:[0,0,0]
	s_nop 1
	v_mfma_scale_f32_16x16x128_f8f6f4 v[94:97], v[210:217], v[202:209], v[94:97], v174, v174 op_sel_hi:[0,0,0]
	s_nop 1
	v_mfma_scale_f32_16x16x128_f8f6f4 v[90:93], v[236:243], v[202:209], v[90:93], v174, v174 op_sel_hi:[0,0,0]
	s_mov_b32 m0, s54
	v_lshl_add_u64 v[166:167], v[170:171], 0, s[56:57]
	s_barrier
	ds_read_b128 v[18:21], v184 offset:49152
	ds_read_b128 v[22:25], v184 offset:50176
	ds_read_b128 v[186:189], v184 offset:51200
	ds_read_b128 v[190:193], v184 offset:52224
	ds_read_b128 v[194:197], v184 offset:53248
	ds_read_b128 v[198:201], v184 offset:54272
	ds_read_b128 v[202:205], v184 offset:55296
	ds_read_b128 v[206:209], v184 offset:56320
	global_load_lds_dwordx4 v[166:167], off
	v_lshl_add_u64 v[166:167], v[172:173], 0, s[56:57]
	s_mov_b32 m0, s66
	s_nop 0
	global_load_lds_dwordx4 v[166:167], off
	s_barrier
	s_waitcnt lgkmcnt(0)
	s_nop 1
	v_mfma_scale_f32_16x16x128_f8f6f4 v[86:89], v[2:9], v[18:25], v[86:89], v174, v174 op_sel_hi:[0,0,0]
	s_nop 1
	v_mfma_scale_f32_16x16x128_f8f6f4 v[82:85], v[10:17], v[18:25], v[82:85], v174, v174 op_sel_hi:[0,0,0]
	s_nop 1
	v_mfma_scale_f32_16x16x128_f8f6f4 v[70:73], v[2:9], v[186:193], v[70:73], v174, v174 op_sel_hi:[0,0,0]
	s_nop 1
	v_mfma_scale_f32_16x16x128_f8f6f4 v[66:69], v[10:17], v[186:193], v[66:69], v174, v174 op_sel_hi:[0,0,0]
	s_nop 1
	v_mfma_scale_f32_16x16x128_f8f6f4 v[54:57], v[2:9], v[194:201], v[54:57], v174, v174 op_sel_hi:[0,0,0]
	s_nop 1
	v_mfma_scale_f32_16x16x128_f8f6f4 v[50:53], v[10:17], v[194:201], v[50:53], v174, v174 op_sel_hi:[0,0,0]
	s_nop 1
	v_mfma_scale_f32_16x16x128_f8f6f4 v[38:41], v[2:9], v[202:209], v[38:41], v174, v174 op_sel_hi:[0,0,0]
	s_nop 1
	v_mfma_scale_f32_16x16x128_f8f6f4 v[34:37], v[10:17], v[202:209], v[34:37], v174, v174 op_sel_hi:[0,0,0]
	s_barrier
; #define PG8_STAGE(bufoff, gbase, voff) do { _Pragma("unroll") for (int _i = 0; _i < 2; ++_i) \
;         __builtin_amdgcn_global_load_lds((const unsigned*)((const char*)(gbase) + (voff)[_i]), (PG8_LAS unsigned*)(lds + (bufoff) + ldsw + _i * 8192), 16, 0, 0); } while (0)
; template <bool FP8, class Epi, class Sched>
; __device__ __forceinline__ void gemm_phase(PG8_LAS unsigned char* lds, const Gemm g, const Sched& S, const Epi& E) {
;     ...
;             PG8_STAGE(PG8_SB(1, 1), b3 + hstep, voffB);
;             PG8_WAIT_V(6); PG8_BAR; PG8_MMA(1, 1, At, B1); PG8_BAR;
;         }
;         if constexpr (FP8) asm volatile("s_nop 15\n\ts_nop 15" ::: "memory");
;         if constexpr (!Epi::AFTER_DRAIN) { E(acc, cur, wr, wc, fr, fq); S.done(cur); }
;   DI void operator()(const f32x4 (&acc)[2][2][4][2], const pg8::Unit& u, int wr, int wc, int fr, int fq) const {
;     const int row0 = u.pm * 256 + wr * 64 + fr, colb = u.pn * 256 + wc * 32 + 8 * fq;
; #pragma unroll
;     for (int ai = 0; ai < 2; ++ai)
; #pragma unroll
;       for (int m = 0; m < 4; ++m) {
;         const int row = row0 + ai * 128 + m * 16;
; #pragma unroll
;         for (int bj = 0; bj < 2; ++bj) {
;           const int col = colb + bj * 128;
;           f32x4 v0 = acc[ai][bj][m][0] * sc, v1 = acc[ai][bj][m][1] * sc;
;           u16* dst = nullptr;
;           if (MODE == 0) { if (col < N) dst = d0 + (size_t)row * ld0 + (col + coff2 + ((col < csplit) ? (coff1 - coff2) : 0)); }
;           else if (MODE == 1) {
;             const int oc = col + coff2 + ((col < csplit) ? (coff1 - coff2) : 0);
;             if (col < N) {
;               if (oc < 2048) dst = d0 + (size_t)row * 2048 + oc;
;               else if (oc < 2112) { rot(v0, v1, row, oc); dst = d2 + (size_t)row * 64 + (oc - 2048); }
;               else dst = d1 + (size_t)row * 4096 + (oc - 2112);
;             }
;           } else if (MODE == 3) {
;             if (col < N) { const bool lo = col < csplit; u16* bp = lo ? d0 : d1; const int ldd = lo ? 2048 : 4096, oc = lo ? col : col + (coff2 - 2112); dst = bp + (size_t)row * ldd + oc + (lo ? coff1 : 0); }
;           } else {
;             if (((col >> 6) % 3) == 2) rot(v0, v1, row, col);
;             dst = d0 + (size_t)row * 3072 + col;
;           }
;           if (dst) { u32x4 w = {pk2(v0[0], v0[1]), pk2(v0[2], v0[3]), pk2(v1[0], v1[1]), pk2(v1[2], v1[3])}; *(u32x4*)dst = w; }
	s_add_u32 s12, s12, 0x30080
	s_addc_u32 s13, s13, 0
	s_add_i32 s16, s16, s23
	v_lshl_add_u64 v[2:3], s[12:13], 0, v[158:159]
	s_mov_b32 m0, s16
	s_nop 0
	global_load_lds_dwordx4 v[2:3], off
	v_lshl_add_u64 v[2:3], s[12:13], 0, v[154:155]
	s_add_i32 m0, s16, 0x2000
	s_nop 0
	global_load_lds_dwordx4 v[2:3], off
	s_waitcnt vmcnt(6)
	s_barrier
	s_nop 1
	v_mfma_scale_f32_16x16x128_f8f6f4 v[78:81], v[210:217], v[18:25], v[78:81], v174, v174 op_sel_hi:[0,0,0]
	s_nop 1
	v_mfma_scale_f32_16x16x128_f8f6f4 v[74:77], v[236:243], v[18:25], v[74:77], v174, v174 op_sel_hi:[0,0,0]
	s_nop 1
	v_mfma_scale_f32_16x16x128_f8f6f4 v[62:65], v[210:217], v[186:193], v[62:65], v174, v174 op_sel_hi:[0,0,0]
	s_nop 1
	v_mfma_scale_f32_16x16x128_f8f6f4 v[58:61], v[236:243], v[186:193], v[58:61], v174, v174 op_sel_hi:[0,0,0]
	s_nop 1
	v_mfma_scale_f32_16x16x128_f8f6f4 v[46:49], v[210:217], v[194:201], v[46:49], v174, v174 op_sel_hi:[0,0,0]
	s_nop 1
	v_mfma_scale_f32_16x16x128_f8f6f4 v[42:45], v[236:243], v[194:201], v[42:45], v174, v174 op_sel_hi:[0,0,0]
	s_nop 1
	v_mfma_scale_f32_16x16x128_f8f6f4 v[30:33], v[210:217], v[202:209], v[30:33], v174, v174 op_sel_hi:[0,0,0]
	s_nop 1
	v_mfma_scale_f32_16x16x128_f8f6f4 v[26:29], v[236:243], v[202:209], v[26:29], v174, v174 op_sel_hi:[0,0,0]
	s_add_i32 s73, s73, 2
	s_add_u32 s71, s71, 0x100
	s_addc_u32 s72, s72, 0
	s_cmp_gt_u32 s73, 9
	s_mov_b64 s[16:17], s[10:11]
	s_barrier
	s_cbranch_scc0 .LBB0_1090
	s_lshl_b32 s10, s28, 8
	s_or_b32 s10, s10, s67
	v_or_b32_e32 v4, s10, v182
	s_ashr_i32 s10, s10, 6
	s_mul_hi_i32 s11, s10, 0x55555556
	s_lshr_b32 s12, s11, 31
	s_add_i32 s11, s11, s12
	v_lshl_add_u32 v16, s29, 8, v175
	v_lshrrev_b32_e32 v0, 1, v4
	s_mul_i32 s11, s11, 3
	s_nop 15
	s_nop 15
	v_and_b32_e32 v2, 28, v0
	v_lshlrev_b32_e32 v0, 5, v16
	s_sub_i32 s10, s10, s11
	v_and_b32_e32 v0, 0xf9e0, v0
	s_cmp_eq_u32 s10, 2
	v_pk_mul_f32 v[14:15], v[152:153], s[58:59] op_sel_hi:[1,0]
	v_pk_mul_f32 v[8:9], v[150:151], s[58:59] op_sel_hi:[1,0]
	v_pk_mul_f32 v[12:13], v[148:149], s[58:59] op_sel_hi:[1,0]
	v_pk_mul_f32 v[10:11], v[146:147], s[58:59] op_sel_hi:[1,0]
	s_cselect_b64 s[16:17], -1, 0
	s_cmp_lg_u32 s10, 2
	v_lshlrev_b32_e32 v0, 3, v0
	v_lshlrev_b32_e32 v2, 3, v2
	v_mov_b32_e32 v238, v2
	v_mov_b32_e32 v239, 0
	v_mov_b32_e32 v236, v16
	v_lshlrev_b32_e32 v236, 5, v236
	v_and_b32_e32 v236, 0xffe0, v236
	v_lshlrev_b32_e32 v236, 3, v236
	v_mov_b32_e32 v237, 0
	v_lshl_add_u64 v[236:237], s[52:53], 0, v[236:237]
	v_lshl_add_u64 v[236:237], v[236:237], 0, v[238:239]
	global_load_dwordx4 v[186:189], v[236:237], off offset:16
	global_load_dwordx4 v[190:193], v[236:237], off
	v_add_u32_e32 v236, 16, v16
	v_lshlrev_b32_e32 v236, 5, v236
	v_and_b32_e32 v236, 0xffe0, v236
	v_lshlrev_b32_e32 v236, 3, v236
	v_mov_b32_e32 v237, 0
	v_lshl_add_u64 v[236:237], s[52:53], 0, v[236:237]
	v_lshl_add_u64 v[236:237], v[236:237], 0, v[238:239]
	global_load_dwordx4 v[194:197], v[236:237], off offset:16
	global_load_dwordx4 v[198:201], v[236:237], off
	v_add_u32_e32 v236, 32, v16
	v_lshlrev_b32_e32 v236, 5, v236
	v_and_b32_e32 v236, 0xffe0, v236
	v_lshlrev_b32_e32 v236, 3, v236
	v_mov_b32_e32 v237, 0
	v_lshl_add_u64 v[236:237], s[52:53], 0, v[236:237]
	v_lshl_add_u64 v[236:237], v[236:237], 0, v[238:239]
	global_load_dwordx4 v[202:205], v[236:237], off offset:16
	global_load_dwordx4 v[206:209], v[236:237], off
	v_add_u32_e32 v236, 48, v16
	v_lshlrev_b32_e32 v236, 5, v236
	v_and_b32_e32 v236, 0xffe0, v236
	v_lshlrev_b32_e32 v236, 3, v236
	v_mov_b32_e32 v237, 0
	v_lshl_add_u64 v[236:237], s[52:53], 0, v[236:237]
	v_lshl_add_u64 v[236:237], v[236:237], 0, v[238:239]
	global_load_dwordx4 v[210:213], v[236:237], off offset:16
	global_load_dwordx4 v[214:217], v[236:237], off
	s_waitcnt vmcnt(0)
	s_cbranch_scc1 .LBB0_1093
	v_mov_b32_e32 v3, v1
	v_mov_b32_e32 v18, v186
	v_mov_b32_e32 v19, v187
	v_mov_b32_e32 v20, v188
	v_mov_b32_e32 v21, v189
	v_mov_b32_e32 v22, v190
	v_mov_b32_e32 v23, v191
	v_mov_b32_e32 v24, v192
	v_mov_b32_e32 v25, v193
	v_pk_mul_f32 v[148:149], v[10:11], v[18:19] op_sel:[1,1] op_sel_hi:[0,1]
	v_pk_mul_f32 v[146:147], v[8:9], v[22:23] op_sel:[1,1] op_sel_hi:[0,1]
	v_pk_mul_f32 v[6:7], v[8:9], v[22:23]
	v_pk_fma_f32 v[8:9], v[8:9], v[22:23], v[146:147] op_sel_hi:[1,0,1]
	s_nop 0
	v_mul_f32_e32 v8, v15, v25
	v_pk_fma_f32 v[22:23], v[14:15], v[24:25], v[8:9] op_sel_hi:[1,1,0] neg_lo:[0,0,1] neg_hi:[0,0,1]
	v_mul_f32_e32 v8, v14, v25
	v_pk_fma_f32 v[24:25], v[14:15], v[24:25], v[8:9] op_sel:[1,0,0] op_sel_hi:[0,1,0]
	v_mul_f32_e32 v8, v13, v21
	v_pk_mul_f32 v[14:15], v[10:11], v[18:19]
	v_pk_fma_f32 v[10:11], v[10:11], v[18:19], v[148:149] op_sel_hi:[1,0,1]
	v_pk_fma_f32 v[18:19], v[12:13], v[20:21], v[8:9] op_sel_hi:[1,1,0] neg_lo:[0,0,1] neg_hi:[0,0,1]
	v_mul_f32_e32 v8, v12, v21
	v_pk_fma_f32 v[20:21], v[12:13], v[20:21], v[8:9] op_sel:[1,0,0] op_sel_hi:[0,1,0]
	v_sub_f32_e32 v10, v14, v148
	v_sub_f32_e32 v8, v6, v146
	v_mov_b32_e32 v12, v18
	v_mov_b32_e32 v13, v20
	v_mov_b32_e32 v14, v22
	v_mov_b32_e32 v15, v24

; #define PG8_STAGE(bufoff, gbase, voff) do { _Pragma("unroll") for (int _i = 0; _i < 2; ++_i) \
;         __builtin_amdgcn_global_load_lds((const unsigned*)((const char*)(gbase) + (voff)[_i]), (PG8_LAS unsigned*)(lds + (bufoff) + ldsw + _i * 8192), 16, 0, 0); } while (0)
; #define PG8_LDA(dst, b, h) do { _Pragma("unroll") for (int m = 0; m < 4; ++m) _Pragma("unroll") for (int k = 0; k < 2; ++k) dst[m][k] = *(const PG8_LAS bf16x8*)(lds + PG8_SA(b, h) + aoff + m * 2048 + k * 1024); } while (0)
; #define PG8_LDB(dst, b, h) do { _Pragma("unroll") for (int n = 0; n < 2; ++n) _Pragma("unroll") for (int k = 0; k < 2; ++k) dst[n][k] = *(const PG8_LAS bf16x8*)(lds + PG8_SB(b, h) + boff + n * 2048 + k * 1024); } while (0)
; #define PG8_WAIT_V(n) asm volatile("s_waitcnt vmcnt(" #n ")" ::: "memory")
; #define PG8_WAIT_L(n) asm volatile("s_waitcnt lgkmcnt(" #n ")" ::: "memory")
; #define PG8_BAR __builtin_amdgcn_s_barrier()
; #define PG8_SCHED __builtin_amdgcn_sched_barrier(0)
; template <bool FP8, class Epi, class Sched>
; __device__ __forceinline__ void gemm_phase(PG8_LAS unsigned char* lds, const Gemm g, const Sched& S, const Epi& E) {
;     ...
;             PG8_LDB(B0, 0, 0); PG8_SCHED; PG8_LDA(At, 0, 0); PG8_STAGE(PG8_SA(1, 1), a1 + hstepA, voffA);
;             PG8_WAIT_L(8); PG8_BAR; PG8_WAIT_L(0); PG8_MMA(0, 0, At, B0); PG8_BAR; PG8_SCHED;
;             PG8_LDB(B1, 0, 1); PG8_STAGE(PG8_SB(0, 0), b2, voffB);
;             PG8_BAR; PG8_WAIT_L(0); PG8_MMA(0, 1, At, B1); PG8_BAR;
;             PG8_LDA(At, 0, 1); PG8_STAGE(PG8_SA(0, 0), a2, voffA);
;             PG8_BAR; PG8_WAIT_L(0); PG8_MMA(1, 0, At, B0); PG8_BAR; PG8_SCHED;
;             PG8_STAGE(PG8_SB(0, 1), b2 + hstep, voffB);
;             PG8_WAIT_V(6); PG8_BAR; PG8_MMA(1, 1, At, B1); PG8_BAR;
;             PG8_LDB(B0, 1, 0); PG8_SCHED; PG8_LDA(At, 1, 0); PG8_STAGE(PG8_SA(0, 1), a2 + hstepA, voffA);
;             PG8_WAIT_L(8); PG8_BAR; PG8_WAIT_L(0); PG8_MMA(0, 0, At, B0); PG8_BAR; PG8_SCHED;
.LBB0_1138:
	s_add_u32 s18, s0, 0xfff80080
	s_addc_u32 s19, s1, -1
	s_add_i32 s30, 0, 0x10000
	v_add_u32_e32 v144, s30, v147
	ds_read_b128 v[140:143], v144
	ds_read_b128 v[150:153], v144 offset:1024
	ds_read_b128 v[154:157], v144 offset:2048
	ds_read_b128 v[158:161], v144 offset:3072
	s_cmp_eq_u32 s87, 4
	s_cselect_b32 s67, s13, s19
	s_cselect_b32 s66, s70, s18
	s_cselect_b32 s19, s11, s73
	s_cselect_b32 s18, s71, s72
	v_lshl_add_u64 v[144:145], s[0:1], 0, v[136:137]
	s_add_i32 m0, s24, 0xc000
	ds_read_b128 v[162:165], v149
	ds_read_b128 v[166:169], v149 offset:1024
	ds_read_b128 v[170:173], v149 offset:2048
	ds_read_b128 v[182:185], v149 offset:3072
	ds_read_b128 v[186:189], v149 offset:4096
	ds_read_b128 v[190:193], v149 offset:5120
	ds_read_b128 v[194:197], v149 offset:6144
	ds_read_b128 v[198:201], v149 offset:7168
	global_load_lds_dwordx4 v[144:145], off
	v_lshl_add_u64 v[144:145], s[0:1], 0, v[138:139]
	s_add_i32 m0, s24, 0xe000
	s_nop 0
	global_load_lds_dwordx4 v[144:145], off
	s_waitcnt lgkmcnt(8)
	s_barrier
	s_waitcnt lgkmcnt(0)
	v_mfma_f32_16x16x32_bf16 v[126:129], v[140:143], v[162:165], v[126:129]
	v_mfma_f32_16x16x32_bf16 v[122:125], v[154:157], v[162:165], v[122:125]
	v_mfma_f32_16x16x32_bf16 v[114:117], v[140:143], v[170:173], v[114:117]
	v_mfma_f32_16x16x32_bf16 v[106:109], v[154:157], v[170:173], v[106:109]
	v_mfma_f32_16x16x32_bf16 v[98:101], v[140:143], v[186:189], v[98:101]
	v_mfma_f32_16x16x32_bf16 v[90:93], v[154:157], v[186:189], v[90:93]
	v_mfma_f32_16x16x32_bf16 v[82:85], v[140:143], v[194:197], v[82:85]
	v_mfma_f32_16x16x32_bf16 v[74:77], v[154:157], v[194:197], v[74:77]
	v_mfma_f32_16x16x32_bf16 v[126:129], v[150:153], v[166:169], v[126:129]
	v_mfma_f32_16x16x32_bf16 v[122:125], v[158:161], v[166:169], v[122:125]
	v_mfma_f32_16x16x32_bf16 v[114:117], v[150:153], v[182:185], v[114:117]
	v_mfma_f32_16x16x32_bf16 v[106:109], v[158:161], v[182:185], v[106:109]
	v_mfma_f32_16x16x32_bf16 v[98:101], v[150:153], v[190:193], v[98:101]
	v_mfma_f32_16x16x32_bf16 v[90:93], v[158:161], v[190:193], v[90:93]
	v_mfma_f32_16x16x32_bf16 v[82:85], v[150:153], v[198:201], v[82:85]
	v_mfma_f32_16x16x32_bf16 v[74:77], v[158:161], v[198:201], v[74:77]
	s_barrier
	s_add_i32 s86, 0, 0x14000
	v_add_u32_e32 v144, s86, v147
	s_add_i32 s30, s30, s23
	ds_read_b128 v[202:205], v144
	ds_read_b128 v[206:209], v144 offset:1024
	ds_read_b128 v[210:213], v144 offset:2048
	ds_read_b128 v[214:217], v144 offset:3072
	v_lshl_add_u64 v[144:145], s[18:19], 0, v[134:135]
	s_mov_b32 m0, s30
	v_lshl_add_u64 v[174:175], s[18:19], 0, v[130:131]
	global_load_lds_dwordx4 v[144:145], off
	s_add_i32 m0, s30, 0x2000
	s_nop 0
	global_load_lds_dwordx4 v[174:175], off
	s_barrier
	s_waitcnt lgkmcnt(0)
	v_mfma_f32_16x16x32_bf16 v[118:121], v[202:205], v[162:165], v[118:121]
	v_mfma_f32_16x16x32_bf16 v[110:113], v[210:213], v[162:165], v[110:113]
	v_mfma_f32_16x16x32_bf16 v[102:105], v[202:205], v[170:173], v[102:105]
	v_mfma_f32_16x16x32_bf16 v[94:97], v[210:213], v[170:173], v[94:97]
	v_mfma_f32_16x16x32_bf16 v[86:89], v[202:205], v[186:189], v[86:89]
	v_mfma_f32_16x16x32_bf16 v[78:81], v[210:213], v[186:189], v[78:81]
	v_mfma_f32_16x16x32_bf16 v[70:73], v[202:205], v[194:197], v[70:73]
	v_mfma_f32_16x16x32_bf16 v[66:69], v[210:213], v[194:197], v[66:69]
	v_mfma_f32_16x16x32_bf16 v[118:121], v[206:209], v[166:169], v[118:121]
	v_mfma_f32_16x16x32_bf16 v[110:113], v[214:217], v[166:169], v[110:113]
	v_mfma_f32_16x16x32_bf16 v[102:105], v[206:209], v[182:185], v[102:105]
	v_mfma_f32_16x16x32_bf16 v[94:97], v[214:217], v[182:185], v[94:97]
	v_mfma_f32_16x16x32_bf16 v[86:89], v[206:209], v[190:193], v[86:89]
	v_mfma_f32_16x16x32_bf16 v[78:81], v[214:217], v[190:193], v[78:81]
	v_mfma_f32_16x16x32_bf16 v[70:73], v[206:209], v[198:201], v[70:73]
	v_mfma_f32_16x16x32_bf16 v[66:69], v[214:217], v[198:201], v[66:69]
	s_mov_b32 m0, s24
	v_lshl_add_u64 v[236:237], s[66:67], 0, v[0:1]
	s_barrier
	ds_read_b128 v[162:165], v149 offset:16384
	ds_read_b128 v[166:169], v149 offset:17408
	ds_read_b128 v[170:173], v149 offset:18432
	ds_read_b128 v[182:185], v149 offset:19456
	ds_read_b128 v[186:189], v149 offset:20480
	ds_read_b128 v[190:193], v149 offset:21504
	ds_read_b128 v[194:197], v149 offset:22528
	ds_read_b128 v[198:201], v149 offset:23552
	global_load_lds_dwordx4 v[236:237], off
	v_lshl_add_u64 v[238:239], s[66:67], 0, v[132:133]
	s_mov_b32 m0, s25
	s_nop 0
	global_load_lds_dwordx4 v[238:239], off
	s_barrier
	s_waitcnt lgkmcnt(0)
	v_mfma_f32_16x16x32_bf16 v[62:65], v[140:143], v[162:165], v[62:65]
	v_mfma_f32_16x16x32_bf16 v[58:61], v[154:157], v[162:165], v[58:61]
	v_mfma_f32_16x16x32_bf16 v[50:53], v[140:143], v[170:173], v[50:53]
	v_mfma_f32_16x16x32_bf16 v[42:45], v[154:157], v[170:173], v[42:45]
	v_mfma_f32_16x16x32_bf16 v[34:37], v[140:143], v[186:189], v[34:37]
	v_mfma_f32_16x16x32_bf16 v[26:29], v[154:157], v[186:189], v[26:29]
	v_mfma_f32_16x16x32_bf16 v[18:21], v[140:143], v[194:197], v[18:21]
	v_mfma_f32_16x16x32_bf16 v[10:13], v[154:157], v[194:197], v[10:13]
	v_mfma_f32_16x16x32_bf16 v[62:65], v[150:153], v[166:169], v[62:65]
	v_mfma_f32_16x16x32_bf16 v[58:61], v[158:161], v[166:169], v[58:61]
	v_mfma_f32_16x16x32_bf16 v[50:53], v[150:153], v[182:185], v[50:53]
	v_mfma_f32_16x16x32_bf16 v[42:45], v[158:161], v[182:185], v[42:45]
	v_mfma_f32_16x16x32_bf16 v[34:37], v[150:153], v[190:193], v[34:37]
	v_mfma_f32_16x16x32_bf16 v[26:29], v[158:161], v[190:193], v[26:29]
	v_mfma_f32_16x16x32_bf16 v[18:21], v[150:153], v[198:201], v[18:21]
	v_mfma_f32_16x16x32_bf16 v[10:13], v[158:161], v[198:201], v[10:13]
	s_barrier
; #define PG8_STAGE(bufoff, gbase, voff) do { _Pragma("unroll") for (int _i = 0; _i < 2; ++_i) \
;         __builtin_amdgcn_global_load_lds((const unsigned*)((const char*)(gbase) + (voff)[_i]), (PG8_LAS unsigned*)(lds + (bufoff) + ldsw + _i * 8192), 16, 0, 0); } while (0)
; #define PG8_LDA(dst, b, h) do { _Pragma("unroll") for (int m = 0; m < 4; ++m) _Pragma("unroll") for (int k = 0; k < 2; ++k) dst[m][k] = *(const PG8_LAS bf16x8*)(lds + PG8_SA(b, h) + aoff + m * 2048 + k * 1024); } while (0)
; #define PG8_LDB(dst, b, h) do { _Pragma("unroll") for (int n = 0; n < 2; ++n) _Pragma("unroll") for (int k = 0; k < 2; ++k) dst[n][k] = *(const PG8_LAS bf16x8*)(lds + PG8_SB(b, h) + boff + n * 2048 + k * 1024); } while (0)
; #define PG8_WAIT_V(n) asm volatile("s_waitcnt vmcnt(" #n ")" ::: "memory")
; #define PG8_WAIT_L(n) asm volatile("s_waitcnt lgkmcnt(" #n ")" ::: "memory")
; #define PG8_BAR __builtin_amdgcn_s_barrier()
; #define PG8_SCHED __builtin_amdgcn_sched_barrier(0)
; template <bool FP8, class Epi, class Sched>
; __device__ __forceinline__ void gemm_phase(PG8_LAS unsigned char* lds, const Gemm g, const Sched& S, const Epi& E) {
;     ...
;             PG8_STAGE(PG8_SB(0, 1), b2 + hstep, voffB);
;             PG8_WAIT_V(6); PG8_BAR; PG8_MMA(1, 1, At, B1); PG8_BAR;
;             PG8_LDB(B0, 1, 0); PG8_SCHED; PG8_LDA(At, 1, 0); PG8_STAGE(PG8_SA(0, 1), a2 + hstepA, voffA);
;             PG8_WAIT_L(8); PG8_BAR; PG8_WAIT_L(0); PG8_MMA(0, 0, At, B0); PG8_BAR; PG8_SCHED;
;             PG8_LDB(B1, 1, 1); PG8_STAGE(PG8_SB(1, 0), b3, voffB);
	s_add_u32 s30, s18, 0x20000
	s_addc_u32 s31, s19, 0
	s_add_i32 s86, s86, s23
	v_lshl_add_u64 v[140:141], s[30:31], 0, v[134:135]
	s_mov_b32 m0, s86
	s_nop 0
	global_load_lds_dwordx4 v[140:141], off
	v_lshl_add_u64 v[140:141], s[30:31], 0, v[130:131]
	s_add_i32 m0, s86, 0x2000
	s_nop 0
	global_load_lds_dwordx4 v[140:141], off
	s_waitcnt vmcnt(6)
	s_barrier
	v_mfma_f32_16x16x32_bf16 v[54:57], v[202:205], v[162:165], v[54:57]
	v_mfma_f32_16x16x32_bf16 v[46:49], v[210:213], v[162:165], v[46:49]
	v_mfma_f32_16x16x32_bf16 v[38:41], v[202:205], v[170:173], v[38:41]
	v_mfma_f32_16x16x32_bf16 v[30:33], v[210:213], v[170:173], v[30:33]
	v_mfma_f32_16x16x32_bf16 v[22:25], v[202:205], v[186:189], v[22:25]
	v_mfma_f32_16x16x32_bf16 v[14:17], v[210:213], v[186:189], v[14:17]
	v_mfma_f32_16x16x32_bf16 v[6:9], v[202:205], v[194:197], v[6:9]
	v_mfma_f32_16x16x32_bf16 v[2:5], v[210:213], v[194:197], v[2:5]
	v_mfma_f32_16x16x32_bf16 v[54:57], v[206:209], v[166:169], v[54:57]
	v_mfma_f32_16x16x32_bf16 v[46:49], v[214:217], v[166:169], v[46:49]
	v_mfma_f32_16x16x32_bf16 v[38:41], v[206:209], v[182:185], v[38:41]
	v_mfma_f32_16x16x32_bf16 v[30:33], v[214:217], v[182:185], v[30:33]
	v_mfma_f32_16x16x32_bf16 v[22:25], v[206:209], v[190:193], v[22:25]
	v_mfma_f32_16x16x32_bf16 v[14:17], v[214:217], v[190:193], v[14:17]
	v_mfma_f32_16x16x32_bf16 v[6:9], v[206:209], v[198:201], v[6:9]
	v_mfma_f32_16x16x32_bf16 v[2:5], v[214:217], v[198:201], v[2:5]
	s_add_i32 s86, 0, 0x18000
	v_add_u32_e32 v158, s86, v147
	s_barrier
	ds_read_b128 v[140:143], v158
	ds_read_b128 v[150:153], v158 offset:1024
	ds_read_b128 v[154:157], v158 offset:2048
	ds_read_b128 v[158:161], v158 offset:3072
	s_add_u32 s30, s66, 0x80000
	s_addc_u32 s31, s67, 0
	s_mov_b32 m0, s26
	v_lshl_add_u64 v[202:203], s[30:31], 0, v[0:1]
	ds_read_b128 v[162:165], v149 offset:32768
	ds_read_b128 v[166:169], v149 offset:33792
	ds_read_b128 v[170:173], v149 offset:34816
	ds_read_b128 v[182:185], v149 offset:35840
	ds_read_b128 v[186:189], v149 offset:36864
	ds_read_b128 v[190:193], v149 offset:37888
	ds_read_b128 v[194:197], v149 offset:38912
	ds_read_b128 v[198:201], v149 offset:39936
	global_load_lds_dwordx4 v[202:203], off
	v_lshl_add_u64 v[202:203], s[30:31], 0, v[132:133]
	s_mov_b32 m0, s27
	s_nop 0
	global_load_lds_dwordx4 v[202:203], off
	s_waitcnt lgkmcnt(8)
	s_barrier
	s_waitcnt lgkmcnt(0)
	v_mfma_f32_16x16x32_bf16 v[126:129], v[140:143], v[162:165], v[126:129]
	v_mfma_f32_16x16x32_bf16 v[122:125], v[154:157], v[162:165], v[122:125]
	v_mfma_f32_16x16x32_bf16 v[114:117], v[140:143], v[170:173], v[114:117]
	v_mfma_f32_16x16x32_bf16 v[106:109], v[154:157], v[170:173], v[106:109]
	v_mfma_f32_16x16x32_bf16 v[98:101], v[140:143], v[186:189], v[98:101]
	v_mfma_f32_16x16x32_bf16 v[90:93], v[154:157], v[186:189], v[90:93]
	v_mfma_f32_16x16x32_bf16 v[82:85], v[140:143], v[194:197], v[82:85]
	v_mfma_f32_16x16x32_bf16 v[74:77], v[154:157], v[194:197], v[74:77]
	v_mfma_f32_16x16x32_bf16 v[126:129], v[150:153], v[166:169], v[126:129]
	v_mfma_f32_16x16x32_bf16 v[122:125], v[158:161], v[166:169], v[122:125]
	v_mfma_f32_16x16x32_bf16 v[114:117], v[150:153], v[182:185], v[114:117]
	v_mfma_f32_16x16x32_bf16 v[106:109], v[158:161], v[182:185], v[106:109]
	v_mfma_f32_16x16x32_bf16 v[98:101], v[150:153], v[190:193], v[98:101]
	v_mfma_f32_16x16x32_bf16 v[90:93], v[158:161], v[190:193], v[90:93]
	v_mfma_f32_16x16x32_bf16 v[82:85], v[150:153], v[198:201], v[82:85]
	v_mfma_f32_16x16x32_bf16 v[74:77], v[158:161], v[198:201], v[74:77]
	s_barrier
	s_add_i32 s30, 0, 0x1c000
	s_add_i32 s31, s86, s23
	v_add_u32_e32 v214, s30, v147
	v_lshl_add_u64 v[144:145], v[144:145], 0, s[56:57]
	s_mov_b32 m0, s31
	ds_read_b128 v[202:205], v214
	ds_read_b128 v[206:209], v214 offset:1024
	ds_read_b128 v[210:213], v214 offset:2048
	ds_read_b128 v[214:217], v214 offset:3072
	global_load_lds_dwordx4 v[144:145], off
	v_lshl_add_u64 v[144:145], v[174:175], 0, s[56:57]
	s_add_i32 m0, s31, 0x2000
	s_nop 0
	global_load_lds_dwordx4 v[144:145], off
	s_barrier
; #define PG8_STAGE(bufoff, gbase, voff) do { _Pragma("unroll") for (int _i = 0; _i < 2; ++_i) \
;         __builtin_amdgcn_global_load_lds((const unsigned*)((const char*)(gbase) + (voff)[_i]), (PG8_LAS unsigned*)(lds + (bufoff) + ldsw + _i * 8192), 16, 0, 0); } while (0)
; #define PG8_LDA(dst, b, h) do { _Pragma("unroll") for (int m = 0; m < 4; ++m) _Pragma("unroll") for (int k = 0; k < 2; ++k) dst[m][k] = *(const PG8_LAS bf16x8*)(lds + PG8_SA(b, h) + aoff + m * 2048 + k * 1024); } while (0)
; #define PG8_WAIT_V(n) asm volatile("s_waitcnt vmcnt(" #n ")" ::: "memory")
; #define PG8_WAIT_L(n) asm volatile("s_waitcnt lgkmcnt(" #n ")" ::: "memory")
; #define PG8_BAR __builtin_amdgcn_s_barrier()
; #define PG8_SCHED __builtin_amdgcn_sched_barrier(0)
; template <bool FP8, class Epi, class Sched>
; __device__ __forceinline__ void gemm_phase(PG8_LAS unsigned char* lds, const Gemm g, const Sched& S, const Epi& E) {
;     ...
;             PG8_BAR; PG8_WAIT_L(0); PG8_MMA(0, 1, At, B1); PG8_BAR;
;             PG8_LDA(At, 1, 1); PG8_STAGE(PG8_SA(1, 0), a3, voffA);
;             PG8_BAR; PG8_WAIT_L(0); PG8_MMA(1, 0, At, B0); PG8_BAR; PG8_SCHED;
;             PG8_STAGE(PG8_SB(1, 1), b3 + hstep, voffB);
;             PG8_WAIT_V(6); PG8_BAR; PG8_MMA(1, 1, At, B1); PG8_BAR;
;         }
;         if constexpr (FP8) asm volatile("s_nop 15\n\ts_nop 15" ::: "memory");
;         if constexpr (!Epi::AFTER_DRAIN) { E(acc, cur, wr, wc, fr, fq); S.done(cur); }
;   DI void operator()(const f32x4 (&acc)[2][2][4][2], const pg8::Unit& u, int wr, int wc, int fr, int fq) const {
;     ...
;           if (MODE == 0) { if (col < N) dst = d0 + (size_t)row * ld0 + (col + coff2 + ((col < csplit) ? (coff1 - coff2) : 0)); }
;     ...
;           if (dst) { u32x4 w = {pk2(v0[0], v0[1]), pk2(v0[2], v0[3]), pk2(v1[0], v1[1]), pk2(v1[2], v1[3])}; *(u32x4*)dst = w; }
	s_waitcnt lgkmcnt(0)
	v_mfma_f32_16x16x32_bf16 v[118:121], v[202:205], v[162:165], v[118:121]
	v_mfma_f32_16x16x32_bf16 v[110:113], v[210:213], v[162:165], v[110:113]
	v_mfma_f32_16x16x32_bf16 v[102:105], v[202:205], v[170:173], v[102:105]
	v_mfma_f32_16x16x32_bf16 v[94:97], v[210:213], v[170:173], v[94:97]
	v_mfma_f32_16x16x32_bf16 v[86:89], v[202:205], v[186:189], v[86:89]
	v_mfma_f32_16x16x32_bf16 v[78:81], v[210:213], v[186:189], v[78:81]
	v_mfma_f32_16x16x32_bf16 v[70:73], v[202:205], v[194:197], v[70:73]
	v_mfma_f32_16x16x32_bf16 v[66:69], v[210:213], v[194:197], v[66:69]
	v_mfma_f32_16x16x32_bf16 v[118:121], v[206:209], v[166:169], v[118:121]
	v_mfma_f32_16x16x32_bf16 v[110:113], v[214:217], v[166:169], v[110:113]
	v_mfma_f32_16x16x32_bf16 v[102:105], v[206:209], v[182:185], v[102:105]
	v_mfma_f32_16x16x32_bf16 v[94:97], v[214:217], v[182:185], v[94:97]
	v_mfma_f32_16x16x32_bf16 v[86:89], v[206:209], v[190:193], v[86:89]
	v_mfma_f32_16x16x32_bf16 v[78:81], v[214:217], v[190:193], v[78:81]
	v_mfma_f32_16x16x32_bf16 v[70:73], v[206:209], v[198:201], v[70:73]
	v_mfma_f32_16x16x32_bf16 v[66:69], v[214:217], v[198:201], v[66:69]
	s_mov_b32 m0, s28
	v_lshl_add_u64 v[144:145], v[236:237], 0, s[56:57]
	s_barrier
	ds_read_b128 v[162:165], v149 offset:49152
	ds_read_b128 v[166:169], v149 offset:50176
	ds_read_b128 v[170:173], v149 offset:51200
	ds_read_b128 v[182:185], v149 offset:52224
	ds_read_b128 v[186:189], v149 offset:53248
	ds_read_b128 v[190:193], v149 offset:54272
	ds_read_b128 v[194:197], v149 offset:55296
	ds_read_b128 v[198:201], v149 offset:56320
	global_load_lds_dwordx4 v[144:145], off
	v_lshl_add_u64 v[144:145], v[238:239], 0, s[56:57]
	s_mov_b32 m0, s29
	s_nop 0
	global_load_lds_dwordx4 v[144:145], off
	s_barrier
	s_waitcnt lgkmcnt(0)
	v_mfma_f32_16x16x32_bf16 v[62:65], v[140:143], v[162:165], v[62:65]
	v_mfma_f32_16x16x32_bf16 v[58:61], v[154:157], v[162:165], v[58:61]
	v_mfma_f32_16x16x32_bf16 v[50:53], v[140:143], v[170:173], v[50:53]
	v_mfma_f32_16x16x32_bf16 v[42:45], v[154:157], v[170:173], v[42:45]
	v_mfma_f32_16x16x32_bf16 v[34:37], v[140:143], v[186:189], v[34:37]
	v_mfma_f32_16x16x32_bf16 v[26:29], v[154:157], v[186:189], v[26:29]
	v_mfma_f32_16x16x32_bf16 v[18:21], v[140:143], v[194:197], v[18:21]
	v_mfma_f32_16x16x32_bf16 v[10:13], v[154:157], v[194:197], v[10:13]
	v_mfma_f32_16x16x32_bf16 v[62:65], v[150:153], v[166:169], v[62:65]
	v_mfma_f32_16x16x32_bf16 v[58:61], v[158:161], v[166:169], v[58:61]
	v_mfma_f32_16x16x32_bf16 v[50:53], v[150:153], v[182:185], v[50:53]
	v_mfma_f32_16x16x32_bf16 v[42:45], v[158:161], v[182:185], v[42:45]
	v_mfma_f32_16x16x32_bf16 v[34:37], v[150:153], v[190:193], v[34:37]
	v_mfma_f32_16x16x32_bf16 v[26:29], v[158:161], v[190:193], v[26:29]
	v_mfma_f32_16x16x32_bf16 v[18:21], v[150:153], v[198:201], v[18:21]
	v_mfma_f32_16x16x32_bf16 v[10:13], v[158:161], v[198:201], v[10:13]
	s_barrier
	s_add_u32 s18, s18, 0x20080
	s_addc_u32 s19, s19, 0
	s_add_i32 s30, s30, s23
	v_lshl_add_u64 v[140:141], s[18:19], 0, v[134:135]
	s_mov_b32 m0, s30
	s_nop 0
	global_load_lds_dwordx4 v[140:141], off
	v_lshl_add_u64 v[140:141], s[18:19], 0, v[130:131]
	s_add_i32 m0, s30, 0x2000
	s_nop 0
	global_load_lds_dwordx4 v[140:141], off
	s_waitcnt vmcnt(6)
	s_barrier
	v_mfma_f32_16x16x32_bf16 v[54:57], v[202:205], v[162:165], v[54:57]
	v_mfma_f32_16x16x32_bf16 v[46:49], v[210:213], v[162:165], v[46:49]
	v_mfma_f32_16x16x32_bf16 v[38:41], v[202:205], v[170:173], v[38:41]
	v_mfma_f32_16x16x32_bf16 v[30:33], v[210:213], v[170:173], v[30:33]
	v_mfma_f32_16x16x32_bf16 v[22:25], v[202:205], v[186:189], v[22:25]
	v_mfma_f32_16x16x32_bf16 v[14:17], v[210:213], v[186:189], v[14:17]
	v_mfma_f32_16x16x32_bf16 v[6:9], v[202:205], v[194:197], v[6:9]
	v_mfma_f32_16x16x32_bf16 v[2:5], v[210:213], v[194:197], v[2:5]
	v_mfma_f32_16x16x32_bf16 v[54:57], v[206:209], v[166:169], v[54:57]
	v_mfma_f32_16x16x32_bf16 v[46:49], v[214:217], v[166:169], v[46:49]
	v_mfma_f32_16x16x32_bf16 v[38:41], v[206:209], v[182:185], v[38:41]
	v_mfma_f32_16x16x32_bf16 v[30:33], v[214:217], v[182:185], v[30:33]
	v_mfma_f32_16x16x32_bf16 v[22:25], v[206:209], v[190:193], v[22:25]
	v_mfma_f32_16x16x32_bf16 v[14:17], v[214:217], v[190:193], v[14:17]
	v_mfma_f32_16x16x32_bf16 v[6:9], v[206:209], v[198:201], v[6:9]
	v_mfma_f32_16x16x32_bf16 v[2:5], v[214:217], v[198:201], v[2:5]
	s_add_i32 s87, s87, 2
	s_add_u32 s0, s0, 0x100
	s_addc_u32 s1, s1, 0
	s_add_u32 s72, s72, 0x100
	s_addc_u32 s73, s73, 0
	s_cmp_gt_u32 s87, 5
	s_barrier
	s_cbranch_scc0 .LBB0_1138
	v_lshl_add_u32 v142, s69, 8, v146
	v_ashrrev_i32_e32 v143, 31, v142
	v_lshl_or_b32 v140, s68, 8, v148
	s_movk_i32 s0, 0x1000
	v_lshlrev_b64 v[144:145], 13, v[142:143]
	v_cmp_gt_i32_e32 vcc, s0, v140
	v_ashrrev_i32_e32 v141, 31, v140
	v_lshl_add_u64 v[144:145], s[90:91], 0, v[144:145]
	s_and_saveexec_b64 s[0:1], vcc
	s_cbranch_execz .LBB0_1141
	v_lshl_add_u64 v[150:151], v[140:141], 1, v[144:145]
	v_cvt_pk_bf16_f32 v126, v126, v127
	v_cvt_pk_bf16_f32 v127, v128, v129
	v_cvt_pk_bf16_f32 v128, v122, v123
	v_cvt_pk_bf16_f32 v129, v124, v125
	global_store_dwordx4 v[150:151], v[126:129], off

; DI int crow(int reg, int hi) { return (reg & 3) + 8 * (reg >> 2) + 4 * hi; }
; template <int DQK, int W1, int DV, int VW, int MODE> ...
;     ...
;       s[0] = s_block<KSTR, ND, 0>(bufa + klane, qf, negm);
;       s[1] = s_block<KSTR, ND, 1>(bufa + klane, qf, negm);
;       if (MODE == 0) {
;         if (__builtin_amdgcn_readfirstlane((int)(kb + 63 > tq0))) {
; #pragma unroll
;           for (int n = 0; n < 2; ++n)
; #pragma unroll
;             for (int i = 0; i < 16; ++i) { const int key = kb + 32 * n + crow(i, hi); if (key > tq) s[n][i] = NEGV; }
;         }
;       } else if (MODE == 1) {
;         const bool far = (tq0 - (kb + 63)) >= 128;
; #pragma unroll
;         for (int n = 0; n < 2; ++n) {
;           const unsigned wb = (n ? mw1 : mw0) >> (4 * hi);
;           if (far) {
; #pragma unroll
;             for (int i = 0; i < 16; ++i) {
;               const float v = fmaf(s[n][i], c2, bias_far);
;               s[n][i] = ((wb >> ((i & 3) + 8 * (i >> 2))) & 1u) ? v : NEGV;
;             }
;           } else {
; #pragma unroll
;             for (int i = 0; i < 16; ++i) {
;               const int key = kb + 32 * n + crow(i, hi);
;               int rel = tq - key; rel = rel < 0 ? 0 : (rel > 128 ? 128 : rel);
;               const float v = fmaf(s[n][i], c2, lutw[rel]);
;               s[n][i] = ((wb >> ((i & 3) + 8 * (i >> 2))) & 1u) ? v : NEGV;
;             }
;           }
;         }
;       } else if (MODE == 2) {
; #pragma unroll
;         for (int n = 0; n < 2; ++n)
; #pragma unroll
;           for (int i = 0; i < 16; ++i) {
;             const int key = kb + 32 * n + crow(i, hi), rel = tq - key;
;             const bool ok = ((unsigned)rel < 128u) && (key >= 0);
;             const float v = fmaf(s[n][i], c2, lutw[rel & 127]);
;             s[n][i] = ok ? v : NEGV;
;           }
.LBB0_1307:
	v_and_b32_e32 v2, 31, v105
	v_mul_u32_u24_e32 v2, 0x90, v2
	s_cmp_lg_u32 0, -1
	v_lshl_add_u32 v109, v3, 4, v2
	s_cselect_b32 s31, 0, 0
	v_add_u32_e32 v106, s31, v109
	ds_read_b128 v[4:7], v106 offset:0
	ds_read_b128 v[8:11], v106 offset:32
	ds_read_b128 v[12:15], v106 offset:64
	ds_read_b128 v[36:39], v106 offset:0x60
	s_waitcnt lgkmcnt(0)
	v_lshlrev_b32_e32 v82, 2, v3
	v_mfma_f32_32x32x16_bf16 v[18:33], v[4:7], v[78:81], 0
	v_lshlrev_b32_e32 v4, 3, v105
	v_lshlrev_b32_e32 v2, 1, v105
	v_lshrrev_b32_e32 v3, 2, v105
	v_and_b32_e32 v4, 24, v4
	v_or_b32_e32 v5, s73, v82
	v_or_b32_e32 v103, 1, v82
	v_and_or_b32 v3, v3, 3, v82
	v_mfma_f32_32x32x16_bf16 v[18:33], v[8:11], v[74:77], v[18:33]
	v_and_or_b32 v2, v2, 32, v4
	v_sub_u32_e32 v4, v0, v5
	v_or_b32_e32 v5, s73, v103
	v_lshlrev_b32_e32 v3, 6, v3
	s_movk_i32 s36, 0x2400
	v_sub_u32_e32 v48, v0, v5
	v_or3_b32 v107, v3, v2, s36
	v_mfma_f32_32x32x16_bf16 v[18:33], v[12:15], v[70:73], v[18:33]
	s_movk_i32 s3, 0x80
	v_and_b32_e32 v2, 0x7f, v4
	v_and_b32_e32 v6, 0x7f, v48
	v_or_b32_e32 v88, 2, v82
	v_cmp_gt_u32_e32 vcc, s3, v4
	v_lshl_add_u32 v49, v2, 2, s27
	v_lshl_add_u32 v50, v6, 2, s27
	v_mfma_f32_32x32x16_bf16 v[18:33], v[36:39], v[66:69], v[18:33]
	ds_read_b128 v[2:5], v106 offset:0x1200
	ds_read_b128 v[36:39], v106 offset:0x1220
	ds_read_b128 v[40:43], v106 offset:0x1240
	ds_read_b128 v[44:47], v106 offset:0x1260
	s_waitcnt lgkmcnt(0)
	v_or_b32_e32 v6, s73, v88
	v_sub_u32_e32 v51, v0, v6
	v_or_b32_e32 v89, 9, v82
	v_or_b32_e32 v90, 8, v82
	v_or_b32_e32 v91, 11, v82
	v_or_b32_e32 v92, 10, v82
	v_mfma_f32_32x32x16_bf16 v[2:17], v[2:5], v[78:81], 0
	v_or_b32_e32 v83, 3, v82
	v_or_b32_e32 v53, s73, v83
	v_sub_u32_e32 v53, v0, v53
	s_cmp_gt_i32 s73, -1
	v_and_b32_e32 v52, 0x7f, v51
	v_and_b32_e32 v54, 0x7f, v53
	s_cselect_b64 s[0:1], -1, 0
	v_mfma_f32_32x32x16_bf16 v[2:17], v[36:39], v[74:77], v[2:17]
	v_or_b32_e32 v36, s73, v90
	v_or_b32_e32 v38, s73, v89
	v_sub_u32_e32 v36, v0, v36
	v_sub_u32_e32 v38, v0, v38
	v_and_b32_e32 v37, 0x7f, v36
	v_and_b32_e32 v39, 0x7f, v38
	v_lshl_add_u32 v37, v37, 2, s27
	v_mfma_f32_32x32x16_bf16 v[2:17], v[40:43], v[70:73], v[2:17]
	v_or_b32_e32 v40, s73, v92
	v_or_b32_e32 v42, s73, v91
	v_sub_u32_e32 v40, v0, v40
	v_sub_u32_e32 v42, v0, v42
	v_and_b32_e32 v41, 0x7f, v40
	v_and_b32_e32 v43, 0x7f, v42
	v_lshl_add_u32 v39, v39, 2, s27
	v_lshl_add_u32 v41, v41, 2, s27
	v_lshl_add_u32 v43, v43, 2, s27
	v_lshl_add_u32 v52, v52, 2, s27
	v_lshl_add_u32 v54, v54, 2, s27
	v_mfma_f32_32x32x16_bf16 v[2:17], v[44:47], v[66:69], v[2:17]
	ds_read_b32 v44, v49
	ds_read_b32 v45, v50
	ds_read_b32 v46, v52
	ds_read_b32 v47, v54
	ds_read_b32 v37, v37
	ds_read_b32 v39, v39
	ds_read_b32 v41, v41
	ds_read_b32 v43, v43
	s_waitcnt lgkmcnt(0)
	v_fmac_f32_e32 v44, 0x3e38aa3b, v18
	s_and_b64 vcc, s[0:1], vcc
	v_cndmask_b32_e32 v18, v232, v44, vcc
	v_cmp_gt_u32_e32 vcc, s3, v48
	v_fmac_f32_e32 v45, 0x3e38aa3b, v19
	s_and_b64 vcc, s[0:1], vcc
	v_cndmask_b32_e32 v19, v232, v45, vcc
	v_cmp_gt_u32_e32 vcc, s3, v51
	v_fmac_f32_e32 v46, 0x3e38aa3b, v20
	s_and_b64 vcc, s[0:1], vcc
	v_cndmask_b32_e32 v20, v232, v46, vcc
	v_cmp_gt_u32_e32 vcc, s3, v53
	v_fmac_f32_e32 v47, 0x3e38aa3b, v21
	s_and_b64 vcc, s[0:1], vcc
	v_cndmask_b32_e32 v21, v232, v47, vcc
	v_cmp_gt_u32_e32 vcc, s3, v36
	v_fmac_f32_e32 v37, 0x3e38aa3b, v22
	s_and_b64 vcc, s[0:1], vcc
	v_cndmask_b32_e32 v22, v232, v37, vcc
	v_cmp_gt_u32_e32 vcc, s3, v38
	v_fmac_f32_e32 v39, 0x3e38aa3b, v23
	s_and_b64 vcc, s[0:1], vcc
	v_cndmask_b32_e32 v23, v232, v39, vcc
	v_cmp_gt_u32_e32 vcc, s3, v40
	v_fmac_f32_e32 v41, 0x3e38aa3b, v24
	s_and_b64 vcc, s[0:1], vcc
	v_cndmask_b32_e32 v24, v232, v41, vcc
	v_cmp_gt_u32_e32 vcc, s3, v42
	v_fmac_f32_e32 v43, 0x3e38aa3b, v25
	s_and_b64 vcc, s[0:1], vcc
	v_or_b32_e32 v93, 17, v82
	v_or_b32_e32 v94, 16, v82
	v_or_b32_e32 v95, 19, v82
	v_or_b32_e32 v96, 18, v82
	v_or_b32_e32 v97, 25, v82
	v_or_b32_e32 v98, 24, v82
	v_or_b32_e32 v99, 27, v82
	v_or_b32_e32 v100, 26, v82
	v_cndmask_b32_e32 v25, v232, v43, vcc
	v_or_b32_e32 v36, s73, v94
	v_or_b32_e32 v37, s73, v93
	v_or_b32_e32 v39, s73, v96
	v_or_b32_e32 v41, s73, v95
	v_or_b32_e32 v43, s73, v98
	v_or_b32_e32 v45, s73, v97
	v_or_b32_e32 v47, s73, v100
	v_or_b32_e32 v49, s73, v99
	v_sub_u32_e32 v36, v0, v36
	v_sub_u32_e32 v37, v0, v37
	v_sub_u32_e32 v39, v0, v39
	v_sub_u32_e32 v41, v0, v41
	v_sub_u32_e32 v43, v0, v43
	v_sub_u32_e32 v45, v0, v45
	v_sub_u32_e32 v47, v0, v47
	v_sub_u32_e32 v49, v0, v49
	v_cmp_gt_u32_e32 vcc, s3, v36
	v_and_b32_e32 v36, 0x7f, v36
	v_and_b32_e32 v38, 0x7f, v37
	v_and_b32_e32 v40, 0x7f, v39
	v_and_b32_e32 v42, 0x7f, v41
	v_and_b32_e32 v44, 0x7f, v43
	v_and_b32_e32 v46, 0x7f, v45
	v_and_b32_e32 v48, 0x7f, v47
	v_and_b32_e32 v50, 0x7f, v49
	v_lshl_add_u32 v36, v36, 2, s27
	v_lshl_add_u32 v38, v38, 2, s27
	v_lshl_add_u32 v40, v40, 2, s27
	v_lshl_add_u32 v42, v42, 2, s27
	v_lshl_add_u32 v44, v44, 2, s27
	v_lshl_add_u32 v46, v46, 2, s27
	v_lshl_add_u32 v48, v48, 2, s27
	v_lshl_add_u32 v50, v50, 2, s27
	ds_read_b32 v36, v36
	ds_read_b32 v38, v38
	ds_read_b32 v40, v40
	ds_read_b32 v42, v42
	ds_read_b32 v44, v44
	ds_read_b32 v46, v46
	ds_read_b32 v48, v48
	ds_read_b32 v50, v50
	s_waitcnt lgkmcnt(0)
; DI int crow(int reg, int hi) { return (reg & 3) + 8 * (reg >> 2) + 4 * hi; }
; template <int DQK, int W1, int DV, int VW, int MODE> ...
;     ...
;             for (int i = 0; i < 16; ++i) {
;               const int key = kb + 32 * n + crow(i, hi);
;               int rel = tq - key; rel = rel < 0 ? 0 : (rel > 128 ? 128 : rel);
;               const float v = fmaf(s[n][i], c2, lutw[rel]);
;               s[n][i] = ((wb >> ((i & 3) + 8 * (i >> 2))) & 1u) ? v : NEGV;
;             }
;           }
;         }
;       } else if (MODE == 2) {
; #pragma unroll
;         for (int n = 0; n < 2; ++n)
; #pragma unroll
;           for (int i = 0; i < 16; ++i) {
;             const int key = kb + 32 * n + crow(i, hi), rel = tq - key;
;             const bool ok = ((unsigned)rel < 128u) && (key >= 0);
;             const float v = fmaf(s[n][i], c2, lutw[rel & 127]);
;             s[n][i] = ok ? v : NEGV;
;           }
	v_fmac_f32_e32 v36, 0x3e38aa3b, v26
	s_and_b64 vcc, s[0:1], vcc
	v_cndmask_b32_e32 v26, v232, v36, vcc
	v_cmp_gt_u32_e32 vcc, s3, v37
	v_fmac_f32_e32 v38, 0x3e38aa3b, v27
	s_and_b64 vcc, s[0:1], vcc
	v_cndmask_b32_e32 v27, v232, v38, vcc
	v_cmp_gt_u32_e32 vcc, s3, v39
	v_fmac_f32_e32 v40, 0x3e38aa3b, v28
	s_and_b64 vcc, s[0:1], vcc
	v_cndmask_b32_e32 v28, v232, v40, vcc
	v_cmp_gt_u32_e32 vcc, s3, v41
	v_fmac_f32_e32 v42, 0x3e38aa3b, v29
	s_and_b64 vcc, s[0:1], vcc
	v_cndmask_b32_e32 v29, v232, v42, vcc
	v_cmp_gt_u32_e32 vcc, s3, v43
	v_fmac_f32_e32 v44, 0x3e38aa3b, v30
	s_and_b64 vcc, s[0:1], vcc
	v_cndmask_b32_e32 v30, v232, v44, vcc
	v_cmp_gt_u32_e32 vcc, s3, v45
	v_fmac_f32_e32 v46, 0x3e38aa3b, v31
	s_and_b64 vcc, s[0:1], vcc
	v_cndmask_b32_e32 v31, v232, v46, vcc
	v_cmp_gt_u32_e32 vcc, s3, v47
	v_fmac_f32_e32 v48, 0x3e38aa3b, v32
	s_and_b64 vcc, s[0:1], vcc
	s_add_i32 s73, s28, 0x780
	v_cndmask_b32_e32 v32, v232, v48, vcc
	v_cmp_gt_u32_e32 vcc, s3, v49
	v_or_b32_e32 v36, s73, v82
	v_or_b32_e32 v37, s73, v103
	v_or_b32_e32 v39, s73, v88
	v_or_b32_e32 v41, s73, v83
	v_or_b32_e32 v43, s73, v90
	v_or_b32_e32 v45, s73, v89
	v_or_b32_e32 v47, s73, v92
	v_or_b32_e32 v49, s73, v91
	v_fmac_f32_e32 v50, 0x3e38aa3b, v33
	s_and_b64 vcc, s[0:1], vcc
	v_sub_u32_e32 v36, v0, v36
	v_sub_u32_e32 v37, v0, v37
	v_sub_u32_e32 v39, v0, v39
	v_sub_u32_e32 v41, v0, v41
	v_sub_u32_e32 v43, v0, v43
	v_sub_u32_e32 v45, v0, v45
	v_sub_u32_e32 v47, v0, v47
	v_sub_u32_e32 v49, v0, v49
	v_cndmask_b32_e32 v33, v232, v50, vcc
	v_cmp_gt_u32_e32 vcc, s3, v36
	v_and_b32_e32 v36, 0x7f, v36
	v_and_b32_e32 v38, 0x7f, v37
	v_and_b32_e32 v40, 0x7f, v39
	v_and_b32_e32 v42, 0x7f, v41
	v_and_b32_e32 v44, 0x7f, v43
	v_and_b32_e32 v46, 0x7f, v45
	v_and_b32_e32 v48, 0x7f, v47
	v_and_b32_e32 v50, 0x7f, v49
	s_cmp_gt_i32 s73, -1
	v_lshl_add_u32 v36, v36, 2, s27
	v_lshl_add_u32 v38, v38, 2, s27
	v_lshl_add_u32 v40, v40, 2, s27
	v_lshl_add_u32 v42, v42, 2, s27
	v_lshl_add_u32 v44, v44, 2, s27
	v_lshl_add_u32 v46, v46, 2, s27
	v_lshl_add_u32 v48, v48, 2, s27
	v_lshl_add_u32 v50, v50, 2, s27
	s_cselect_b64 s[0:1], -1, 0
	ds_read_b32 v36, v36
	ds_read_b32 v38, v38
	ds_read_b32 v40, v40
	ds_read_b32 v42, v42
	ds_read_b32 v44, v44
	ds_read_b32 v46, v46
	ds_read_b32 v48, v48
	ds_read_b32 v50, v50
	s_waitcnt lgkmcnt(0)
	v_fmac_f32_e32 v36, 0x3e38aa3b, v2
	s_and_b64 vcc, s[0:1], vcc
	v_cndmask_b32_e32 v36, v232, v36, vcc
	v_cmp_gt_u32_e32 vcc, s3, v37
	v_fmac_f32_e32 v38, 0x3e38aa3b, v3
	s_and_b64 vcc, s[0:1], vcc
	v_cndmask_b32_e32 v37, v232, v38, vcc
	v_cmp_gt_u32_e32 vcc, s3, v39
	v_fmac_f32_e32 v40, 0x3e38aa3b, v4
	s_and_b64 vcc, s[0:1], vcc
	v_cndmask_b32_e32 v38, v232, v40, vcc
	v_cmp_gt_u32_e32 vcc, s3, v41
	v_fmac_f32_e32 v42, 0x3e38aa3b, v5
	s_and_b64 vcc, s[0:1], vcc
	v_cndmask_b32_e32 v39, v232, v42, vcc
	v_cmp_gt_u32_e32 vcc, s3, v43
	v_fmac_f32_e32 v44, 0x3e38aa3b, v6
	s_and_b64 vcc, s[0:1], vcc
	v_cndmask_b32_e32 v40, v232, v44, vcc
	v_cmp_gt_u32_e32 vcc, s3, v45
	v_fmac_f32_e32 v46, 0x3e38aa3b, v7
	s_and_b64 vcc, s[0:1], vcc
	v_cndmask_b32_e32 v41, v232, v46, vcc
	v_cmp_gt_u32_e32 vcc, s3, v47
	v_fmac_f32_e32 v48, 0x3e38aa3b, v8
	s_and_b64 vcc, s[0:1], vcc
	v_cndmask_b32_e32 v42, v232, v48, vcc
	v_cmp_gt_u32_e32 vcc, s3, v49
	v_or_b32_e32 v2, s73, v94
	v_or_b32_e32 v3, s73, v93
	v_or_b32_e32 v5, s73, v96
	v_or_b32_e32 v7, s73, v95
	v_fmac_f32_e32 v50, 0x3e38aa3b, v9
	s_and_b64 vcc, s[0:1], vcc
	v_sub_u32_e32 v2, v0, v2
	v_sub_u32_e32 v3, v0, v3
	v_sub_u32_e32 v5, v0, v5
	v_sub_u32_e32 v7, v0, v7
	v_or_b32_e32 v9, s73, v98
	v_or_b32_e32 v45, s73, v97
	v_or_b32_e32 v46, s73, v100
	v_or_b32_e32 v47, s73, v99
	v_cndmask_b32_e32 v43, v232, v50, vcc
	v_cmp_gt_u32_e32 vcc, s3, v2
	v_and_b32_e32 v2, 0x7f, v2
	v_and_b32_e32 v4, 0x7f, v3
	v_and_b32_e32 v6, 0x7f, v5
	v_and_b32_e32 v8, 0x7f, v7
	v_sub_u32_e32 v9, v0, v9
	v_sub_u32_e32 v49, v0, v45
	v_sub_u32_e32 v50, v0, v46
	v_sub_u32_e32 v51, v0, v47
	v_lshl_add_u32 v2, v2, 2, s27
	v_lshl_add_u32 v4, v4, 2, s27
	v_lshl_add_u32 v6, v6, 2, s27
	v_lshl_add_u32 v8, v8, 2, s27
	v_and_b32_e32 v44, 0x7f, v9
	v_and_b32_e32 v45, 0x7f, v49
	v_and_b32_e32 v46, 0x7f, v50
	v_and_b32_e32 v47, 0x7f, v51
	v_lshl_add_u32 v44, v44, 2, s27
	v_lshl_add_u32 v45, v45, 2, s27
	v_lshl_add_u32 v46, v46, 2, s27
	v_lshl_add_u32 v47, v47, 2, s27
	ds_read_b32 v2, v2
	ds_read_b32 v4, v4
	ds_read_b32 v6, v6
	ds_read_b32 v8, v8
	ds_read_b32 v48, v44
	ds_read_b32 v52, v45
	ds_read_b32 v53, v46
	ds_read_b32 v54, v47
	s_waitcnt lgkmcnt(0)
; template <int DQK, int W1, int DV, int VW, int MODE> ...
;     ...
;       float mx = s[0][0];
; #pragma unroll
;       for (int i = 1; i < 16; ++i) mx = fmaxf(mx, s[0][i]);
; #pragma unroll
;       for (int i = 0; i < 16; ++i) mx = fmaxf(mx, s[1][i]);
;       mx = xhalf_max(mx);
;       if (MODE == 0) {
;         if (t == 0) {
;           m = mx;
;           s[0] = s[0] - mx; s[1] = s[1] - mx; negm = negm - mx;
;         } else if (__any(mx > 8.0f)) {
;           const float d = fmaxf(mx, 0.f), alpha = __builtin_amdgcn_exp2f(-d);
;           m += d; l *= alpha;
;           s[0] = s[0] - d; s[1] = s[1] - d; negm = negm - d;
; #pragma unroll
;           for (int cb = 0; cb < NCB; ++cb)
; #pragma unroll
;             for (int r = 0; r < 16; ++r) o[cb][r] *= alpha;
;         }
;       } else if (__any(mx - m > 8.0f)) {
;         const float mnew = fmaxf(m, mx), alpha = __builtin_amdgcn_exp2f(m - mnew);
;         m = mnew; l *= alpha;
; #pragma unroll
;         for (int cb = 0; cb < NCB; ++cb)
; #pragma unroll
;           for (int r = 0; r < 16; ++r) o[cb][r] *= alpha;
;       }
;       {
;         f32x16 e0 = s[0], e1 = s[1];
;         if (MODE != 0) { const float nm = -m; e0 = e0 + nm; e1 = e1 + nm; }
; #pragma unroll
;         for (int i = 0; i < 16; ++i) { e0[i] = __builtin_amdgcn_exp2f(e0[i]); e1[i] = __builtin_amdgcn_exp2f(e1[i]); }
;         s[0] = e0; s[1] = e1;
;         const f32x16 sm = e0 + e1;
;         typedef __attribute__((ext_vector_type(8))) float f32x8;
;         const f32x8 h8 = sm.lo + sm.hi;
;         const f32x4 h4 = h8.lo + h8.hi;
;         const f32x2 h2 = h4.lo + h4.hi;
;         l += h2[0] + h2[1];
;       }
;       bf16x8 pb[2][2];
; #pragma unroll
;       for (int n = 0; n < 2; ++n)
; #pragma unroll
;         for (int s2 = 0; s2 < 2; ++s2) {
;           u32x4 pw = {pk2(s[n][8 * s2 + 0], s[n][8 * s2 + 1]), pk2(s[n][8 * s2 + 2], s[n][8 * s2 + 3]),
;                       pk2(s[n][8 * s2 + 4], s[n][8 * s2 + 5]), pk2(s[n][8 * s2 + 6], s[n][8 * s2 + 7])};
;           pb[n][s2] = __builtin_bit_cast(bf16x8, pw);
;         }
;       pv_block<0>(o[0], bufa + vlane, pb);
;       if constexpr (NCB > 1) pv_block<1>(o[1], bufa + vlane, pb);
;       if constexpr (NCB > 2) pv_block<2>(o[2], bufa + vlane, pb);
;       if constexpr (NCB > 3) pv_block<3>(o[3], bufa + vlane, pb);
;     }
;     asm volatile("s_waitcnt vmcnt(0)" ::: "memory");
	v_fmac_f32_e32 v2, 0x3e38aa3b, v10
	s_and_b64 vcc, s[0:1], vcc
	v_cndmask_b32_e32 v44, v232, v2, vcc
	v_cmp_gt_u32_e32 vcc, s3, v3
	v_max_f32_e32 v2, v18, v19
	v_fmac_f32_e32 v4, 0x3e38aa3b, v11
	s_and_b64 vcc, s[0:1], vcc
	v_max3_f32 v2, v2, v20, v21
	v_cndmask_b32_e32 v45, v232, v4, vcc
	v_cmp_gt_u32_e32 vcc, s3, v5
	v_max3_f32 v2, v2, v22, v23
	v_fmac_f32_e32 v6, 0x3e38aa3b, v12
	s_and_b64 vcc, s[0:1], vcc
	v_max3_f32 v2, v2, v24, v25
	v_cndmask_b32_e32 v46, v232, v6, vcc
	v_cmp_gt_u32_e32 vcc, s3, v7
	v_max3_f32 v2, v2, v26, v27
	v_fmac_f32_e32 v8, 0x3e38aa3b, v13
	s_and_b64 vcc, s[0:1], vcc
	v_max3_f32 v2, v2, v28, v29
	v_cndmask_b32_e32 v47, v232, v8, vcc
	v_cmp_gt_u32_e32 vcc, s3, v9
	v_max3_f32 v2, v2, v30, v31
	v_fmac_f32_e32 v48, 0x3e38aa3b, v14
	s_and_b64 vcc, s[0:1], vcc
	v_max3_f32 v2, v2, v32, v33
	v_cndmask_b32_e32 v48, v232, v48, vcc
	v_cmp_gt_u32_e32 vcc, s3, v49
	v_max3_f32 v2, v2, v36, v37
	v_fmac_f32_e32 v52, 0x3e38aa3b, v15
	s_and_b64 vcc, s[0:1], vcc
	v_max3_f32 v2, v2, v38, v39
	v_cndmask_b32_e32 v49, v232, v52, vcc
	v_cmp_gt_u32_e32 vcc, s3, v50
	v_max3_f32 v2, v2, v40, v41
	v_fmac_f32_e32 v53, 0x3e38aa3b, v16
	s_and_b64 vcc, s[0:1], vcc
	v_max3_f32 v2, v2, v42, v43
	v_cndmask_b32_e32 v50, v232, v53, vcc
	v_cmp_gt_u32_e32 vcc, s3, v51
	v_max3_f32 v2, v2, v44, v45
	v_fmac_f32_e32 v54, 0x3e38aa3b, v17
	s_and_b64 vcc, s[0:1], vcc
	v_max3_f32 v2, v2, v46, v47
	v_cndmask_b32_e32 v51, v232, v54, vcc
	v_max3_f32 v2, v2, v48, v49
	v_max3_f32 v2, v2, v50, v51
	v_mov_b32_e32 v3, v2
	s_nop 1
	v_permlane32_swap_b32_e32 v2, v3
	v_max_f32_e32 v3, v3, v3
	v_max_f32_e32 v2, v2, v2
	v_mul_f32_e32 v35, 0x3fb8aa3b, v34
	v_max_f32_e32 v2, v2, v3
	v_max_f32_e32 v52, v35, v2
	v_fmamk_f32 v2, v34, 0xbfb8aa3b, v2
	v_cmp_lt_f32_e32 vcc, s21, v2
	s_mov_b32 s0, 0x3fb8aa3b
	s_cmp_eq_u64 vcc, 0
	v_fma_f32 v3, v34, s0, -v52
	s_cselect_b64 s[0:1], -1, 0
	v_exp_f32_e32 v108, v3
	v_cndmask_b32_e64 v102, v52, v35, s[0:1]
	v_pk_add_f32 v[24:25], v[24:25], v[102:103] op_sel_hi:[1,0] neg_lo:[0,1] neg_hi:[0,1]
	v_pk_add_f32 v[22:23], v[22:23], v[102:103] op_sel_hi:[1,0] neg_lo:[0,1] neg_hi:[0,1]
	v_pk_add_f32 v[20:21], v[20:21], v[102:103] op_sel_hi:[1,0] neg_lo:[0,1] neg_hi:[0,1]
	v_pk_add_f32 v[18:19], v[18:19], v[102:103] op_sel_hi:[1,0] neg_lo:[0,1] neg_hi:[0,1]
	v_pk_add_f32 v[38:39], v[38:39], v[102:103] op_sel_hi:[1,0] neg_lo:[0,1] neg_hi:[0,1]
	v_pk_add_f32 v[58:59], v[32:33], v[102:103] op_sel_hi:[1,0] neg_lo:[0,1] neg_hi:[0,1]
	v_pk_add_f32 v[54:55], v[30:31], v[102:103] op_sel_hi:[1,0] neg_lo:[0,1] neg_hi:[0,1]
	v_pk_add_f32 v[126:127], v[46:47], v[102:103] op_sel_hi:[1,0] neg_lo:[0,1] neg_hi:[0,1]
	v_pk_add_f32 v[30:31], v[44:45], v[102:103] op_sel_hi:[1,0] neg_lo:[0,1] neg_hi:[0,1]
	v_pk_add_f32 v[32:33], v[42:43], v[102:103] op_sel_hi:[1,0] neg_lo:[0,1] neg_hi:[0,1]
	v_exp_f32_e32 v34, v18
	v_exp_f32_e32 v35, v19
	v_exp_f32_e32 v42, v20
	v_exp_f32_e32 v44, v38
	v_exp_f32_e32 v43, v21
	v_exp_f32_e32 v45, v39
	v_exp_f32_e32 v38, v22
	v_exp_f32_e32 v39, v23
	v_exp_f32_e32 v46, v24
	v_exp_f32_e32 v47, v25
	v_mul_f32_e32 v2, 0, v108
	v_cndmask_b32_e64 v2, v2, 0, s[0:1]
	v_mov_b32_e32 v3, v2
	v_mov_b32_e32 v4, v2
	v_mov_b32_e32 v5, v2
	v_mov_b32_e32 v6, v2
	v_mov_b32_e32 v7, v2
	v_mov_b32_e32 v8, v2
	v_mov_b32_e32 v9, v2
	v_mov_b32_e32 v10, v2
	v_mov_b32_e32 v11, v2
	v_mov_b32_e32 v12, v2
	v_mov_b32_e32 v13, v2
	v_mov_b32_e32 v14, v2
	v_mov_b32_e32 v15, v2
	v_mov_b32_e32 v16, v2
	v_mov_b32_e32 v17, v2
	v_pk_add_f32 v[28:29], v[28:29], v[102:103] op_sel_hi:[1,0] neg_lo:[0,1] neg_hi:[0,1]
	v_pk_add_f32 v[26:27], v[26:27], v[102:103] op_sel_hi:[1,0] neg_lo:[0,1] neg_hi:[0,1]
	v_cvt_pk_bf16_f32 v110, v34, v35
	v_cvt_pk_bf16_f32 v111, v42, v43
	v_cvt_pk_bf16_f32 v112, v38, v39
	v_cvt_pk_bf16_f32 v113, v46, v47
	v_pk_add_f32 v[64:65], v[50:51], v[102:103] op_sel_hi:[1,0] neg_lo:[0,1] neg_hi:[0,1]
	v_pk_add_f32 v[130:131], v[48:49], v[102:103] op_sel_hi:[1,0] neg_lo:[0,1] neg_hi:[0,1]
	v_exp_f32_e32 v48, v32
	v_exp_f32_e32 v49, v33
	v_exp_f32_e32 v50, v26
	v_exp_f32_e32 v52, v30
	v_exp_f32_e32 v51, v27
	v_exp_f32_e32 v53, v31
	v_exp_f32_e32 v56, v28
	v_exp_f32_e32 v57, v29
	v_add_u32_e32 v101, s31, v107
	ds_read_b64_tr_b16 v[122:123], v101 offset:0
	ds_read_b64_tr_b16 v[124:125], v101 offset:0x200
	ds_read_b64_tr_b16 v[60:61], v101 offset:0x400
	ds_read_b64_tr_b16 v[62:63], v101 offset:0x600
	ds_read_b64_tr_b16 v[118:119], v101 offset:0x800
	ds_read_b64_tr_b16 v[120:121], v101 offset:0xa00
	ds_read_b64_tr_b16 v[114:115], v101 offset:0xc00
	ds_read_b64_tr_b16 v[116:117], v101 offset:0xe00
	s_waitcnt lgkmcnt(0)
	v_exp_f32_e32 v54, v54
	v_mfma_f32_32x32x16_bf16 v[18:33], v[122:125], v[110:113], v[2:17]
	v_exp_f32_e32 v55, v55
	v_exp_f32_e32 v58, v58
	v_exp_f32_e32 v59, v59
	v_cvt_pk_bf16_f32 v122, v50, v51
	v_cvt_pk_bf16_f32 v123, v56, v57
	v_cvt_pk_bf16_f32 v124, v54, v55
	v_cvt_pk_bf16_f32 v125, v58, v59
	v_pk_add_f32 v[40:41], v[40:41], v[102:103] op_sel_hi:[1,0] neg_lo:[0,1] neg_hi:[0,1]
	v_pk_add_f32 v[36:37], v[36:37], v[102:103] op_sel_hi:[1,0] neg_lo:[0,1] neg_hi:[0,1]
	v_mfma_f32_32x32x16_bf16 v[18:33], v[60:63], v[122:125], v[18:33]
	v_exp_f32_e32 v36, v36
	v_exp_f32_e32 v37, v37
	v_exp_f32_e32 v40, v40
	v_exp_f32_e32 v41, v41
	v_exp_f32_e32 v62, v126
	v_exp_f32_e32 v63, v127
	v_cvt_pk_bf16_f32 v126, v36, v37
	v_cvt_pk_bf16_f32 v127, v44, v45
	v_cvt_pk_bf16_f32 v128, v40, v41
	v_cvt_pk_bf16_f32 v129, v48, v49
	v_exp_f32_e32 v60, v130
	v_exp_f32_e32 v61, v131
	v_mfma_f32_32x32x16_bf16 v[18:33], v[118:121], v[126:129], v[18:33]
	v_exp_f32_e32 v64, v64
	v_exp_f32_e32 v65, v65
	v_cvt_pk_bf16_f32 v118, v52, v53
	v_cvt_pk_bf16_f32 v119, v62, v63
	v_cvt_pk_bf16_f32 v120, v60, v61
	v_cvt_pk_bf16_f32 v121, v64, v65
	s_add_i32 s73, s28, 0x7e0
	s_and_b64 vcc, exec, s[8:9]
	v_mfma_f32_32x32x16_bf16 v[18:33], v[114:117], v[118:121], v[18:33]
	ds_read_b64_tr_b16 v[138:139], v101 offset:0x1000
	ds_read_b64_tr_b16 v[140:141], v101 offset:0x1200
	ds_read_b64_tr_b16 v[134:135], v101 offset:0x1400
	ds_read_b64_tr_b16 v[136:137], v101 offset:0x1600
	ds_read_b64_tr_b16 v[130:131], v101 offset:0x1800
	ds_read_b64_tr_b16 v[132:133], v101 offset:0x1a00
	ds_read_b64_tr_b16 v[114:115], v101 offset:0x1c00
	ds_read_b64_tr_b16 v[116:117], v101 offset:0x1e00
	s_waitcnt lgkmcnt(0)
	s_waitcnt vmcnt(0)
	s_barrier
	s_mov_b32 s86, 0x800000
	s_movk_i32 s87, 0x3fff
	v_mfma_f32_32x32x16_bf16 v[2:17], v[138:141], v[110:113], v[2:17]
	v_mov_b32_e32 v110, v244
	s_nop 0
	v_lshlrev_b32_e32 v111, 4, v110
	v_add_u32_e32 v104, s29, v111
	v_mfma_f32_32x32x16_bf16 v[2:17], v[134:137], v[122:125], v[2:17]
	v_mfma_f32_32x32x16_bf16 v[2:17], v[130:133], v[126:129], v[2:17]
	v_mfma_f32_32x32x16_bf16 v[2:17], v[114:117], v[118:121], v[2:17]
	s_cbranch_vccz .LBB0_1313
	s_and_b64 vcc, exec, s[10:11]
	s_cbranch_vccz .LBB0_1314

; template <int DQK, int W1, int DV, int VW, int MODE> ...
;     ...
;       s[0] = s_block<KSTR, ND, 0>(bufa + klane, qf, negm);
;       s[1] = s_block<KSTR, ND, 1>(bufa + klane, qf, negm);
;     ...
;         f32x16 e0 = s[0], e1 = s[1];
;         if (MODE != 0) { const float nm = -m; e0 = e0 + nm; e1 = e1 + nm; }
; #pragma unroll
;         for (int i = 0; i < 16; ++i) { e0[i] = __builtin_amdgcn_exp2f(e0[i]); e1[i] = __builtin_amdgcn_exp2f(e1[i]); }
;         s[0] = e0; s[1] = e1;
;         const f32x16 sm = e0 + e1;
;         typedef __attribute__((ext_vector_type(8))) float f32x8;
;         const f32x8 h8 = sm.lo + sm.hi;
;         const f32x4 h4 = h8.lo + h8.hi;
;         const f32x2 h2 = h4.lo + h4.hi;
;         l += h2[0] + h2[1];
;       }
;       bf16x8 pb[2][2];
; #pragma unroll
;       for (int n = 0; n < 2; ++n)
; #pragma unroll
;         for (int s2 = 0; s2 < 2; ++s2) {
;           u32x4 pw = {pk2(s[n][8 * s2 + 0], s[n][8 * s2 + 1]), pk2(s[n][8 * s2 + 2], s[n][8 * s2 + 3]),
;                       pk2(s[n][8 * s2 + 4], s[n][8 * s2 + 5]), pk2(s[n][8 * s2 + 6], s[n][8 * s2 + 7])};
;           pb[n][s2] = __builtin_bit_cast(bf16x8, pw);
;         }
;       pv_block<0>(o[0], bufa + vlane, pb);
;       if constexpr (NCB > 1) pv_block<1>(o[1], bufa + vlane, pb);
;       if constexpr (NCB > 2) pv_block<2>(o[2], bufa + vlane, pb);
;       if constexpr (NCB > 3) pv_block<3>(o[3], bufa + vlane, pb);
;     }
;     asm volatile("s_waitcnt vmcnt(0)" ::: "memory");
;     __syncthreads();
.LBB0_1317:
	v_mov_b32_e32 v110, v104
	v_mov_b32_e32 v111, v104
	v_pk_add_f32 v[56:57], v[56:57], v[104:105] op_sel_hi:[1,0]
	v_pk_add_f32 v[54:55], v[54:55], v[104:105] op_sel_hi:[1,0]
	v_pk_add_f32 v[52:53], v[52:53], v[104:105] op_sel_hi:[1,0]
	v_pk_add_f32 v[50:51], v[50:51], v[110:111]
	v_pk_add_f32 v[34:35], v[34:35], v[110:111]
	v_exp_f32_e32 v110, v50
	v_exp_f32_e32 v111, v51
	v_exp_f32_e32 v120, v52
	v_exp_f32_e32 v121, v53
	v_exp_f32_e32 v124, v54
	v_exp_f32_e32 v125, v55
	v_exp_f32_e32 v128, v56
	v_exp_f32_e32 v129, v57
	s_cmp_lg_u32 0, -1
	v_pk_add_f32 v[36:37], v[36:37], v[104:105] op_sel_hi:[1,0]
	s_cselect_b32 s0, 0, 0
	v_pk_add_f32 v[42:43], v[42:43], v[104:105] op_sel_hi:[1,0]
	v_pk_add_f32 v[40:41], v[40:41], v[104:105] op_sel_hi:[1,0]
	v_pk_add_f32 v[38:39], v[38:39], v[104:105] op_sel_hi:[1,0]
	v_exp_f32_e32 v118, v34
	v_exp_f32_e32 v119, v35
	v_exp_f32_e32 v122, v36
	v_exp_f32_e32 v123, v37
	v_cvt_pk_bf16_f32 v34, v110, v111
	v_cvt_pk_bf16_f32 v35, v120, v121
	v_cvt_pk_bf16_f32 v36, v124, v125
	v_cvt_pk_bf16_f32 v37, v128, v129
	s_addk_i32 s0, 0x4400
	v_pk_add_f32 v[64:65], v[64:65], v[104:105] op_sel_hi:[1,0]
	v_pk_add_f32 v[62:63], v[62:63], v[104:105] op_sel_hi:[1,0]
	v_pk_add_f32 v[60:61], v[60:61], v[104:105] op_sel_hi:[1,0]
	v_pk_add_f32 v[58:59], v[58:59], v[104:105] op_sel_hi:[1,0]
	v_pk_add_f32 v[112:113], v[48:49], v[104:105] op_sel_hi:[1,0]
	v_pk_add_f32 v[114:115], v[46:47], v[104:105] op_sel_hi:[1,0]
	v_pk_add_f32 v[116:117], v[44:45], v[104:105] op_sel_hi:[1,0]
	v_exp_f32_e32 v126, v38
	v_exp_f32_e32 v127, v39
	v_exp_f32_e32 v130, v40
	v_exp_f32_e32 v131, v41
	v_exp_f32_e32 v134, v42
	v_exp_f32_e32 v135, v43
	v_add_u32_e32 v105, s0, v107
	ds_read_b64_tr_b16 v[50:51], v105 offset:0
	ds_read_b64_tr_b16 v[52:53], v105 offset:0x200
	ds_read_b64_tr_b16 v[46:47], v105 offset:0x400
	ds_read_b64_tr_b16 v[48:49], v105 offset:0x600
	ds_read_b64_tr_b16 v[42:43], v105 offset:0x800
	ds_read_b64_tr_b16 v[44:45], v105 offset:0xa00
	ds_read_b64_tr_b16 v[38:39], v105 offset:0xc00
	ds_read_b64_tr_b16 v[40:41], v105 offset:0xe00
	s_waitcnt lgkmcnt(0)
	v_exp_f32_e32 v132, v58
	v_mfma_f32_32x32x16_bf16 v[18:33], v[50:53], v[34:37], v[18:33]
	v_exp_f32_e32 v133, v59
	v_exp_f32_e32 v136, v60
	v_exp_f32_e32 v137, v61
	v_exp_f32_e32 v138, v62
	v_exp_f32_e32 v139, v63
	v_exp_f32_e32 v140, v64
	v_exp_f32_e32 v141, v65
	v_cvt_pk_bf16_f32 v50, v132, v133
	v_cvt_pk_bf16_f32 v51, v136, v137
	v_cvt_pk_bf16_f32 v52, v138, v139
	v_cvt_pk_bf16_f32 v53, v140, v141
	v_exp_f32_e32 v116, v116
	v_exp_f32_e32 v117, v117
	v_mfma_f32_32x32x16_bf16 v[18:33], v[46:49], v[50:53], v[18:33]
	v_cvt_pk_bf16_f32 v46, v118, v119
	v_cvt_pk_bf16_f32 v47, v122, v123
	v_cvt_pk_bf16_f32 v48, v126, v127
	v_cvt_pk_bf16_f32 v49, v130, v131
	v_exp_f32_e32 v114, v114
	v_exp_f32_e32 v115, v115
	v_exp_f32_e32 v112, v112
	v_mfma_f32_32x32x16_bf16 v[18:33], v[42:45], v[46:49], v[18:33]
	v_exp_f32_e32 v113, v113
	v_cvt_pk_bf16_f32 v42, v134, v135
	v_cvt_pk_bf16_f32 v43, v116, v117
	v_cvt_pk_bf16_f32 v44, v114, v115
	v_cvt_pk_bf16_f32 v45, v112, v113
	s_movk_i32 s1, 0x80
	s_add_i32 s0, s28, 0x800
	v_mfma_f32_32x32x16_bf16 v[18:33], v[38:41], v[42:45], v[18:33]
	ds_read_b64_tr_b16 v[62:63], v105 offset:0x1000
	ds_read_b64_tr_b16 v[64:65], v105 offset:0x1200
	ds_read_b64_tr_b16 v[58:59], v105 offset:0x1400
	ds_read_b64_tr_b16 v[60:61], v105 offset:0x1600
	ds_read_b64_tr_b16 v[54:55], v105 offset:0x1800
	ds_read_b64_tr_b16 v[56:57], v105 offset:0x1a00
	ds_read_b64_tr_b16 v[38:39], v105 offset:0x1c00
	ds_read_b64_tr_b16 v[40:41], v105 offset:0x1e00
	s_waitcnt lgkmcnt(0)
	s_waitcnt vmcnt(0)
	s_barrier
	s_movk_i32 s20, 0x600
	v_readlane_b32 s3, v254, 29
	v_mfma_f32_32x32x16_bf16 v[2:17], v[62:65], v[34:37], v[2:17]
	v_mfma_f32_32x32x16_bf16 v[2:17], v[58:61], v[50:53], v[2:17]
	v_mfma_f32_32x32x16_bf16 v[2:17], v[54:57], v[46:49], v[2:17]
	v_mfma_f32_32x32x16_bf16 v[2:17], v[38:41], v[42:45], v[2:17]
	ds_read_b128 v[34:37], v106 offset:0
	ds_read_b128 v[38:41], v106 offset:32
	ds_read_b128 v[42:45], v106 offset:64
	ds_read_b128 v[46:49], v106 offset:0x60
	s_waitcnt lgkmcnt(0)
	s_nop 0
	v_mfma_f32_32x32x16_bf16 v[50:65], v[34:37], v[78:81], 0
	v_add_f32_e64 v34, v136, v116
	v_add_f32_e64 v35, v137, v117
	v_add_f32_e64 v36, v120, v122
	v_add_f32_e64 v37, v121, v123
	v_mfma_f32_32x32x16_bf16 v[50:65], v[38:41], v[74:77], v[50:65]
	v_add_f32_e64 v38, v140, v112
	v_add_f32_e64 v39, v141, v113
	v_add_f32_e64 v112, v124, v126
	v_add_f32_e64 v113, v125, v127
	v_add_f32_e64 v40, v128, v130
	v_add_f32_e64 v41, v129, v131
	v_pk_add_f32 v[128:129], v[36:37], v[34:35]
	v_pk_add_f32 v[126:127], v[40:41], v[38:39]
	v_mfma_f32_32x32x16_bf16 v[50:65], v[42:45], v[70:73], v[50:65]
	v_add_f32_e64 v44, v110, v118
	v_add_f32_e64 v45, v111, v119
	v_add_f32_e64 v110, v138, v114
	v_add_f32_e64 v111, v139, v115
	v_add_f32_e64 v42, v132, v134
	v_add_f32_e64 v43, v133, v135
	v_pk_add_f32 v[122:123], v[112:113], v[110:111]
	ds_read_b128 v[34:37], v106 offset:0x1200
	ds_read_b128 v[110:113], v106 offset:0x1220
	ds_read_b128 v[114:117], v106 offset:0x1240
	ds_read_b128 v[118:121], v106 offset:0x1260
	s_waitcnt lgkmcnt(0)
; DI int crow(int reg, int hi) { return (reg & 3) + 8 * (reg >> 2) + 4 * hi; }
; template <int DQK, int W1, int DV, int VW, int MODE> ...
;     ...
;       } else if (MODE == 2) {
; #pragma unroll
;         for (int n = 0; n < 2; ++n)
; #pragma unroll
;           for (int i = 0; i < 16; ++i) {
;             const int key = kb + 32 * n + crow(i, hi), rel = tq - key;
;             const bool ok = ((unsigned)rel < 128u) && (key >= 0);
;             const float v = fmaf(s[n][i], c2, lutw[rel & 127]);
;             s[n][i] = ok ? v : NEGV;
;           }
	v_pk_add_f32 v[124:125], v[44:45], v[42:43]
	v_mfma_f32_32x32x16_bf16 v[50:65], v[46:49], v[66:69], v[50:65]
	v_mfma_f32_32x32x16_bf16 v[34:49], v[34:37], v[78:81], 0
	v_add_f32_e64 v78, v128, v126
	v_add_f32_e64 v79, v129, v127
	v_add_f32_e64 v80, v124, v122
	v_add_f32_e64 v81, v125, v123
	v_add_f32_e64 v78, v80, v78
	v_add_f32_e64 v79, v81, v79
	v_add_f32_e32 v78, v78, v79
	v_add_f32_e32 v106, v108, v78
	v_mfma_f32_32x32x16_bf16 v[34:49], v[110:113], v[74:77], v[34:49]
	v_or_b32_e32 v78, s73, v103
	v_or_b32_e32 v79, s73, v82
	v_sub_u32_e32 v74, v0, v78
	v_or_b32_e32 v78, s73, v83
	v_sub_u32_e32 v75, v0, v79
	v_sub_u32_e32 v78, v0, v78
	v_and_b32_e32 v76, 0x7f, v75
	v_mfma_f32_32x32x16_bf16 v[34:49], v[114:117], v[70:73], v[34:49]
	v_or_b32_e32 v70, s73, v88
	v_sub_u32_e32 v79, v0, v70
	v_and_b32_e32 v70, 0x7f, v79
	v_and_b32_e32 v71, 0x7f, v78
	v_lshl_add_u32 v76, v76, 2, s27
	v_and_b32_e32 v77, 0x7f, v74
	v_lshl_add_u32 v70, v70, 2, s27
	v_mfma_f32_32x32x16_bf16 v[34:49], v[118:121], v[66:69], v[34:49]
	v_or_b32_e32 v67, s73, v90
	v_or_b32_e32 v66, s73, v89
	v_sub_u32_e32 v81, v0, v67
	v_sub_u32_e32 v80, v0, v66
	v_and_b32_e32 v66, 0x7f, v81
	v_lshl_add_u32 v72, v66, 2, s27
	v_and_b32_e32 v66, 0x7f, v80
	v_or_b32_e32 v67, s73, v92
	v_lshl_add_u32 v73, v66, 2, s27
	v_or_b32_e32 v66, s73, v91
	v_sub_u32_e32 v107, v0, v67
	v_sub_u32_e32 v105, v0, v66
	v_and_b32_e32 v66, 0x7f, v107
	v_lshl_add_u32 v71, v71, 2, s27
	v_lshl_add_u32 v108, v66, 2, s27
	v_and_b32_e32 v66, 0x7f, v105
	v_lshl_add_u32 v77, v77, 2, s27
	v_lshl_add_u32 v109, v66, 2, s27
	ds_read_b32 v66, v76
	ds_read_b32 v67, v77
	ds_read_b32 v68, v70
	ds_read_b32 v69, v71
	ds_read_b32 v70, v72
	ds_read_b32 v71, v73
	ds_read_b32 v72, v108
	ds_read_b32 v73, v109
	s_waitcnt lgkmcnt(6)
	v_pk_fma_f32 v[50:51], v[50:51], s[64:65], v[66:67] op_sel_hi:[1,0,1]
	v_cmp_gt_u32_e32 vcc, s1, v74
	s_waitcnt lgkmcnt(4)
	v_pk_fma_f32 v[52:53], v[52:53], s[64:65], v[68:69] op_sel_hi:[1,0,1]
	s_waitcnt lgkmcnt(2)
	v_pk_fma_f32 v[54:55], v[54:55], s[64:65], v[70:71] op_sel_hi:[1,0,1]
	v_cndmask_b32_e32 v51, v232, v51, vcc
	v_cmp_gt_u32_e32 vcc, s1, v75
	s_waitcnt lgkmcnt(0)
	v_pk_fma_f32 v[56:57], v[56:57], s[64:65], v[72:73] op_sel_hi:[1,0,1]
	v_or_b32_e32 v66, s73, v93
	v_cndmask_b32_e32 v50, v232, v50, vcc
	v_cmp_gt_u32_e32 vcc, s1, v78
	v_or_b32_e32 v67, s73, v94
	v_or_b32_e32 v68, s73, v95
	v_cndmask_b32_e32 v53, v232, v53, vcc
	v_cmp_gt_u32_e32 vcc, s1, v79
	v_or_b32_e32 v69, s73, v96
	v_or_b32_e32 v70, s73, v97
	v_cndmask_b32_e32 v52, v232, v52, vcc
	v_cmp_gt_u32_e32 vcc, s1, v80
	v_or_b32_e32 v71, s73, v98
	v_or_b32_e32 v72, s73, v99
	v_or_b32_e32 v73, s73, v100
	v_cndmask_b32_e32 v55, v232, v55, vcc
	v_cmp_gt_u32_e32 vcc, s1, v81
	v_sub_u32_e32 v74, v0, v66
	v_sub_u32_e32 v75, v0, v67
	v_sub_u32_e32 v76, v0, v68
	v_sub_u32_e32 v77, v0, v69
	v_sub_u32_e32 v78, v0, v70
	v_sub_u32_e32 v79, v0, v71
	v_sub_u32_e32 v80, v0, v72
	v_sub_u32_e32 v81, v0, v73
	v_cndmask_b32_e32 v54, v232, v54, vcc
	v_cmp_gt_u32_e32 vcc, s1, v105
	v_and_b32_e32 v66, 0x7f, v75
	v_and_b32_e32 v67, 0x7f, v74
	v_and_b32_e32 v68, 0x7f, v77
	v_and_b32_e32 v69, 0x7f, v76
	v_and_b32_e32 v70, 0x7f, v79
	v_and_b32_e32 v71, 0x7f, v78
	v_and_b32_e32 v72, 0x7f, v81
	v_and_b32_e32 v73, 0x7f, v80
	v_cndmask_b32_e32 v57, v232, v57, vcc
	v_cmp_gt_u32_e32 vcc, s1, v107
	v_lshl_add_u32 v66, v66, 2, s27
	v_lshl_add_u32 v67, v67, 2, s27
	v_lshl_add_u32 v68, v68, 2, s27
	v_lshl_add_u32 v69, v69, 2, s27
	v_lshl_add_u32 v70, v70, 2, s27
	v_lshl_add_u32 v71, v71, 2, s27
	v_lshl_add_u32 v72, v72, 2, s27
	v_lshl_add_u32 v73, v73, 2, s27
	v_cndmask_b32_e32 v56, v232, v56, vcc
	ds_read_b32 v66, v66
	ds_read_b32 v67, v67
	ds_read_b32 v68, v68
	ds_read_b32 v69, v69
	ds_read_b32 v70, v70
	ds_read_b32 v71, v71
	ds_read_b32 v72, v72
	ds_read_b32 v73, v73
	s_waitcnt lgkmcnt(6)
	v_pk_fma_f32 v[58:59], v[58:59], s[64:65], v[66:67] op_sel_hi:[1,0,1]
	v_cmp_gt_u32_e32 vcc, s1, v74
	s_waitcnt lgkmcnt(4)
	v_pk_fma_f32 v[60:61], v[60:61], s[64:65], v[68:69] op_sel_hi:[1,0,1]
	s_waitcnt lgkmcnt(2)
	v_pk_fma_f32 v[62:63], v[62:63], s[64:65], v[70:71] op_sel_hi:[1,0,1]
	v_cndmask_b32_e32 v59, v232, v59, vcc
	v_cmp_gt_u32_e32 vcc, s1, v75
	s_waitcnt lgkmcnt(0)
	v_pk_fma_f32 v[64:65], v[64:65], s[64:65], v[72:73] op_sel_hi:[1,0,1]
	v_or_b32_e32 v66, s0, v103
	v_cndmask_b32_e32 v58, v232, v58, vcc
	v_cmp_gt_u32_e32 vcc, s1, v76
	v_or_b32_e32 v67, s0, v82
	v_or_b32_e32 v68, s0, v83
	v_cndmask_b32_e32 v61, v232, v61, vcc
	v_cmp_gt_u32_e32 vcc, s1, v77
	v_or_b32_e32 v69, s0, v88
	v_or_b32_e32 v70, s0, v89
	v_cndmask_b32_e32 v60, v232, v60, vcc
	v_cmp_gt_u32_e32 vcc, s1, v78
	v_or_b32_e32 v71, s0, v90
	v_or_b32_e32 v72, s0, v91
	v_cndmask_b32_e32 v63, v232, v63, vcc
	v_cmp_gt_u32_e32 vcc, s1, v79
	v_or_b32_e32 v73, s0, v92
	v_sub_u32_e32 v74, v0, v66
	v_cndmask_b32_e32 v62, v232, v62, vcc
	v_cmp_gt_u32_e32 vcc, s1, v80
	v_sub_u32_e32 v75, v0, v67
	v_sub_u32_e32 v76, v0, v68
	v_cndmask_b32_e32 v65, v232, v65, vcc
	v_cmp_gt_u32_e32 vcc, s1, v81
	v_sub_u32_e32 v77, v0, v69
	v_sub_u32_e32 v78, v0, v70
	v_sub_u32_e32 v79, v0, v71
	v_sub_u32_e32 v80, v0, v72
	v_sub_u32_e32 v81, v0, v73
	v_and_b32_e32 v66, 0x7f, v75
	v_and_b32_e32 v67, 0x7f, v74
	v_and_b32_e32 v68, 0x7f, v77
	v_and_b32_e32 v69, 0x7f, v76
	v_and_b32_e32 v70, 0x7f, v79
	v_and_b32_e32 v71, 0x7f, v78
	v_and_b32_e32 v72, 0x7f, v81
	v_and_b32_e32 v73, 0x7f, v80
	v_lshl_add_u32 v66, v66, 2, s27
	v_lshl_add_u32 v67, v67, 2, s27
	v_lshl_add_u32 v68, v68, 2, s27
	v_lshl_add_u32 v69, v69, 2, s27
	v_lshl_add_u32 v70, v70, 2, s27
	v_lshl_add_u32 v71, v71, 2, s27
	v_lshl_add_u32 v72, v72, 2, s27
	v_lshl_add_u32 v73, v73, 2, s27
	v_cndmask_b32_e32 v64, v232, v64, vcc
	ds_read_b32 v66, v66
	ds_read_b32 v67, v67
	ds_read_b32 v68, v68
	ds_read_b32 v69, v69
	ds_read_b32 v70, v70
	ds_read_b32 v71, v71
	ds_read_b32 v72, v72
	ds_read_b32 v73, v73
	s_waitcnt lgkmcnt(6)
; DI int crow(int reg, int hi) { return (reg & 3) + 8 * (reg >> 2) + 4 * hi; }
; template <int DQK, int W1, int DV, int VW, int MODE> ...
;     ...
;           for (int i = 0; i < 16; ++i) {
;             const int key = kb + 32 * n + crow(i, hi), rel = tq - key;
;             const bool ok = ((unsigned)rel < 128u) && (key >= 0);
;             const float v = fmaf(s[n][i], c2, lutw[rel & 127]);
;             s[n][i] = ok ? v : NEGV;
;           }
;       } else {
; #pragma unroll
;         for (int n = 0; n < 2; ++n)
; #pragma unroll
;           for (int i = 0; i < 16; ++i) s[n][i] *= c2;
;       }
;       float mx = s[0][0];
; #pragma unroll
;       for (int i = 1; i < 16; ++i) mx = fmaxf(mx, s[0][i]);
; #pragma unroll
;       for (int i = 0; i < 16; ++i) mx = fmaxf(mx, s[1][i]);
;       mx = xhalf_max(mx);
;       if (MODE == 0) {
;         if (t == 0) {
;           m = mx;
;           s[0] = s[0] - mx; s[1] = s[1] - mx; negm = negm - mx;
;         } else if (__any(mx > 8.0f)) {
;           const float d = fmaxf(mx, 0.f), alpha = __builtin_amdgcn_exp2f(-d);
;           m += d; l *= alpha;
;           s[0] = s[0] - d; s[1] = s[1] - d; negm = negm - d;
; #pragma unroll
;           for (int cb = 0; cb < NCB; ++cb)
; #pragma unroll
;             for (int r = 0; r < 16; ++r) o[cb][r] *= alpha;
;         }
;       } else if (__any(mx - m > 8.0f)) {
;         const float mnew = fmaxf(m, mx), alpha = __builtin_amdgcn_exp2f(m - mnew);
;         m = mnew; l *= alpha;
; #pragma unroll
;         for (int cb = 0; cb < NCB; ++cb)
; #pragma unroll
;           for (int r = 0; r < 16; ++r) o[cb][r] *= alpha;
;       }
	v_pk_fma_f32 v[34:35], v[34:35], s[64:65], v[66:67] op_sel_hi:[1,0,1]
	v_cmp_gt_u32_e32 vcc, s1, v74
	s_waitcnt lgkmcnt(4)
	v_pk_fma_f32 v[36:37], v[36:37], s[64:65], v[68:69] op_sel_hi:[1,0,1]
	s_waitcnt lgkmcnt(2)
	v_pk_fma_f32 v[38:39], v[38:39], s[64:65], v[70:71] op_sel_hi:[1,0,1]
	v_cndmask_b32_e32 v35, v232, v35, vcc
	v_cmp_gt_u32_e32 vcc, s1, v75
	s_waitcnt lgkmcnt(0)
	v_pk_fma_f32 v[40:41], v[40:41], s[64:65], v[72:73] op_sel_hi:[1,0,1]
	v_or_b32_e32 v68, s0, v95
	v_cndmask_b32_e32 v34, v232, v34, vcc
	v_cmp_gt_u32_e32 vcc, s1, v76
	v_or_b32_e32 v69, s0, v96
	v_or_b32_e32 v70, s0, v97
	v_cndmask_b32_e32 v37, v232, v37, vcc
	v_cmp_gt_u32_e32 vcc, s1, v77
	v_or_b32_e32 v71, s0, v98
	v_or_b32_e32 v72, s0, v99
	v_cndmask_b32_e32 v36, v232, v36, vcc
	v_cmp_gt_u32_e32 vcc, s1, v78
	v_or_b32_e32 v73, s0, v100
	v_sub_u32_e32 v76, v0, v68
	v_cndmask_b32_e32 v39, v232, v39, vcc
	v_cmp_gt_u32_e32 vcc, s1, v79
	v_sub_u32_e32 v77, v0, v69
	v_sub_u32_e32 v78, v0, v70
	v_cndmask_b32_e32 v38, v232, v38, vcc
	v_cmp_gt_u32_e32 vcc, s1, v80
	v_sub_u32_e32 v79, v0, v71
	v_sub_u32_e32 v80, v0, v72
	v_cndmask_b32_e32 v67, v232, v41, vcc
	v_cmp_gt_u32_e32 vcc, s1, v81
	v_or_b32_e32 v41, s0, v94
	v_sub_u32_e32 v75, v0, v41
	v_cndmask_b32_e32 v66, v232, v40, vcc
	v_or_b32_e32 v40, s0, v93
	v_sub_u32_e32 v74, v0, v40
	v_sub_u32_e32 v81, v0, v73
	v_and_b32_e32 v40, 0x7f, v75
	v_and_b32_e32 v41, 0x7f, v74
	v_and_b32_e32 v68, 0x7f, v77
	v_and_b32_e32 v69, 0x7f, v76
	v_and_b32_e32 v70, 0x7f, v79
	v_and_b32_e32 v71, 0x7f, v78
	v_and_b32_e32 v72, 0x7f, v81
	v_and_b32_e32 v73, 0x7f, v80
	v_lshl_add_u32 v40, v40, 2, s27
	v_lshl_add_u32 v41, v41, 2, s27
	v_lshl_add_u32 v68, v68, 2, s27
	v_lshl_add_u32 v69, v69, 2, s27
	v_lshl_add_u32 v70, v70, 2, s27
	v_lshl_add_u32 v71, v71, 2, s27
	v_lshl_add_u32 v72, v72, 2, s27
	v_lshl_add_u32 v73, v73, 2, s27
	ds_read_b32 v40, v40
	ds_read_b32 v41, v41
	ds_read_b32 v68, v68
	ds_read_b32 v69, v69
	ds_read_b32 v70, v70
	ds_read_b32 v71, v71
	ds_read_b32 v72, v72
	ds_read_b32 v73, v73
	s_waitcnt lgkmcnt(6)
	v_pk_fma_f32 v[40:41], v[42:43], s[64:65], v[40:41] op_sel_hi:[1,0,1]
	v_cmp_gt_u32_e32 vcc, s1, v74
	s_nop 1
	v_cndmask_b32_e32 v43, v232, v41, vcc
	v_cmp_gt_u32_e32 vcc, s1, v75
	s_nop 1
	v_cndmask_b32_e32 v42, v232, v40, vcc
	s_waitcnt lgkmcnt(4)
	v_pk_fma_f32 v[40:41], v[44:45], s[64:65], v[68:69] op_sel_hi:[1,0,1]
	v_cmp_gt_u32_e32 vcc, s1, v76
	s_nop 1
	v_cndmask_b32_e32 v45, v232, v41, vcc
	v_cmp_gt_u32_e32 vcc, s1, v77
	s_nop 1
	v_cndmask_b32_e32 v44, v232, v40, vcc
	s_waitcnt lgkmcnt(2)
	v_pk_fma_f32 v[40:41], v[46:47], s[64:65], v[70:71] op_sel_hi:[1,0,1]
	v_cmp_gt_u32_e32 vcc, s1, v78
	s_nop 1
	v_cndmask_b32_e32 v47, v232, v41, vcc
	v_cmp_gt_u32_e32 vcc, s1, v79
	s_nop 1
	v_cndmask_b32_e32 v46, v232, v40, vcc
	s_waitcnt lgkmcnt(0)
	v_pk_fma_f32 v[40:41], v[48:49], s[64:65], v[72:73] op_sel_hi:[1,0,1]
	v_cmp_gt_u32_e32 vcc, s1, v80
	s_nop 1
	v_cndmask_b32_e32 v49, v232, v41, vcc
	v_cmp_gt_u32_e32 vcc, s1, v81
	s_nop 1
	v_cndmask_b32_e32 v48, v232, v40, vcc
	v_max_f32_e32 v40, v50, v51
	v_max3_f32 v40, v40, v52, v53
	v_max3_f32 v40, v40, v54, v55
	v_max3_f32 v40, v40, v56, v57
	v_max3_f32 v40, v40, v58, v59
	v_max3_f32 v40, v40, v60, v61
	v_max3_f32 v40, v40, v62, v63
	v_max3_f32 v40, v40, v64, v65
	v_max3_f32 v40, v40, v34, v35
	v_max3_f32 v40, v40, v36, v37
	v_max3_f32 v40, v40, v38, v39
	v_max3_f32 v40, v40, v66, v67
	v_max3_f32 v40, v40, v42, v43
	v_max3_f32 v40, v40, v44, v45
	v_max3_f32 v40, v40, v46, v47
	v_max3_f32 v40, v40, v48, v49
	v_mov_b32_e32 v41, v40
	s_nop 1
	v_permlane32_swap_b32_e32 v40, v41
	v_max_f32_e32 v41, v41, v41
	v_max_f32_e32 v40, v40, v40
	v_max_f32_e32 v40, v40, v41
	v_sub_f32_e32 v41, v40, v102
	v_cmp_lt_f32_e32 vcc, s21, v41
	s_cbranch_vccz .LBB0_1319
	v_max_f32_e32 v40, v40, v40
	v_max_f32_e32 v41, v102, v102
	v_max_f32_e32 v41, v41, v40
	v_sub_f32_e32 v40, v102, v41
	v_exp_f32_e32 v40, v40
	v_xor_b32_e32 v104, 0x80000000, v41
	v_pk_mul_f32 v[32:33], v[32:33], v[40:41] op_sel_hi:[1,0]
	v_pk_mul_f32 v[30:31], v[30:31], v[40:41] op_sel_hi:[1,0]
	v_pk_mul_f32 v[28:29], v[28:29], v[40:41] op_sel_hi:[1,0]
	v_pk_mul_f32 v[26:27], v[26:27], v[40:41] op_sel_hi:[1,0]
	v_pk_mul_f32 v[24:25], v[24:25], v[40:41] op_sel_hi:[1,0]
	v_pk_mul_f32 v[22:23], v[22:23], v[40:41] op_sel_hi:[1,0]
	v_pk_mul_f32 v[20:21], v[20:21], v[40:41] op_sel_hi:[1,0]
	v_pk_mul_f32 v[18:19], v[18:19], v[40:41] op_sel_hi:[1,0]
	v_pk_mul_f32 v[16:17], v[16:17], v[40:41] op_sel_hi:[1,0]
	v_pk_mul_f32 v[14:15], v[14:15], v[40:41] op_sel_hi:[1,0]
	v_pk_mul_f32 v[12:13], v[12:13], v[40:41] op_sel_hi:[1,0]
	v_pk_mul_f32 v[10:11], v[10:11], v[40:41] op_sel_hi:[1,0]
	v_pk_mul_f32 v[8:9], v[8:9], v[40:41] op_sel_hi:[1,0]
	v_pk_mul_f32 v[6:7], v[6:7], v[40:41] op_sel_hi:[1,0]
	v_pk_mul_f32 v[4:5], v[4:5], v[40:41] op_sel_hi:[1,0]
	v_pk_mul_f32 v[2:3], v[2:3], v[40:41] op_sel_hi:[1,0]
	v_mul_f32_e32 v106, v106, v40

; #define PG8_STAGE(bufoff, gbase, voff) do { _Pragma("unroll") for (int _i = 0; _i < 2; ++_i) \
;         __builtin_amdgcn_global_load_lds((const unsigned*)((const char*)(gbase) + (voff)[_i]), (PG8_LAS unsigned*)(lds + (bufoff) + ldsw + _i * 8192), 16, 0, 0); } while (0)
; #define PG8_LDA(dst, b, h) do { _Pragma("unroll") for (int m = 0; m < 4; ++m) _Pragma("unroll") for (int k = 0; k < 2; ++k) dst[m][k] = *(const PG8_LAS bf16x8*)(lds + PG8_SA(b, h) + aoff + m * 2048 + k * 1024); } while (0)
; #define PG8_LDB(dst, b, h) do { _Pragma("unroll") for (int n = 0; n < 2; ++n) _Pragma("unroll") for (int k = 0; k < 2; ++k) dst[n][k] = *(const PG8_LAS bf16x8*)(lds + PG8_SB(b, h) + boff + n * 2048 + k * 1024); } while (0)
; #define PG8_WAIT_V(n) asm volatile("s_waitcnt vmcnt(" #n ")" ::: "memory")
; #define PG8_WAIT_L(n) asm volatile("s_waitcnt lgkmcnt(" #n ")" ::: "memory")
; #define PG8_BAR __builtin_amdgcn_s_barrier()
; #define PG8_SCHED __builtin_amdgcn_sched_barrier(0)
; template <bool FP8, class Epi, class Sched>
; __device__ __forceinline__ void gemm_phase(PG8_LAS unsigned char* lds, const Gemm g, const Sched& S, const Epi& E) {
;     ...
;             PG8_LDB(B0, 0, 0); PG8_SCHED; PG8_LDA(At, 0, 0); PG8_STAGE(PG8_SA(1, 1), a1 + hstepA, voffA);
;             PG8_WAIT_L(8); PG8_BAR; PG8_WAIT_L(0); PG8_MMA(0, 0, At, B0); PG8_BAR; PG8_SCHED;
;             PG8_LDB(B1, 0, 1); PG8_STAGE(PG8_SB(0, 0), b2, voffB);
;             PG8_BAR; PG8_WAIT_L(0); PG8_MMA(0, 1, At, B1); PG8_BAR;
;             PG8_LDA(At, 0, 1); PG8_STAGE(PG8_SA(0, 0), a2, voffA);
;             PG8_BAR; PG8_WAIT_L(0); PG8_MMA(1, 0, At, B0); PG8_BAR; PG8_SCHED;
;             PG8_STAGE(PG8_SB(0, 1), b2 + hstep, voffB);
;             PG8_WAIT_V(6); PG8_BAR; PG8_MMA(1, 1, At, B1); PG8_BAR;
;             PG8_LDB(B0, 1, 0); PG8_SCHED; PG8_LDA(At, 1, 0); PG8_STAGE(PG8_SA(0, 1), a2 + hstepA, voffA);
;             PG8_WAIT_L(8); PG8_BAR; PG8_WAIT_L(0); PG8_MMA(0, 0, At, B0); PG8_BAR; PG8_SCHED;
.LBB0_1543:
	s_add_u32 s12, s16, 0x100
	s_addc_u32 s13, s17, 0
	s_add_i32 s30, 0, 0x10000
	v_add_u32_e32 v6, s30, v170
	ds_read_b128 v[10:13], v6
	ds_read_b128 v[14:17], v6 offset:1024
	ds_read_b128 v[2:5], v6 offset:2048
	ds_read_b128 v[6:9], v6 offset:3072
	s_cmp_eq_u32 s72, 20
	s_cselect_b32 s19, s1, s13
	s_cselect_b32 s18, s0, s12
	s_cselect_b32 s15, s11, s71
	s_cselect_b32 s14, s10, s70
	v_lshl_add_u64 v[18:19], s[16:17], 0, v[156:157]
	s_add_i32 m0, s24, 0xc000
	ds_read_b128 v[182:185], v172
	ds_read_b128 v[186:189], v172 offset:1024
	ds_read_b128 v[190:193], v172 offset:2048
	ds_read_b128 v[194:197], v172 offset:3072
	ds_read_b128 v[198:201], v172 offset:4096
	ds_read_b128 v[202:205], v172 offset:5120
	ds_read_b128 v[206:209], v172 offset:6144
	ds_read_b128 v[210:213], v172 offset:7168
	global_load_lds_dwordx4 v[18:19], off
	v_lshl_add_u64 v[18:19], s[16:17], 0, v[158:159]
	s_add_i32 m0, s24, 0xe000
	s_nop 0
	global_load_lds_dwordx4 v[18:19], off
	s_waitcnt lgkmcnt(8)
	s_barrier
	s_waitcnt lgkmcnt(0)
	s_nop 1
	v_mfma_scale_f32_16x16x128_f8f6f4 v[150:153], v[10:17], v[182:189], v[150:153], v168, v168 op_sel_hi:[0,0,0]
	s_nop 1
	v_mfma_scale_f32_16x16x128_f8f6f4 v[146:149], v[2:9], v[182:189], v[146:149], v168, v168 op_sel_hi:[0,0,0]
	s_nop 1
	v_mfma_scale_f32_16x16x128_f8f6f4 v[142:145], v[10:17], v[190:197], v[142:145], v168, v168 op_sel_hi:[0,0,0]
	s_nop 1
	v_mfma_scale_f32_16x16x128_f8f6f4 v[138:141], v[2:9], v[190:197], v[138:141], v168, v168 op_sel_hi:[0,0,0]
	s_nop 1
	v_mfma_scale_f32_16x16x128_f8f6f4 v[118:121], v[10:17], v[198:205], v[118:121], v168, v168 op_sel_hi:[0,0,0]
	s_nop 1
	v_mfma_scale_f32_16x16x128_f8f6f4 v[114:117], v[2:9], v[198:205], v[114:117], v168, v168 op_sel_hi:[0,0,0]
	s_nop 1
	v_mfma_scale_f32_16x16x128_f8f6f4 v[110:113], v[10:17], v[206:213], v[110:113], v168, v168 op_sel_hi:[0,0,0]
	s_nop 1
	v_mfma_scale_f32_16x16x128_f8f6f4 v[106:109], v[2:9], v[206:213], v[106:109], v168, v168 op_sel_hi:[0,0,0]
	s_barrier
	s_add_i32 s31, 0, 0x14000
	s_add_i32 s16, s30, s23
	v_add_u32_e32 v22, s31, v170
	v_lshl_add_u64 v[160:161], s[14:15], 0, v[0:1]
	s_mov_b32 m0, s16
	ds_read_b128 v[236:239], v22
	ds_read_b128 v[240:243], v22 offset:1024
	ds_read_b128 v[18:21], v22 offset:2048
	ds_read_b128 v[22:25], v22 offset:3072
	global_load_lds_dwordx4 v[160:161], off
	v_lshl_add_u64 v[162:163], s[14:15], 0, v[154:155]
	s_add_i32 m0, s16, 0x2000
	s_nop 0
	global_load_lds_dwordx4 v[162:163], off
	s_barrier
	s_waitcnt lgkmcnt(0)
	s_nop 1
	v_mfma_scale_f32_16x16x128_f8f6f4 v[134:137], v[236:243], v[182:189], v[134:137], v168, v168 op_sel_hi:[0,0,0]
	s_nop 1
	v_mfma_scale_f32_16x16x128_f8f6f4 v[130:133], v[18:25], v[182:189], v[130:133], v168, v168 op_sel_hi:[0,0,0]
	s_nop 1
	v_mfma_scale_f32_16x16x128_f8f6f4 v[126:129], v[236:243], v[190:197], v[126:129], v168, v168 op_sel_hi:[0,0,0]
	s_nop 1
	v_mfma_scale_f32_16x16x128_f8f6f4 v[122:125], v[18:25], v[190:197], v[122:125], v168, v168 op_sel_hi:[0,0,0]
	s_nop 1
	v_mfma_scale_f32_16x16x128_f8f6f4 v[102:105], v[236:243], v[198:205], v[102:105], v168, v168 op_sel_hi:[0,0,0]
	s_nop 1
	v_mfma_scale_f32_16x16x128_f8f6f4 v[98:101], v[18:25], v[198:205], v[98:101], v168, v168 op_sel_hi:[0,0,0]
	s_nop 1
	v_mfma_scale_f32_16x16x128_f8f6f4 v[94:97], v[236:243], v[206:213], v[94:97], v168, v168 op_sel_hi:[0,0,0]
	s_nop 1
	v_mfma_scale_f32_16x16x128_f8f6f4 v[90:93], v[18:25], v[206:213], v[90:93], v168, v168 op_sel_hi:[0,0,0]
	s_mov_b32 m0, s24
	v_lshl_add_u64 v[164:165], s[18:19], 0, v[0:1]
	s_barrier
	ds_read_b128 v[182:185], v172 offset:16384
	ds_read_b128 v[186:189], v172 offset:17408
	ds_read_b128 v[190:193], v172 offset:18432
	ds_read_b128 v[194:197], v172 offset:19456
	ds_read_b128 v[198:201], v172 offset:20480
	ds_read_b128 v[202:205], v172 offset:21504
	ds_read_b128 v[206:209], v172 offset:22528
	ds_read_b128 v[210:213], v172 offset:23552
	global_load_lds_dwordx4 v[164:165], off
	v_lshl_add_u64 v[166:167], s[18:19], 0, v[154:155]
	s_mov_b32 m0, s25
	s_nop 0
	global_load_lds_dwordx4 v[166:167], off
	s_barrier
	s_waitcnt lgkmcnt(0)
	s_nop 1
	v_mfma_scale_f32_16x16x128_f8f6f4 v[86:89], v[10:17], v[182:189], v[86:89], v168, v168 op_sel_hi:[0,0,0]
	s_nop 1
	v_mfma_scale_f32_16x16x128_f8f6f4 v[82:85], v[2:9], v[182:189], v[82:85], v168, v168 op_sel_hi:[0,0,0]
	s_nop 1
	v_mfma_scale_f32_16x16x128_f8f6f4 v[78:81], v[10:17], v[190:197], v[78:81], v168, v168 op_sel_hi:[0,0,0]
	s_nop 1
	v_mfma_scale_f32_16x16x128_f8f6f4 v[74:77], v[2:9], v[190:197], v[74:77], v168, v168 op_sel_hi:[0,0,0]
	s_nop 1
	v_mfma_scale_f32_16x16x128_f8f6f4 v[54:57], v[10:17], v[198:205], v[54:57], v168, v168 op_sel_hi:[0,0,0]
	s_nop 1
	v_mfma_scale_f32_16x16x128_f8f6f4 v[50:53], v[2:9], v[198:205], v[50:53], v168, v168 op_sel_hi:[0,0,0]
	s_nop 1
	v_mfma_scale_f32_16x16x128_f8f6f4 v[46:49], v[10:17], v[206:213], v[46:49], v168, v168 op_sel_hi:[0,0,0]
	s_nop 1
	v_mfma_scale_f32_16x16x128_f8f6f4 v[42:45], v[2:9], v[206:213], v[42:45], v168, v168 op_sel_hi:[0,0,0]
	s_barrier
	s_add_u32 s16, s14, 0x60000
	s_addc_u32 s17, s15, 0
	s_add_i32 s30, s31, s23
	v_lshl_add_u64 v[2:3], s[16:17], 0, v[0:1]
	s_mov_b32 m0, s30
	s_nop 0
	global_load_lds_dwordx4 v[2:3], off
	v_lshl_add_u64 v[2:3], s[16:17], 0, v[154:155]
	s_add_i32 m0, s30, 0x2000
	s_nop 0
	global_load_lds_dwordx4 v[2:3], off
	s_waitcnt vmcnt(6)
	s_barrier
; #define PG8_STAGE(bufoff, gbase, voff) do { _Pragma("unroll") for (int _i = 0; _i < 2; ++_i) \
;         __builtin_amdgcn_global_load_lds((const unsigned*)((const char*)(gbase) + (voff)[_i]), (PG8_LAS unsigned*)(lds + (bufoff) + ldsw + _i * 8192), 16, 0, 0); } while (0)
; #define PG8_LDA(dst, b, h) do { _Pragma("unroll") for (int m = 0; m < 4; ++m) _Pragma("unroll") for (int k = 0; k < 2; ++k) dst[m][k] = *(const PG8_LAS bf16x8*)(lds + PG8_SA(b, h) + aoff + m * 2048 + k * 1024); } while (0)
; #define PG8_LDB(dst, b, h) do { _Pragma("unroll") for (int n = 0; n < 2; ++n) _Pragma("unroll") for (int k = 0; k < 2; ++k) dst[n][k] = *(const PG8_LAS bf16x8*)(lds + PG8_SB(b, h) + boff + n * 2048 + k * 1024); } while (0)
; #define PG8_WAIT_V(n) asm volatile("s_waitcnt vmcnt(" #n ")" ::: "memory")
; #define PG8_WAIT_L(n) asm volatile("s_waitcnt lgkmcnt(" #n ")" ::: "memory")
; #define PG8_BAR __builtin_amdgcn_s_barrier()
; #define PG8_SCHED __builtin_amdgcn_sched_barrier(0)
; template <bool FP8, class Epi, class Sched>
; __device__ __forceinline__ void gemm_phase(PG8_LAS unsigned char* lds, const Gemm g, const Sched& S, const Epi& E) {
;     ...
;             PG8_WAIT_V(6); PG8_BAR; PG8_MMA(1, 1, At, B1); PG8_BAR;
;             PG8_LDB(B0, 1, 0); PG8_SCHED; PG8_LDA(At, 1, 0); PG8_STAGE(PG8_SA(0, 1), a2 + hstepA, voffA);
;             PG8_WAIT_L(8); PG8_BAR; PG8_WAIT_L(0); PG8_MMA(0, 0, At, B0); PG8_BAR; PG8_SCHED;
;             PG8_LDB(B1, 1, 1); PG8_STAGE(PG8_SB(1, 0), b3, voffB);
;             PG8_BAR; PG8_WAIT_L(0); PG8_MMA(0, 1, At, B1); PG8_BAR;
;             PG8_LDA(At, 1, 1); PG8_STAGE(PG8_SA(1, 0), a3, voffA);
;             PG8_BAR; PG8_WAIT_L(0); PG8_MMA(1, 0, At, B0); PG8_BAR; PG8_SCHED;
	s_nop 1
	v_mfma_scale_f32_16x16x128_f8f6f4 v[70:73], v[236:243], v[182:189], v[70:73], v168, v168 op_sel_hi:[0,0,0]
	s_nop 1
	v_mfma_scale_f32_16x16x128_f8f6f4 v[66:69], v[18:25], v[182:189], v[66:69], v168, v168 op_sel_hi:[0,0,0]
	s_nop 1
	v_mfma_scale_f32_16x16x128_f8f6f4 v[62:65], v[236:243], v[190:197], v[62:65], v168, v168 op_sel_hi:[0,0,0]
	s_nop 1
	v_mfma_scale_f32_16x16x128_f8f6f4 v[58:61], v[18:25], v[190:197], v[58:61], v168, v168 op_sel_hi:[0,0,0]
	s_nop 1
	v_mfma_scale_f32_16x16x128_f8f6f4 v[38:41], v[236:243], v[198:205], v[38:41], v168, v168 op_sel_hi:[0,0,0]
	s_nop 1
	v_mfma_scale_f32_16x16x128_f8f6f4 v[34:37], v[18:25], v[198:205], v[34:37], v168, v168 op_sel_hi:[0,0,0]
	s_nop 1
	v_mfma_scale_f32_16x16x128_f8f6f4 v[30:33], v[236:243], v[206:213], v[30:33], v168, v168 op_sel_hi:[0,0,0]
	s_nop 1
	v_mfma_scale_f32_16x16x128_f8f6f4 v[26:29], v[18:25], v[206:213], v[26:29], v168, v168 op_sel_hi:[0,0,0]
	s_add_i32 s30, 0, 0x18000
	v_add_u32_e32 v14, s30, v170
	s_barrier
	ds_read_b128 v[2:5], v14
	ds_read_b128 v[6:9], v14 offset:1024
	ds_read_b128 v[10:13], v14 offset:2048
	ds_read_b128 v[14:17], v14 offset:3072
	s_add_u32 s16, s18, 0x60000
	s_addc_u32 s17, s19, 0
	s_mov_b32 m0, s26
	v_lshl_add_u64 v[174:175], s[16:17], 0, v[0:1]
	ds_read_b128 v[18:21], v172 offset:32768
	ds_read_b128 v[22:25], v172 offset:33792
	ds_read_b128 v[182:185], v172 offset:34816
	ds_read_b128 v[186:189], v172 offset:35840
	ds_read_b128 v[190:193], v172 offset:36864
	ds_read_b128 v[194:197], v172 offset:37888
	ds_read_b128 v[198:201], v172 offset:38912
	ds_read_b128 v[202:205], v172 offset:39936
	global_load_lds_dwordx4 v[174:175], off
	v_lshl_add_u64 v[174:175], s[16:17], 0, v[154:155]
	s_mov_b32 m0, s27
	s_nop 0
	global_load_lds_dwordx4 v[174:175], off
	s_waitcnt lgkmcnt(8)
	s_barrier
	s_waitcnt lgkmcnt(0)
	s_nop 1
	v_mfma_scale_f32_16x16x128_f8f6f4 v[150:153], v[2:9], v[18:25], v[150:153], v168, v168 op_sel_hi:[0,0,0]
	s_nop 1
	v_mfma_scale_f32_16x16x128_f8f6f4 v[146:149], v[10:17], v[18:25], v[146:149], v168, v168 op_sel_hi:[0,0,0]
	s_nop 1
	v_mfma_scale_f32_16x16x128_f8f6f4 v[142:145], v[2:9], v[182:189], v[142:145], v168, v168 op_sel_hi:[0,0,0]
	s_nop 1
	v_mfma_scale_f32_16x16x128_f8f6f4 v[138:141], v[10:17], v[182:189], v[138:141], v168, v168 op_sel_hi:[0,0,0]
	s_nop 1
	v_mfma_scale_f32_16x16x128_f8f6f4 v[118:121], v[2:9], v[190:197], v[118:121], v168, v168 op_sel_hi:[0,0,0]
	s_nop 1
	v_mfma_scale_f32_16x16x128_f8f6f4 v[114:117], v[10:17], v[190:197], v[114:117], v168, v168 op_sel_hi:[0,0,0]
	s_nop 1
	v_mfma_scale_f32_16x16x128_f8f6f4 v[110:113], v[2:9], v[198:205], v[110:113], v168, v168 op_sel_hi:[0,0,0]
	s_nop 1
	v_mfma_scale_f32_16x16x128_f8f6f4 v[106:109], v[10:17], v[198:205], v[106:109], v168, v168 op_sel_hi:[0,0,0]
	s_barrier
	s_add_i32 s16, 0, 0x1c000
	s_add_i32 s17, s30, s23
	v_add_u32_e32 v173, s16, v170
	v_lshl_add_u64 v[160:161], v[160:161], 0, s[56:57]
	s_mov_b32 m0, s17
	ds_read_b128 v[206:209], v173
	ds_read_b128 v[210:213], v173 offset:1024
	ds_read_b128 v[236:239], v173 offset:2048
	ds_read_b128 v[240:243], v173 offset:3072
	global_load_lds_dwordx4 v[160:161], off
	v_lshl_add_u64 v[160:161], v[162:163], 0, s[56:57]
	s_add_i32 m0, s17, 0x2000
	s_nop 0
	global_load_lds_dwordx4 v[160:161], off
	s_barrier
	s_waitcnt lgkmcnt(0)
	s_nop 1
	v_mfma_scale_f32_16x16x128_f8f6f4 v[134:137], v[206:213], v[18:25], v[134:137], v168, v168 op_sel_hi:[0,0,0]
	s_nop 1
	v_mfma_scale_f32_16x16x128_f8f6f4 v[130:133], v[236:243], v[18:25], v[130:133], v168, v168 op_sel_hi:[0,0,0]
	s_nop 1
	v_mfma_scale_f32_16x16x128_f8f6f4 v[126:129], v[206:213], v[182:189], v[126:129], v168, v168 op_sel_hi:[0,0,0]
	s_nop 1
	v_mfma_scale_f32_16x16x128_f8f6f4 v[122:125], v[236:243], v[182:189], v[122:125], v168, v168 op_sel_hi:[0,0,0]
	s_nop 1
	v_mfma_scale_f32_16x16x128_f8f6f4 v[102:105], v[206:213], v[190:197], v[102:105], v168, v168 op_sel_hi:[0,0,0]
	s_nop 1
	v_mfma_scale_f32_16x16x128_f8f6f4 v[98:101], v[236:243], v[190:197], v[98:101], v168, v168 op_sel_hi:[0,0,0]
	s_nop 1
	v_mfma_scale_f32_16x16x128_f8f6f4 v[94:97], v[206:213], v[198:205], v[94:97], v168, v168 op_sel_hi:[0,0,0]
	s_nop 1
	v_mfma_scale_f32_16x16x128_f8f6f4 v[90:93], v[236:243], v[198:205], v[90:93], v168, v168 op_sel_hi:[0,0,0]
	s_mov_b32 m0, s54
	v_lshl_add_u64 v[160:161], v[164:165], 0, s[56:57]
	s_barrier
	ds_read_b128 v[18:21], v172 offset:49152
	ds_read_b128 v[22:25], v172 offset:50176
	ds_read_b128 v[182:185], v172 offset:51200
	ds_read_b128 v[186:189], v172 offset:52224
	ds_read_b128 v[190:193], v172 offset:53248
	ds_read_b128 v[194:197], v172 offset:54272
	ds_read_b128 v[198:201], v172 offset:55296
	ds_read_b128 v[202:205], v172 offset:56320
	global_load_lds_dwordx4 v[160:161], off
	v_lshl_add_u64 v[160:161], v[166:167], 0, s[56:57]
	s_mov_b32 m0, s66
	s_nop 0
	global_load_lds_dwordx4 v[160:161], off
	s_barrier
	s_waitcnt lgkmcnt(0)
	s_nop 1
	v_mfma_scale_f32_16x16x128_f8f6f4 v[86:89], v[2:9], v[18:25], v[86:89], v168, v168 op_sel_hi:[0,0,0]
	s_nop 1
	v_mfma_scale_f32_16x16x128_f8f6f4 v[82:85], v[10:17], v[18:25], v[82:85], v168, v168 op_sel_hi:[0,0,0]
	s_nop 1
	v_mfma_scale_f32_16x16x128_f8f6f4 v[78:81], v[2:9], v[182:189], v[78:81], v168, v168 op_sel_hi:[0,0,0]
	s_nop 1
	v_mfma_scale_f32_16x16x128_f8f6f4 v[74:77], v[10:17], v[182:189], v[74:77], v168, v168 op_sel_hi:[0,0,0]
	s_nop 1
	v_mfma_scale_f32_16x16x128_f8f6f4 v[54:57], v[2:9], v[190:197], v[54:57], v168, v168 op_sel_hi:[0,0,0]
	s_nop 1
	v_mfma_scale_f32_16x16x128_f8f6f4 v[50:53], v[10:17], v[190:197], v[50:53], v168, v168 op_sel_hi:[0,0,0]
	s_nop 1
	v_mfma_scale_f32_16x16x128_f8f6f4 v[46:49], v[2:9], v[198:205], v[46:49], v168, v168 op_sel_hi:[0,0,0]
	s_nop 1
	v_mfma_scale_f32_16x16x128_f8f6f4 v[42:45], v[10:17], v[198:205], v[42:45], v168, v168 op_sel_hi:[0,0,0]
	s_barrier
; #define PG8_STAGE(bufoff, gbase, voff) do { _Pragma("unroll") for (int _i = 0; _i < 2; ++_i) \
;         __builtin_amdgcn_global_load_lds((const unsigned*)((const char*)(gbase) + (voff)[_i]), (PG8_LAS unsigned*)(lds + (bufoff) + ldsw + _i * 8192), 16, 0, 0); } while (0)
; #define PG8_WAIT_V(n) asm volatile("s_waitcnt vmcnt(" #n ")" ::: "memory")
; #define PG8_BAR __builtin_amdgcn_s_barrier()
; template <bool FP8, class Epi, class Sched>
; __device__ __forceinline__ void gemm_phase(PG8_LAS unsigned char* lds, const Gemm g, const Sched& S, const Epi& E) {
;     ...
;             PG8_STAGE(PG8_SB(1, 1), b3 + hstep, voffB);
;             PG8_WAIT_V(6); PG8_BAR; PG8_MMA(1, 1, At, B1); PG8_BAR;
;         }
;         if constexpr (FP8) asm volatile("s_nop 15\n\ts_nop 15" ::: "memory");
;         if constexpr (!Epi::AFTER_DRAIN) { E(acc, cur, wr, wc, fr, fq); S.done(cur); }
;   DI void operator()(const f32x4 (&acc)[2][2][4][2], const pg8::Unit& u, int wr, int wc, int fr, int fq) const {
;     const int row0 = u.pm * 256 + wr * 64 + fr, col0 = u.pn * 256 + wc * 32 + 4 * fq;
; #pragma unroll
;     for (int ai = 0; ai < 2; ++ai)
; #pragma unroll
;       for (int mp = 0; mp < 2; ++mp) {
;         f32x4 xv[2][2][2];
; #pragma unroll
;         for (int mm = 0; mm < 2; ++mm)
; #pragma unroll
;           for (int bj = 0; bj < 2; ++bj)
; #pragma unroll
;             for (int n = 0; n < 2; ++n)
;               xv[mm][bj][n] = *(const f32x4*)(xin + (size_t)(row0 + ai * 128 + (mp * 2 + mm) * 16) * 2048 + col0 + bj * 128 + n * 16);
; #pragma unroll
;         for (int mm = 0; mm < 2; ++mm)
; #pragma unroll
;           for (int bj = 0; bj < 2; ++bj)
; #pragma unroll
;             for (int n = 0; n < 2; ++n)
;               *(f32x4*)(xout + (size_t)(row0 + ai * 128 + (mp * 2 + mm) * 16) * 2048 + col0 + bj * 128 + n * 16) = xv[mm][bj][n] + acc[ai][bj][mp * 2 + mm][n] * sc;
;         asm volatile("" ::: "memory");
;       }
	s_add_u32 s14, s14, 0x60080
	s_addc_u32 s15, s15, 0
	s_add_i32 s16, s16, s23
	v_lshl_add_u64 v[2:3], s[14:15], 0, v[0:1]
	s_mov_b32 m0, s16
	s_nop 0
	global_load_lds_dwordx4 v[2:3], off
	v_lshl_add_u64 v[2:3], s[14:15], 0, v[154:155]
	s_add_i32 m0, s16, 0x2000
	s_nop 0
	global_load_lds_dwordx4 v[2:3], off
	s_waitcnt vmcnt(6)
	s_barrier
	s_nop 1
	v_mfma_scale_f32_16x16x128_f8f6f4 v[70:73], v[206:213], v[18:25], v[70:73], v168, v168 op_sel_hi:[0,0,0]
	s_nop 1
	v_mfma_scale_f32_16x16x128_f8f6f4 v[66:69], v[236:243], v[18:25], v[66:69], v168, v168 op_sel_hi:[0,0,0]
	s_nop 1
	v_mfma_scale_f32_16x16x128_f8f6f4 v[62:65], v[206:213], v[182:189], v[62:65], v168, v168 op_sel_hi:[0,0,0]
	s_nop 1
	v_mfma_scale_f32_16x16x128_f8f6f4 v[58:61], v[236:243], v[182:189], v[58:61], v168, v168 op_sel_hi:[0,0,0]
	s_nop 1
	v_mfma_scale_f32_16x16x128_f8f6f4 v[38:41], v[206:213], v[190:197], v[38:41], v168, v168 op_sel_hi:[0,0,0]
	s_nop 1
	v_mfma_scale_f32_16x16x128_f8f6f4 v[34:37], v[236:243], v[190:197], v[34:37], v168, v168 op_sel_hi:[0,0,0]
	s_nop 1
	v_mfma_scale_f32_16x16x128_f8f6f4 v[30:33], v[206:213], v[198:205], v[30:33], v168, v168 op_sel_hi:[0,0,0]
	s_nop 1
	v_mfma_scale_f32_16x16x128_f8f6f4 v[26:29], v[236:243], v[198:205], v[26:29], v168, v168 op_sel_hi:[0,0,0]
	s_add_i32 s72, s72, 2
	s_add_u32 s70, s70, 0x100
	s_addc_u32 s71, s71, 0
	s_cmp_gt_u32 s72, 21
	s_mov_b64 s[16:17], s[12:13]
	s_barrier
	s_cbranch_scc0 .LBB0_1543
	v_lshl_or_b32 v2, s28, 8, v171
	v_lshl_add_u32 v8, s29, 8, v169
	v_ashrrev_i32_e32 v3, 31, v2
	v_readlane_b32 s12, v254, 47
	v_lshlrev_b64 v[2:3], 2, v[2:3]
	v_readlane_b32 s13, v254, 48
	v_ashrrev_i32_e32 v9, 31, v8
	v_lshlrev_b64 v[6:7], 13, v[8:9]
	v_lshl_add_u64 v[4:5], s[12:13], 0, v[2:3]
	s_nop 15
	s_nop 15
	v_lshl_add_u64 v[22:23], v[4:5], 0, v[6:7]
	global_load_dwordx4 v[10:13], v[22:23], off
	global_load_dwordx4 v[14:17], v[22:23], off offset:64
	global_load_dwordx4 v[18:21], v[22:23], off offset:512
	s_nop 0
	global_load_dwordx4 v[22:25], v[22:23], off offset:576
	v_or_b32_e32 v160, 16, v8
	v_ashrrev_i32_e32 v161, 31, v160
	v_lshlrev_b64 v[174:175], 13, v[160:161]
	v_lshl_add_u64 v[186:187], v[4:5], 0, v[174:175]
	global_load_dwordx4 v[160:163], v[186:187], off
	global_load_dwordx4 v[164:167], v[186:187], off offset:64
	global_load_dwordx4 v[182:185], v[186:187], off offset:512
	s_nop 0
	global_load_dwordx4 v[186:189], v[186:187], off offset:576
	s_mov_b64 s[12:13], 0x120000
	s_and_b64 vcc, exec, s[8:9]
	s_mov_b32 s28, s68
	s_mov_b32 s29, s69
	s_mov_b64 s[16:17], s[0:1]
	s_waitcnt vmcnt(0)
	v_pk_fma_f32 v[10:11], v[150:151], s[88:89], v[10:11] op_sel_hi:[1,0,1]
	v_lshl_add_u64 v[150:151], s[80:81], 0, v[6:7]
	v_pk_fma_f32 v[12:13], v[152:153], s[88:89], v[12:13] op_sel_hi:[1,0,1]
	v_lshl_add_u64 v[150:151], v[150:151], 0, v[2:3]
	global_store_dwordx4 v[150:151], v[10:13], off
	s_nop 1
	v_pk_fma_f32 v[12:13], v[148:149], s[88:89], v[16:17] op_sel_hi:[1,0,1]
	v_pk_fma_f32 v[10:11], v[146:147], s[88:89], v[14:15] op_sel_hi:[1,0,1]
	global_store_dwordx4 v[150:151], v[10:13], off offset:64
	v_lshl_add_u64 v[14:15], s[80:81], 0, v[174:175]
	v_lshl_add_u64 v[14:15], v[14:15], 0, v[2:3]
	v_pk_fma_f32 v[12:13], v[136:137], s[88:89], v[20:21] op_sel_hi:[1,0,1]
	v_pk_fma_f32 v[10:11], v[134:135], s[88:89], v[18:19] op_sel_hi:[1,0,1]
	global_store_dwordx4 v[150:151], v[10:13], off offset:512
	s_nop 1
	v_pk_fma_f32 v[12:13], v[132:133], s[88:89], v[24:25] op_sel_hi:[1,0,1]
	v_pk_fma_f32 v[10:11], v[130:131], s[88:89], v[22:23] op_sel_hi:[1,0,1]
	global_store_dwordx4 v[150:151], v[10:13], off offset:576
	s_nop 1
	v_pk_fma_f32 v[12:13], v[144:145], s[88:89], v[162:163] op_sel_hi:[1,0,1]
	v_pk_fma_f32 v[10:11], v[142:143], s[88:89], v[160:161] op_sel_hi:[1,0,1]
	global_store_dwordx4 v[14:15], v[10:13], off
	s_nop 1
	v_pk_fma_f32 v[12:13], v[140:141], s[88:89], v[166:167] op_sel_hi:[1,0,1]
	v_pk_fma_f32 v[10:11], v[138:139], s[88:89], v[164:165] op_sel_hi:[1,0,1]
	global_store_dwordx4 v[14:15], v[10:13], off offset:64
	s_nop 1
	v_pk_fma_f32 v[12:13], v[128:129], s[88:89], v[184:185] op_sel_hi:[1,0,1]
	v_pk_fma_f32 v[10:11], v[126:127], s[88:89], v[182:183] op_sel_hi:[1,0,1]
	global_store_dwordx4 v[14:15], v[10:13], off offset:512
	s_nop 1
	v_pk_fma_f32 v[12:13], v[124:125], s[88:89], v[188:189] op_sel_hi:[1,0,1]
	v_pk_fma_f32 v[10:11], v[122:123], s[88:89], v[186:187] op_sel_hi:[1,0,1]
	global_store_dwordx4 v[14:15], v[10:13], off offset:576
	s_nop 1
	v_or_b32_e32 v10, 32, v8
	v_ashrrev_i32_e32 v11, 31, v10
	v_lshlrev_b64 v[138:139], 13, v[10:11]
	v_lshl_add_u64 v[22:23], v[4:5], 0, v[138:139]
	global_load_dwordx4 v[10:13], v[22:23], off
	global_load_dwordx4 v[14:17], v[22:23], off offset:64
	global_load_dwordx4 v[18:21], v[22:23], off offset:512
	s_nop 0
	global_load_dwordx4 v[22:25], v[22:23], off offset:576
	v_or_b32_e32 v8, 48, v8
	v_ashrrev_i32_e32 v9, 31, v8
	v_lshlrev_b64 v[140:141], 13, v[8:9]
	v_lshl_add_u64 v[8:9], v[4:5], 0, v[140:141]
	global_load_dwordx4 v[122:125], v[8:9], off
	global_load_dwordx4 v[126:129], v[8:9], off offset:64
	global_load_dwordx4 v[130:133], v[8:9], off offset:512
	global_load_dwordx4 v[134:137], v[8:9], off offset:576
	v_lshl_add_u64 v[8:9], s[80:81], 0, v[138:139]
	s_waitcnt vmcnt(0)
; #define PG8_WAIT_V(n) asm volatile("s_waitcnt vmcnt(" #n ")" ::: "memory")
; #define PG8_BAR __builtin_amdgcn_s_barrier()
; template <bool FP8, class Epi, class Sched>
; __device__ __forceinline__ void gemm_phase(PG8_LAS unsigned char* lds, const Gemm g, const Sched& S, const Epi& E) {
;     ...
;         if constexpr (!Epi::AFTER_DRAIN) { E(acc, cur, wr, wc, fr, fq); S.done(cur); }
;         if (!has_next) break;
; #pragma unroll
;         for (int a = 0; a < 2; ++a)
; #pragma unroll
;             for (int b = 0; b < 2; ++b)
; #pragma unroll
;                 for (int m = 0; m < 4; ++m)
; #pragma unroll
;                     for (int n = 0; n < 2; ++n) acc[a][b][m][n] = (f32x4){0.f, 0.f, 0.f, 0.f};
;         cur = nxt; cA = nA; cB = nB; ++ui;
;     }
;     PG8_WAIT_V(0);
;     if (wr == 0) PG8_BAR;
;     PG8_BAR;
;   DI void operator()(const f32x4 (&acc)[2][2][4][2], const pg8::Unit& u, int wr, int wc, int fr, int fq) const {
;     const int row0 = u.pm * 256 + wr * 64 + fr, col0 = u.pn * 256 + wc * 32 + 4 * fq;
; #pragma unroll
;     for (int ai = 0; ai < 2; ++ai)
; #pragma unroll
;       for (int mp = 0; mp < 2; ++mp) {
;         f32x4 xv[2][2][2];
; #pragma unroll
;         for (int mm = 0; mm < 2; ++mm)
; #pragma unroll
;           for (int bj = 0; bj < 2; ++bj)
; #pragma unroll
;             for (int n = 0; n < 2; ++n)
;               xv[mm][bj][n] = *(const f32x4*)(xin + (size_t)(row0 + ai * 128 + (mp * 2 + mm) * 16) * 2048 + col0 + bj * 128 + n * 16);
; #pragma unroll
;         for (int mm = 0; mm < 2; ++mm)
; #pragma unroll
;           for (int bj = 0; bj < 2; ++bj)
; #pragma unroll
;             for (int n = 0; n < 2; ++n)
;               *(f32x4*)(xout + (size_t)(row0 + ai * 128 + (mp * 2 + mm) * 16) * 2048 + col0 + bj * 128 + n * 16) = xv[mm][bj][n] + acc[ai][bj][mp * 2 + mm][n] * sc;
;         asm volatile("" ::: "memory");
;       }
;   }
	v_pk_fma_f32 v[12:13], v[120:121], s[88:89], v[12:13] op_sel_hi:[1,0,1]
	v_pk_fma_f32 v[10:11], v[118:119], s[88:89], v[10:11] op_sel_hi:[1,0,1]
	v_lshl_add_u64 v[118:119], v[8:9], 0, v[2:3]
	global_store_dwordx4 v[118:119], v[10:13], off
	v_pk_fma_f32 v[8:9], v[114:115], s[88:89], v[14:15] op_sel_hi:[1,0,1]
	s_nop 0
	v_pk_fma_f32 v[10:11], v[116:117], s[88:89], v[16:17] op_sel_hi:[1,0,1]
	global_store_dwordx4 v[118:119], v[8:11], off offset:64
	v_lshl_add_u64 v[12:13], s[80:81], 0, v[140:141]
	v_lshl_add_u64 v[12:13], v[12:13], 0, v[2:3]
	v_pk_fma_f32 v[10:11], v[104:105], s[88:89], v[20:21] op_sel_hi:[1,0,1]
	v_pk_fma_f32 v[8:9], v[102:103], s[88:89], v[18:19] op_sel_hi:[1,0,1]
	global_store_dwordx4 v[118:119], v[8:11], off offset:512
	s_nop 1
	v_pk_fma_f32 v[10:11], v[100:101], s[88:89], v[24:25] op_sel_hi:[1,0,1]
	v_pk_fma_f32 v[8:9], v[98:99], s[88:89], v[22:23] op_sel_hi:[1,0,1]
	global_store_dwordx4 v[118:119], v[8:11], off offset:576
	v_lshl_add_u64 v[24:25], v[6:7], 0, s[60:61]
	v_lshl_add_u64 v[20:21], v[4:5], 0, v[24:25]
	v_pk_fma_f32 v[10:11], v[112:113], s[88:89], v[124:125] op_sel_hi:[1,0,1]
	v_pk_fma_f32 v[8:9], v[110:111], s[88:89], v[122:123] op_sel_hi:[1,0,1]
	global_store_dwordx4 v[12:13], v[8:11], off
	v_lshl_add_u64 v[24:25], s[80:81], 0, v[24:25]
	v_lshl_add_u64 v[24:25], v[24:25], 0, v[2:3]
	v_pk_fma_f32 v[10:11], v[108:109], s[88:89], v[128:129] op_sel_hi:[1,0,1]
	v_pk_fma_f32 v[8:9], v[106:107], s[88:89], v[126:127] op_sel_hi:[1,0,1]
	global_store_dwordx4 v[12:13], v[8:11], off offset:64
	v_lshl_add_u64 v[106:107], v[6:7], 0, s[12:13]
	v_lshl_add_u64 v[102:103], v[4:5], 0, v[106:107]
	v_pk_fma_f32 v[10:11], v[96:97], s[88:89], v[132:133] op_sel_hi:[1,0,1]
	v_pk_fma_f32 v[8:9], v[94:95], s[88:89], v[130:131] op_sel_hi:[1,0,1]
	global_store_dwordx4 v[12:13], v[8:11], off offset:512
	s_mov_b64 s[12:13], 0x140000
	s_nop 0
	v_pk_fma_f32 v[10:11], v[92:93], s[88:89], v[136:137] op_sel_hi:[1,0,1]
	v_pk_fma_f32 v[8:9], v[90:91], s[88:89], v[134:135] op_sel_hi:[1,0,1]
	global_store_dwordx4 v[12:13], v[8:11], off offset:576
	global_load_dwordx4 v[8:11], v[20:21], off
	global_load_dwordx4 v[12:15], v[20:21], off offset:64
	global_load_dwordx4 v[16:19], v[20:21], off offset:512
	s_nop 0
	global_load_dwordx4 v[20:23], v[20:21], off offset:576
	s_nop 0
	global_load_dwordx4 v[90:93], v[102:103], off
	global_load_dwordx4 v[94:97], v[102:103], off offset:64
	global_load_dwordx4 v[98:101], v[102:103], off offset:512
	s_nop 0
	global_load_dwordx4 v[102:105], v[102:103], off offset:576
	s_waitcnt vmcnt(0)
	v_pk_fma_f32 v[10:11], v[88:89], s[88:89], v[10:11] op_sel_hi:[1,0,1]
	v_pk_fma_f32 v[8:9], v[86:87], s[88:89], v[8:9] op_sel_hi:[1,0,1]
	global_store_dwordx4 v[24:25], v[8:11], off
	s_nop 1
	v_pk_fma_f32 v[10:11], v[84:85], s[88:89], v[14:15] op_sel_hi:[1,0,1]
	v_pk_fma_f32 v[8:9], v[82:83], s[88:89], v[12:13] op_sel_hi:[1,0,1]
	global_store_dwordx4 v[24:25], v[8:11], off offset:64
	v_lshl_add_u64 v[12:13], s[80:81], 0, v[106:107]
	v_lshl_add_u64 v[12:13], v[12:13], 0, v[2:3]
	v_pk_fma_f32 v[10:11], v[72:73], s[88:89], v[18:19] op_sel_hi:[1,0,1]
	v_pk_fma_f32 v[8:9], v[70:71], s[88:89], v[16:17] op_sel_hi:[1,0,1]
	global_store_dwordx4 v[24:25], v[8:11], off offset:512
	s_nop 1
	v_pk_fma_f32 v[10:11], v[68:69], s[88:89], v[22:23] op_sel_hi:[1,0,1]
	v_pk_fma_f32 v[8:9], v[66:67], s[88:89], v[20:21] op_sel_hi:[1,0,1]
	global_store_dwordx4 v[24:25], v[8:11], off offset:576
	v_lshl_add_u64 v[24:25], v[6:7], 0, s[12:13]
	v_lshl_add_u64 v[20:21], v[4:5], 0, v[24:25]
	v_pk_fma_f32 v[10:11], v[80:81], s[88:89], v[92:93] op_sel_hi:[1,0,1]
	v_pk_fma_f32 v[8:9], v[78:79], s[88:89], v[90:91] op_sel_hi:[1,0,1]
	global_store_dwordx4 v[12:13], v[8:11], off
	s_mov_b64 s[12:13], 0x160000
	v_lshl_add_u64 v[70:71], v[6:7], 0, s[12:13]
	v_pk_fma_f32 v[10:11], v[76:77], s[88:89], v[96:97] op_sel_hi:[1,0,1]
	v_pk_fma_f32 v[8:9], v[74:75], s[88:89], v[94:95] op_sel_hi:[1,0,1]
	global_store_dwordx4 v[12:13], v[8:11], off offset:64
	v_lshl_add_u64 v[66:67], v[4:5], 0, v[70:71]
	v_lshl_add_u64 v[24:25], s[80:81], 0, v[24:25]
	v_pk_fma_f32 v[10:11], v[64:65], s[88:89], v[100:101] op_sel_hi:[1,0,1]
	v_pk_fma_f32 v[8:9], v[62:63], s[88:89], v[98:99] op_sel_hi:[1,0,1]
	global_store_dwordx4 v[12:13], v[8:11], off offset:512
	v_lshl_add_u64 v[24:25], v[24:25], 0, v[2:3]
	s_mov_b64 s[12:13], s[10:11]
	v_pk_fma_f32 v[10:11], v[60:61], s[88:89], v[104:105] op_sel_hi:[1,0,1]
	v_pk_fma_f32 v[8:9], v[58:59], s[88:89], v[102:103] op_sel_hi:[1,0,1]
	global_store_dwordx4 v[12:13], v[8:11], off offset:576
	global_load_dwordx4 v[8:11], v[20:21], off
	global_load_dwordx4 v[12:15], v[20:21], off offset:64
	global_load_dwordx4 v[16:19], v[20:21], off offset:512
	s_nop 0
	global_load_dwordx4 v[20:23], v[20:21], off offset:576
	s_nop 0
	global_load_dwordx4 v[4:7], v[66:67], off
	global_load_dwordx4 v[58:61], v[66:67], off offset:64
	global_load_dwordx4 v[62:65], v[66:67], off offset:512
	s_nop 0
	global_load_dwordx4 v[66:69], v[66:67], off offset:576
	s_waitcnt vmcnt(0)
	v_pk_fma_f32 v[10:11], v[56:57], s[88:89], v[10:11] op_sel_hi:[1,0,1]
	v_pk_fma_f32 v[8:9], v[54:55], s[88:89], v[8:9] op_sel_hi:[1,0,1]
	global_store_dwordx4 v[24:25], v[8:11], off
	v_pk_fma_f32 v[6:7], v[48:49], s[88:89], v[6:7] op_sel_hi:[1,0,1]
	v_pk_fma_f32 v[4:5], v[46:47], s[88:89], v[4:5] op_sel_hi:[1,0,1]
	v_pk_fma_f32 v[10:11], v[52:53], s[88:89], v[14:15] op_sel_hi:[1,0,1]
	v_pk_fma_f32 v[8:9], v[50:51], s[88:89], v[12:13] op_sel_hi:[1,0,1]
	global_store_dwordx4 v[24:25], v[8:11], off offset:64
	s_nop 1
	v_pk_fma_f32 v[10:11], v[40:41], s[88:89], v[18:19] op_sel_hi:[1,0,1]
	v_pk_fma_f32 v[8:9], v[38:39], s[88:89], v[16:17] op_sel_hi:[1,0,1]
	global_store_dwordx4 v[24:25], v[8:11], off offset:512
	s_nop 1
	v_pk_fma_f32 v[10:11], v[36:37], s[88:89], v[22:23] op_sel_hi:[1,0,1]
	v_pk_fma_f32 v[8:9], v[34:35], s[88:89], v[20:21] op_sel_hi:[1,0,1]
	global_store_dwordx4 v[24:25], v[8:11], off offset:576
	s_nop 1
	v_lshl_add_u64 v[8:9], s[80:81], 0, v[70:71]
	v_lshl_add_u64 v[8:9], v[8:9], 0, v[2:3]
	global_store_dwordx4 v[8:9], v[4:7], off
	v_pk_fma_f32 v[2:3], v[42:43], s[88:89], v[58:59] op_sel_hi:[1,0,1]
	s_nop 0
	v_pk_fma_f32 v[4:5], v[44:45], s[88:89], v[60:61] op_sel_hi:[1,0,1]
	global_store_dwordx4 v[8:9], v[2:5], off offset:64
	s_nop 1
	v_pk_fma_f32 v[4:5], v[32:33], s[88:89], v[64:65] op_sel_hi:[1,0,1]
	v_pk_fma_f32 v[2:3], v[30:31], s[88:89], v[62:63] op_sel_hi:[1,0,1]
	global_store_dwordx4 v[8:9], v[2:5], off offset:512
	s_nop 1
	v_pk_fma_f32 v[4:5], v[28:29], s[88:89], v[68:69] op_sel_hi:[1,0,1]
	v_pk_fma_f32 v[2:3], v[26:27], s[88:89], v[66:67] op_sel_hi:[1,0,1]
	global_store_dwordx4 v[8:9], v[2:5], off offset:576
	s_cbranch_vccz .LBB0_1532
	s_waitcnt vmcnt(0)
	s_cmpk_gt_u32 s22, 0xff
	v_readlane_b32 s28, v254, 27
	v_readlane_b32 s29, v254, 28
	s_cbranch_scc1 .LBB0_1547
	s_barrier
